# SSM prompt scan: 6-deep LDS-DMA operand prefetch ring + gathered xe/rstd + batched C.x reads; GLU/SwiGLU epilogue loads hoisted (loads-only counted vmcnt)
# speedup vs baseline: 1.0017x; 1.0010x over previous
.LBB0_86:
	s_and_b32 s0, s24, 0xff
	v_lshl_or_b32 v2, s0, 12, v157
	s_lshl_b32 s2, s0, 6
	global_load_dwordx4 v[94:97], v2, s[12:13]
	global_load_dwordx4 v[90:93], v2, s[12:13] offset:1024
	global_load_dwordx4 v[86:89], v2, s[12:13] offset:2048
	global_load_dwordx4 v[82:85], v2, s[12:13] offset:3072
	global_load_dwordx4 v[74:77], v2, s[14:15]
	global_load_dwordx4 v[78:81], v2, s[14:15] offset:1024
	global_load_dwordx4 v[70:73], v2, s[14:15] offset:2048
	global_load_dwordx4 v[66:69], v2, s[14:15] offset:3072
	v_or_b32_e32 v2, s2, v122
	v_lshlrev_b32_e32 v2, 2, v2
	v_or_b32_e32 v3, 0x80, v2
	s_mov_b32 s3, s37
	global_load_dword v148, v2, s[6:7]
	global_load_dword v158, v2, s[22:23]
	global_load_dword v142, v3, s[6:7]
	global_load_dword v146, v3, s[22:23]
	v_lshl_add_u64 v[2:3], v[126:127], 0, s[2:3]
	s_ashr_i32 s1, s24, 7
	global_load_dwordx4 v[10:13], v[2:3], off
	v_lshl_add_u64 v[2:3], v[128:129], 0, s[2:3]
	s_and_b32 s27, s1, -2
	global_load_dwordx4 v[14:17], v[2:3], off
	v_or_b32_e32 v2, s27, v123
	v_lshlrev_b32_e32 v2, 11, v2
	v_or_b32_e32 v162, v155, v2
	v_or_b32_e32 v136, v151, v2
	v_add_u32_e32 v2, 0xffffe000, v162
	v_ashrrev_i32_e32 v163, 31, v162
	v_cmp_gt_i32_e32 vcc, s26, v162
	v_lshlrev_b64 v[20:21], 2, v[162:163]
	v_lshl_add_u64 v[22:23], s[38:39], 0, v[20:21]
	v_cndmask_b32_e32 v3, 0, v163, vcc
	v_cndmask_b32_e32 v2, v2, v162, vcc
	v_cndmask_b32_e32 v5, v179, v181, vcc
	v_cndmask_b32_e32 v4, v183, v190, vcc
	v_lshlrev_b64 v[2:3], 14, v[2:3]
	v_lshl_add_u64 v[2:3], v[4:5], 0, v[2:3]
	v_lshl_add_u64 v[2:3], v[2:3], 0, s[2:3]
	v_lshl_add_u64 v[6:7], v[2:3], 0, v[124:125]
	v_add_u32_e32 v19, 0xffffe000, v136
	v_ashrrev_i32_e32 v137, 31, v136
	v_cmp_gt_i32_e32 vcc, s26, v136
	global_load_dwordx4 v[2:5], v[6:7], off offset:16
	s_nop 0
	global_load_dwordx4 v[6:9], v[6:7], off
	v_cndmask_b32_e32 v25, v179, v181, vcc
	global_load_dword v178, v[22:23], off
	v_cndmask_b32_e32 v23, 0, v137, vcc
	v_cndmask_b32_e32 v22, v19, v136, vcc
	v_cndmask_b32_e32 v24, v183, v190, vcc
	v_lshlrev_b64 v[22:23], 14, v[22:23]
	v_lshl_add_u64 v[22:23], v[24:25], 0, v[22:23]
	v_lshl_add_u64 v[22:23], v[22:23], 0, s[2:3]
	v_lshl_add_u64 v[22:23], v[22:23], 0, v[134:135]
	global_load_dwordx4 v[102:105], v[22:23], off
	v_lshlrev_b64 v[22:23], 2, v[136:137]
	v_or_b32_e32 v18, 8, v136
	v_lshl_add_u64 v[24:25], s[38:39], 0, v[22:23]
	global_load_dword v156, v[24:25], off
	v_add_u32_e32 v24, 0xffffe008, v136
	v_ashrrev_i32_e32 v19, 31, v18
	v_cmp_gt_i32_e32 vcc, s26, v18
	s_lshl_b32 s1, s0, 4
	s_lshl_b32 s36, s0, 5
	v_cndmask_b32_e32 v25, 0, v19, vcc
	v_cndmask_b32_e32 v24, v24, v18, vcc
	v_cndmask_b32_e32 v27, v179, v181, vcc
	v_cndmask_b32_e32 v26, v183, v190, vcc
	v_lshlrev_b64 v[24:25], 14, v[24:25]
	v_lshl_add_u64 v[24:25], v[26:27], 0, v[24:25]
	v_lshlrev_b64 v[18:19], 2, v[18:19]
	v_lshl_add_u64 v[24:25], v[24:25], 0, s[2:3]
	v_lshl_add_u64 v[26:27], s[38:39], 0, v[18:19]
	v_lshl_add_u64 v[24:25], v[24:25], 0, v[134:135]
	global_load_dword v150, v[26:27], off
	global_load_dwordx4 v[98:101], v[24:25], off
	v_lshl_add_u64 v[138:139], v[130:131], 0, s[36:37]
	v_lshl_add_u64 v[170:171], s[44:45], 0, v[18:19]
	v_lshl_add_u64 v[172:173], s[44:45], 0, v[22:23]
	v_lshl_add_u64 v[174:175], s[44:45], 0, v[20:21]
	s_lshl_b32 s36, s1, 2
	v_mov_b32_e32 v176, v125
	v_mov_b32_e32 v164, v125
	v_mov_b32_e32 v177, v125
	v_mov_b32_e32 v165, v125
	s_waitcnt vmcnt(12)
	v_mov_b32_e32 v149, v148
	s_waitcnt vmcnt(11)
	v_xor_b32_e32 v159, 0x80000000, v158
	v_pk_mov_b32 v[166:167], v[158:159], v[158:159] op_sel:[1,0]
	s_waitcnt vmcnt(9)
	v_xor_b32_e32 v147, 0x80000000, v146
	v_mov_b32_e32 v143, v142
	v_pk_mov_b32 v[168:169], v[146:147], v[146:147] op_sel:[1,0]
	v_mov_b32_e32 v160, v159
	v_mov_b32_e32 v161, v158
	v_mov_b32_e32 v152, v147
	s_waitcnt vmcnt(7)
	v_pk_mul_f32 v[140:141], v[12:13], v[16:17]
	v_pk_mul_f32 v[144:145], v[10:11], v[14:15]
	v_mov_b32_e32 v153, v146
	s_waitcnt vmcnt(0)
	s_mul_i32 s99, s93, 0x7800
	s_add_i32 s99, s99, 0x11000
	s_mov_b32 s98, 0x1400
	s_add_i32 s100, s99, s98
	v_lshlrev_b32_e32 v206, 4, v154
	v_lshlrev_b32_e32 v207, 2, v154
	s_movk_i32 s3, 0xffb0
	v_and_b32_e32 v218, 7, v154
	v_bfe_u32 v219, v154, 3, 1
	v_lshl_or_b32 v220, v219, 3, v218
	v_add_u32_e32 v219, 2, v219
	v_lshl_or_b32 v221, v219, 3, v218
	v_lshlrev_b32_e32 v212, 2, v220
	v_lshlrev_b32_e32 v213, 2, v221
	v_lshrrev_b32_e32 v218, 4, v154
	v_lshrrev_b32_e32 v219, 1, v218
	v_and_b32_e32 v218, 1, v218
	v_lshlrev_b32_e32 v218, 10, v218
	v_lshl_or_b32 v220, v219, 5, v220
	v_lshl_or_b32 v221, v219, 5, v221
	v_lshl_add_u32 v210, v220, 4, v218
	v_lshl_add_u32 v211, v221, 4, v218
.LBB0_87:
	v_add_u32_e32 v11, s3, v162
	v_add_u32_e32 v184, s3, v136
	v_add_u32_e32 v20, 96, v11
	v_add_u32_e32 v21, 96, v184
	v_add_u32_e32 v22, 104, v184
	v_mov_b32_e32 v18, s10
	v_mov_b32_e32 v19, s8
	v_add_u32_e32 v23, 0xffffe060, v11
	v_add_u32_e32 v24, 0xffffe060, v184
	v_cmp_gt_i32_e32 vcc, s26, v20
	v_cmp_gt_i32_e64 s[0:1], s26, v21
	v_cmp_gt_i32_e64 s[4:5], s26, v22
	v_ashrrev_i32_e32 v26, 31, v20
	v_ashrrev_i32_e32 v27, 31, v21
	v_mov_b32_e32 v12, s11
	v_mov_b32_e32 v13, s9
	v_add_u32_e32 v25, 0xffffe068, v184
	v_ashrrev_i32_e32 v28, 31, v22
	v_cndmask_b32_e32 v54, v18, v19, vcc
	v_cndmask_b32_e64 v56, v18, v19, s[0:1]
	v_cndmask_b32_e64 v58, v18, v19, s[4:5]
	v_cndmask_b32_e32 v18, v23, v20, vcc
	v_cndmask_b32_e32 v19, 0, v26, vcc
	v_cndmask_b32_e64 v20, v24, v21, s[0:1]
	v_cndmask_b32_e64 v21, 0, v27, s[0:1]
	v_cndmask_b32_e32 v55, v12, v13, vcc
	v_cndmask_b32_e64 v57, v12, v13, s[0:1]
	v_cndmask_b32_e64 v60, v25, v22, s[4:5]
	v_cndmask_b32_e64 v61, 0, v28, s[4:5]
	v_lshlrev_b64 v[62:63], 14, v[18:19]
	v_lshlrev_b64 v[64:65], 14, v[20:21]
	s_nop 0
	v_mov_b64_e32 v[108:109], v[100:101]
	v_cndmask_b32_e64 v59, v12, v13, s[4:5]
	v_lshlrev_b64 v[60:61], 14, v[60:61]
	v_lshl_add_u64 v[54:55], v[54:55], 0, v[62:63]
	v_lshl_add_u64 v[56:57], v[56:57], 0, v[64:65]
	v_mov_b64_e32 v[112:113], v[104:105]
	v_mov_b64_e32 v[106:107], v[98:99]
	v_mov_b32_e32 v133, v125
	v_lshl_add_u64 v[58:59], v[58:59], 0, v[60:61]
	v_lshl_add_u64 v[200:201], v[54:55], 0, s[36:37]
	v_lshl_add_u64 v[202:203], v[56:57], 0, s[36:37]
	v_mov_b64_e32 v[110:111], v[102:103]
	v_lshl_add_u64 v[204:205], v[58:59], 0, s[36:37]
	v_lshl_add_u64 v[200:201], v[200:201], 0, v[124:125]
	v_lshl_add_u64 v[202:203], v[202:203], 0, v[132:133]
	v_mov_b32_e32 v10, v178
	v_mov_b32_e32 v182, v156
	v_mov_b32_e32 v180, v150
	s_add_i32 m0, s100, 0x1000
	s_nop 0
	global_load_lds_dword v[174:175], off
	s_nop 0
	s_nop 0
	v_lshl_add_u64 v[204:205], v[204:205], 0, v[132:133]
	s_add_i32 m0, s100, 0x3f0
	s_nop 0
	global_load_lds_dwordx4 v[200:201], off offset:16
	s_add_i32 m0, s100, 0x0
	s_nop 0
	global_load_lds_dwordx4 v[200:201], off
	s_nop 0
	s_nop 0
	s_nop 0
	s_add_i32 s98, s98, 0x1400
	s_cmp_eq_u32 s98, 0x7800
	s_cselect_b32 s98, 0, s98
	s_add_i32 s100, s99, s98
	s_cmp_lt_i32 s3, 0
	s_cbranch_scc1 .Lssm_skip
	v_pk_mul_f32 v[6:7], v[6:7], v[10:11] op_sel_hi:[1,0]
	v_pk_mul_f32 v[8:9], v[8:9], v[10:11] op_sel_hi:[1,0]
	v_pk_mul_f32 v[2:3], v[10:11], v[2:3] op_sel_hi:[0,1]
	v_pk_mul_f32 v[4:5], v[10:11], v[4:5] op_sel_hi:[0,1]
	v_cvt_pk_bf16_f32 v50, v6, v7
	v_cvt_pk_bf16_f32 v51, v8, v9
	v_cvt_pk_bf16_f32 v52, v2, v3
	v_cvt_pk_bf16_f32 v53, v4, v5
	v_mov_b32_e32 v186, v177
	v_mov_b32_e32 v187, v176
	v_mfma_f32_32x32x16_bf16 v[2:17], v[50:53], v[94:97], 0
	v_mov_b32_e32 v188, v165
	v_mov_b32_e32 v189, v164
	v_add_u32_e32 v197, 0x800, v191
	v_add_u32_e32 v196, 0xa00, v191
	v_add_u32_e32 v195, 0x1000, v191
	v_add_u32_e32 v194, 0x1400, v191
	v_add_u32_e32 v163, 0x1800, v191
	v_mfma_f32_32x32x16_bf16 v[34:49], v[50:53], v[90:93], 0
	s_nop 3
	v_mov_b32_e32 v198, v2
	v_mov_b32_e32 v2, v4
	v_mov_b32_e32 v4, v6
	v_mov_b32_e32 v6, v8
	v_add_u32_e32 v193, 0x1a00, v191
	v_add_u32_e32 v137, 0x1c00, v191
	s_nop 1
	v_mov_b32_e32 v199, v34
	v_mfma_f32_32x32x16_bf16 v[18:33], v[50:53], v[86:89], 0
	v_mov_b32_e32 v34, v3
	v_mov_b32_e32 v3, v36
	v_mov_b32_e32 v36, v5
	v_mov_b32_e32 v5, v38
	v_mov_b32_e32 v38, v7
	v_mov_b32_e32 v7, v40
	v_mov_b32_e32 v8, v41
	v_mfma_f32_32x32x16_bf16 v[50:65], v[50:53], v[82:85], 0
	v_mov_b32_e32 v40, v10
	v_mov_b32_e32 v41, v42
	v_mov_b32_e32 v10, v43
	v_mov_b32_e32 v42, v12
	v_mov_b32_e32 v43, v44
	v_mov_b32_e32 v12, v45
	v_mov_b32_e32 v44, v14
	v_mov_b32_e32 v45, v46
	v_mov_b32_e32 v14, v47
	v_mov_b32_e32 v46, v16
	v_mov_b32_e32 v47, v48
	v_mov_b32_e32 v16, v49
	v_mov_b32_e32 v48, v18
	v_mov_b32_e32 v49, v50
	v_mov_b32_e32 v50, v19
	v_mov_b32_e32 v18, v20
	v_mov_b32_e32 v19, v52
	v_mov_b32_e32 v52, v21
	v_mov_b32_e32 v20, v22
	v_mov_b32_e32 v21, v54
	v_mov_b32_e32 v54, v23
	v_mov_b32_e32 v22, v24
	v_mov_b32_e32 v23, v56
	v_mov_b32_e32 v24, v57
	v_mov_b32_e32 v56, v26
	v_mov_b32_e32 v57, v58
	v_mov_b32_e32 v26, v59
	v_mov_b32_e32 v58, v28
	v_mov_b32_e32 v59, v60
	v_mov_b32_e32 v28, v61
	v_mov_b32_e32 v60, v30
	v_mov_b32_e32 v61, v62
	v_mov_b32_e32 v30, v63
	v_mov_b32_e32 v62, v32
	v_mov_b32_e32 v63, v64
	v_mov_b32_e32 v32, v65
	v_pk_fma_f32 v[64:65], v[148:149], v[176:177], v[198:199]
	v_pk_fma_f32 v[48:49], v[142:143], v[164:165], v[48:49]
	v_pk_fma_f32 v[64:65], v[160:161], v[186:187], v[64:65]
	v_pk_fma_f32 v[48:49], v[152:153], v[188:189], v[48:49]
	v_pk_fma_f32 v[34:35], v[148:149], v[64:65], v[34:35]
	v_pk_fma_f32 v[50:51], v[142:143], v[48:49], v[50:51]
	v_cvt_pk_bf16_f32 v164, v48, v49
	v_pk_fma_f32 v[34:35], v[160:161], v[64:65], v[34:35] op_sel:[0,1,0] op_sel_hi:[1,0,1]
	v_pk_fma_f32 v[48:49], v[152:153], v[48:49], v[50:51] op_sel:[0,1,0] op_sel_hi:[1,0,1]
	v_pk_fma_f32 v[2:3], v[148:149], v[34:35], v[2:3]
	v_pk_fma_f32 v[18:19], v[142:143], v[48:49], v[18:19]
	v_pk_fma_f32 v[2:3], v[160:161], v[34:35], v[2:3] op_sel:[0,1,0] op_sel_hi:[1,0,1]
	v_pk_fma_f32 v[18:19], v[152:153], v[48:49], v[18:19] op_sel:[0,1,0] op_sel_hi:[1,0,1]
	v_cvt_pk_bf16_f32 v50, v34, v35
	v_pk_fma_f32 v[34:35], v[148:149], v[2:3], v[36:37]
	v_pk_fma_f32 v[36:37], v[142:143], v[18:19], v[52:53]
	v_cvt_pk_bf16_f32 v51, v48, v49
	v_cvt_pk_bf16_f32 v48, v2, v3
	v_cvt_pk_bf16_f32 v49, v18, v19
	v_pk_fma_f32 v[2:3], v[160:161], v[2:3], v[34:35] op_sel:[0,1,0] op_sel_hi:[1,0,1]
	v_pk_fma_f32 v[18:19], v[152:153], v[18:19], v[36:37] op_sel:[0,1,0] op_sel_hi:[1,0,1]
	v_pk_fma_f32 v[4:5], v[148:149], v[2:3], v[4:5]
	v_pk_fma_f32 v[20:21], v[142:143], v[18:19], v[20:21]
	v_cvt_pk_bf16_f32 v34, v2, v3
	v_pk_fma_f32 v[2:3], v[160:161], v[2:3], v[4:5] op_sel:[0,1,0] op_sel_hi:[1,0,1]
	v_pk_fma_f32 v[4:5], v[152:153], v[18:19], v[20:21] op_sel:[0,1,0] op_sel_hi:[1,0,1]
	v_cvt_pk_bf16_f32 v35, v18, v19
	v_pk_fma_f32 v[18:19], v[148:149], v[2:3], v[38:39]
	v_pk_fma_f32 v[20:21], v[142:143], v[4:5], v[54:55]
	ds_write2_b32 v191, v34, v35 offset0:204 offset1:236
	v_cvt_pk_bf16_f32 v34, v2, v3
	v_cvt_pk_bf16_f32 v35, v4, v5
	v_pk_fma_f32 v[2:3], v[160:161], v[2:3], v[18:19] op_sel:[0,1,0] op_sel_hi:[1,0,1]
	v_pk_fma_f32 v[4:5], v[152:153], v[4:5], v[20:21] op_sel:[0,1,0] op_sel_hi:[1,0,1]
	v_pk_fma_f32 v[6:7], v[148:149], v[2:3], v[6:7]
	v_pk_fma_f32 v[18:19], v[142:143], v[4:5], v[22:23]
	v_cvt_pk_bf16_f32 v20, v2, v3
	v_cvt_pk_bf16_f32 v21, v4, v5
	v_pk_fma_f32 v[2:3], v[158:159], v[2:3], v[6:7] op_sel:[0,0,1] op_sel_hi:[1,1,0]
	v_pk_fma_f32 v[4:5], v[146:147], v[4:5], v[18:19] op_sel:[0,0,1] op_sel_hi:[1,1,0]
	ds_write2_b32 v197, v20, v21 offset0:100 offset1:132
	v_pk_mov_b32 v[6:7], v[2:3], v[2:3] op_sel:[1,0]
	v_pk_fma_f32 v[8:9], v[148:149], v[2:3], v[8:9]
	v_pk_mov_b32 v[18:19], v[4:5], v[4:5] op_sel:[1,0]
	v_pk_fma_f32 v[20:21], v[142:143], v[4:5], v[24:25]
	v_cvt_pk_bf16_f32 v22, v6, v7
	v_pk_fma_f32 v[2:3], v[166:167], v[2:3], v[8:9] op_sel:[0,0,1] op_sel_hi:[1,1,0]
	v_cvt_pk_bf16_f32 v8, v18, v19
	v_pk_fma_f32 v[4:5], v[168:169], v[4:5], v[20:21] op_sel:[0,0,1] op_sel_hi:[1,1,0]
	v_pk_fma_f32 v[6:7], v[148:149], v[2:3], v[40:41]
	ds_write2_b32 v197, v22, v8 offset0:168 offset1:200
	v_pk_fma_f32 v[8:9], v[142:143], v[4:5], v[56:57]
	v_cvt_pk_bf16_f32 v18, v2, v3
	v_cvt_pk_bf16_f32 v19, v4, v5
	v_pk_fma_f32 v[2:3], v[158:159], v[2:3], v[6:7] op_sel:[0,0,1] op_sel_hi:[1,1,0]
	v_pk_fma_f32 v[4:5], v[146:147], v[4:5], v[8:9] op_sel:[0,0,1] op_sel_hi:[1,1,0]
	ds_write2_b32 v196, v18, v19 offset0:108 offset1:140
	v_pk_mov_b32 v[6:7], v[2:3], v[2:3] op_sel:[1,0]
	v_pk_fma_f32 v[8:9], v[148:149], v[2:3], v[10:11]
	v_pk_mov_b32 v[10:11], v[4:5], v[4:5] op_sel:[1,0]
	v_pk_fma_f32 v[18:19], v[142:143], v[4:5], v[26:27]
	v_cvt_pk_bf16_f32 v20, v6, v7
	v_pk_fma_f32 v[2:3], v[166:167], v[2:3], v[8:9] op_sel:[0,0,1] op_sel_hi:[1,1,0]
	v_cvt_pk_bf16_f32 v8, v10, v11
	v_pk_fma_f32 v[4:5], v[168:169], v[4:5], v[18:19] op_sel:[0,0,1] op_sel_hi:[1,1,0]
	v_pk_fma_f32 v[6:7], v[148:149], v[2:3], v[42:43]
	ds_write2_b32 v195, v20, v8 offset0:64 offset1:96
	v_pk_fma_f32 v[8:9], v[142:143], v[4:5], v[58:59]
	v_cvt_pk_bf16_f32 v10, v2, v3
	v_cvt_pk_bf16_f32 v11, v4, v5
	v_pk_fma_f32 v[2:3], v[158:159], v[2:3], v[6:7] op_sel:[0,0,1] op_sel_hi:[1,1,0]
	v_pk_fma_f32 v[4:5], v[146:147], v[4:5], v[8:9] op_sel:[0,0,1] op_sel_hi:[1,1,0]
	ds_write2_b32 v195, v10, v11 offset0:132 offset1:164
	v_pk_mov_b32 v[6:7], v[2:3], v[2:3] op_sel:[1,0]
	v_pk_fma_f32 v[8:9], v[148:149], v[2:3], v[12:13]
	v_pk_mov_b32 v[10:11], v[4:5], v[4:5] op_sel:[1,0]
	v_pk_fma_f32 v[12:13], v[142:143], v[4:5], v[28:29]
	v_cvt_pk_bf16_f32 v18, v6, v7
	v_pk_fma_f32 v[2:3], v[166:167], v[2:3], v[8:9] op_sel:[0,0,1] op_sel_hi:[1,1,0]
	v_cvt_pk_bf16_f32 v8, v10, v11
	v_pk_fma_f32 v[4:5], v[168:169], v[4:5], v[12:13] op_sel:[0,0,1] op_sel_hi:[1,1,0]
	v_pk_fma_f32 v[6:7], v[148:149], v[2:3], v[44:45]
	ds_write2_b32 v195, v18, v8 offset0:200 offset1:232
	v_pk_fma_f32 v[8:9], v[142:143], v[4:5], v[60:61]
	v_cvt_pk_bf16_f32 v10, v2, v3
	v_cvt_pk_bf16_f32 v11, v4, v5
	v_pk_fma_f32 v[2:3], v[158:159], v[2:3], v[6:7] op_sel:[0,0,1] op_sel_hi:[1,1,0]
	v_pk_fma_f32 v[4:5], v[146:147], v[4:5], v[8:9] op_sel:[0,0,1] op_sel_hi:[1,1,0]
	ds_write2_b32 v194, v10, v11 offset0:12 offset1:44
	v_pk_mov_b32 v[6:7], v[2:3], v[2:3] op_sel:[1,0]
	v_pk_fma_f32 v[8:9], v[148:149], v[2:3], v[14:15]
	v_pk_mov_b32 v[10:11], v[4:5], v[4:5] op_sel:[1,0]
	v_pk_fma_f32 v[12:13], v[142:143], v[4:5], v[30:31]
	v_cvt_pk_bf16_f32 v14, v6, v7
	v_pk_fma_f32 v[2:3], v[166:167], v[2:3], v[8:9] op_sel:[0,0,1] op_sel_hi:[1,1,0]
	v_cvt_pk_bf16_f32 v8, v10, v11
	v_pk_fma_f32 v[4:5], v[168:169], v[4:5], v[12:13] op_sel:[0,0,1] op_sel_hi:[1,1,0]
	v_pk_fma_f32 v[6:7], v[148:149], v[2:3], v[46:47]
	ds_write2_b32 v163, v14, v8 offset0:96 offset1:128
	v_pk_fma_f32 v[8:9], v[142:143], v[4:5], v[62:63]
	v_cvt_pk_bf16_f32 v10, v2, v3
	v_cvt_pk_bf16_f32 v11, v4, v5
	v_pk_fma_f32 v[2:3], v[158:159], v[2:3], v[6:7] op_sel:[0,0,1] op_sel_hi:[1,1,0]
	v_pk_fma_f32 v[4:5], v[146:147], v[4:5], v[8:9] op_sel:[0,0,1] op_sel_hi:[1,1,0]
	v_cvt_pk_bf16_f32 v133, v64, v65
	ds_write2_b32 v163, v10, v11 offset0:164 offset1:196
	v_pk_mov_b32 v[6:7], v[2:3], v[2:3] op_sel:[1,0]
	v_pk_fma_f32 v[8:9], v[148:149], v[2:3], v[16:17]
	v_pk_mov_b32 v[10:11], v[4:5], v[4:5] op_sel:[1,0]
	v_pk_fma_f32 v[12:13], v[142:143], v[4:5], v[32:33]
	ds_write2_b32 v191, v133, v164 offset1:32
	v_cvt_pk_bf16_f32 v6, v6, v7
	v_pk_fma_f32 v[176:177], v[166:167], v[2:3], v[8:9] op_sel:[0,0,1] op_sel_hi:[1,1,0]
	v_cvt_pk_bf16_f32 v2, v10, v11
	v_pk_fma_f32 v[164:165], v[168:169], v[4:5], v[12:13] op_sel:[0,0,1] op_sel_hi:[1,1,0]
	v_cvt_pk_bf16_f32 v3, v176, v177
	ds_write2_b32 v193, v6, v2 offset0:104 offset1:136
	v_cvt_pk_bf16_f32 v2, v164, v165
	ds_write2_b32 v191, v50, v51 offset0:68 offset1:100
	ds_write2_b32 v191, v48, v49 offset0:136 offset1:168
	ds_write2_b32 v197, v34, v35 offset0:32 offset1:64
	ds_write2_b32 v137, v3, v2 offset0:44 offset1:76
	s_waitcnt lgkmcnt(0)
	ds_read_b128 v[18:21], v192
	ds_read_b128 v[22:25], v192 offset:4352
	ds_read_b128 v[26:29], v192 offset:64
	ds_read_b128 v[30:33], v192 offset:4416
	ds_read_b128 v[34:37], v192 offset:128
	ds_read_b128 v[38:41], v192 offset:4480
	ds_read_b128 v[42:45], v192 offset:192
	ds_read_b128 v[46:49], v192 offset:4544
	s_waitcnt lgkmcnt(6)
	v_mfma_f32_16x16x32_bf16 v[2:5], v[74:77], v[18:21], 0
	v_mfma_f32_16x16x32_bf16 v[6:9], v[74:77], v[22:25], 0
	s_waitcnt lgkmcnt(4)
	v_mfma_f32_16x16x32_bf16 v[2:5], v[78:81], v[26:29], v[2:5]
	v_mfma_f32_16x16x32_bf16 v[6:9], v[78:81], v[30:33], v[6:9]
	s_waitcnt lgkmcnt(2)
	v_mfma_f32_16x16x32_bf16 v[2:5], v[70:73], v[34:37], v[2:5]
	v_mfma_f32_16x16x32_bf16 v[6:9], v[70:73], v[38:41], v[6:9]
	s_waitcnt lgkmcnt(0)
	v_mfma_f32_16x16x32_bf16 v[2:5], v[66:69], v[42:45], v[2:5]
	v_mfma_f32_16x16x32_bf16 v[6:9], v[66:69], v[46:49], v[6:9]
	s_waitcnt vmcnt(15)
	v_add_u32_e32 v208, s100, v206
	v_add_u32_e32 v209, s100, v207
	v_add_u32_e32 v214, s100, v210
	v_add_u32_e32 v215, s100, v211
	v_add_u32_e32 v216, s100, v212
	v_add_u32_e32 v217, s100, v213
	ds_read_b128 v[118:121], v208
	ds_read_b128 v[114:117], v208 offset:1024
	ds_read_b128 v[102:105], v214
	ds_read_b128 v[98:101], v215
	ds_read_b32 v178, v209 offset:4096
	ds_read_b32 v156, v216 offset:4096
	ds_read_b32 v150, v217 offset:4096
	v_mul_f32_e64 v10, v110, v182
	v_mul_f32_e64 v11, v111, v182
	v_pk_mul_f32 v[12:13], v[112:113], v[182:183] op_sel_hi:[1,0]
	v_pk_fma_f32 v[2:3], v[144:145], v[10:11], v[2:3]
	v_pk_fma_f32 v[4:5], v[140:141], v[12:13], v[4:5]
	v_mul_f32_e32 v10, 0x3d372713, v2
	v_mul_f32_e32 v11, 0x3d372713, v3
	v_mul_f32_e32 v12, 0x3d372713, v4
	v_mul_f32_e32 v13, 0x3d372713, v5
	v_mul_f32_e32 v10, v2, v10
	v_mul_f32_e32 v11, v3, v11
	v_mul_f32_e32 v12, v4, v12
	v_mul_f32_e32 v13, v5, v13
	v_fma_f32 v10, v2, v10, v2
	v_fma_f32 v11, v3, v11, v3
	v_fma_f32 v12, v4, v12, v4
	v_fma_f32 v13, v5, v13, v5
	v_mul_f32_e32 v10, 0x3f4c422a, v10
	v_mul_f32_e32 v11, 0x3f4c422a, v11
	v_mul_f32_e32 v12, 0x3f4c422a, v12
	v_mul_f32_e32 v13, 0x3f4c422a, v13
	v_mul_f32_e32 v10, -2.0, v10
	v_mul_f32_e32 v11, -2.0, v11
	v_mul_f32_e32 v12, -2.0, v12
	v_mul_f32_e32 v13, -2.0, v13
	v_mul_f32_e32 v10, 0x3fb8aa3b, v10
	v_mul_f32_e32 v11, 0x3fb8aa3b, v11
	v_mul_f32_e32 v12, 0x3fb8aa3b, v12
	v_mul_f32_e32 v13, 0x3fb8aa3b, v13
	v_exp_f32_e32 v10, v10
	v_exp_f32_e32 v11, v11
	v_exp_f32_e32 v12, v12
	v_exp_f32_e32 v13, v13
	v_add_f32_e32 v10, 1.0, v10
	v_add_f32_e32 v11, 1.0, v11
	v_add_f32_e32 v12, 1.0, v12
	v_add_f32_e32 v13, 1.0, v13
	v_rcp_f32_e32 v10, v10
	v_rcp_f32_e32 v11, v11
	v_rcp_f32_e32 v12, v12
	v_rcp_f32_e32 v13, v13
	v_ashrrev_i32_e32 v185, 31, v184
	v_pk_mul_f32 v[2:3], v[2:3], v[10:11]
	s_add_i32 s3, s3, 16
	v_pk_mul_f32 v[4:5], v[4:5], v[12:13]
	v_cvt_pk_bf16_f32 v2, v2, v3
	v_cvt_pk_bf16_f32 v3, v4, v5
	v_pk_mul_f32 v[4:5], v[106:107], v[180:181] op_sel_hi:[1,0]
	v_pk_mul_f32 v[12:13], v[108:109], v[180:181] op_sel_hi:[1,0]
	v_pk_fma_f32 v[4:5], v[144:145], v[4:5], v[6:7]
	v_pk_fma_f32 v[8:9], v[140:141], v[12:13], v[8:9]
	v_mul_f32_e32 v6, 0x3d372713, v4
	v_mul_f32_e32 v6, v4, v6
	v_fma_f32 v6, v4, v6, v4
	v_mul_f32_e32 v6, 0x3f4c422a, v6
	v_mul_f32_e32 v6, -2.0, v6
	v_mul_f32_e32 v6, 0x3fb8aa3b, v6
	v_exp_f32_e32 v10, v6
	v_mul_f32_e32 v6, 0x3d372713, v5
	v_mul_f32_e32 v12, 0x3d372713, v8
	v_mul_f32_e32 v13, 0x3d372713, v9
	v_mul_f32_e32 v6, v5, v6
	v_mul_f32_e32 v12, v8, v12
	v_mul_f32_e32 v13, v9, v13
	v_fma_f32 v6, v5, v6, v5
	v_fma_f32 v12, v8, v12, v8
	v_fma_f32 v13, v9, v13, v9
	v_mul_f32_e32 v6, 0x3f4c422a, v6
	v_mul_f32_e32 v12, 0x3f4c422a, v12
	v_mul_f32_e32 v13, 0x3f4c422a, v13
	v_mul_f32_e32 v6, -2.0, v6
	v_mul_f32_e32 v12, -2.0, v12
	v_mul_f32_e32 v13, -2.0, v13
	v_mul_f32_e32 v6, 0x3fb8aa3b, v6
	v_mul_f32_e32 v12, 0x3fb8aa3b, v12
	v_mul_f32_e32 v13, 0x3fb8aa3b, v13
	v_exp_f32_e32 v11, v6
	v_exp_f32_e32 v12, v12
	v_exp_f32_e32 v13, v13
	v_add_f32_e32 v10, 1.0, v10
	v_add_f32_e32 v11, 1.0, v11
	v_add_f32_e32 v12, 1.0, v12
	v_add_f32_e32 v13, 1.0, v13
	v_rcp_f32_e32 v10, v10
	v_rcp_f32_e32 v11, v11
	v_rcp_f32_e32 v12, v12
	v_rcp_f32_e32 v13, v13
	v_lshlrev_b64 v[6:7], 13, v[184:185]
	v_lshl_add_u64 v[6:7], v[138:139], 0, v[6:7]
	global_store_dwordx2 v[6:7], v[2:3], off
	v_add_u32_e32 v6, 8, v184
	v_pk_mul_f32 v[2:3], v[4:5], v[10:11]
	v_pk_mul_f32 v[4:5], v[8:9], v[12:13]
	v_ashrrev_i32_e32 v7, 31, v6
	v_cvt_pk_bf16_f32 v2, v2, v3
	v_cvt_pk_bf16_f32 v3, v4, v5
	v_lshlrev_b64 v[4:5], 13, v[6:7]
	v_lshl_add_u64 v[4:5], v[138:139], 0, v[4:5]
	global_store_dwordx2 v[4:5], v[2:3], off
	s_waitcnt lgkmcnt(0)
	v_mov_b64_e32 v[6:7], v[118:119]
	v_mov_b64_e32 v[2:3], v[114:115]
	v_lshl_add_u64 v[170:171], v[170:171], 0, 64
	v_lshl_add_u64 v[172:173], v[172:173], 0, 64
	v_lshl_add_u64 v[174:175], v[174:175], 0, 64
	s_cmpk_lg_i32 s3, 0x7f0
	v_mov_b64_e32 v[8:9], v[120:121]
	v_mov_b64_e32 v[4:5], v[116:117]
	s_cbranch_scc1 .LBB0_87
	s_branch .Lssm_after
.Lssm_skip:
	v_lshl_add_u64 v[170:171], v[170:171], 0, 64
	v_lshl_add_u64 v[172:173], v[172:173], 0, 64
	v_lshl_add_u64 v[174:175], v[174:175], 0, 64
	s_add_i32 s3, s3, 16
	s_cmp_lg_u32 s3, 0
	s_cbranch_scc1 .LBB0_87
	s_waitcnt vmcnt(0)
	s_branch .LBB0_87
.Lssm_after:
	s_waitcnt vmcnt(0)
	v_pk_mul_f32 v[2:3], v[118:119], v[178:179] op_sel_hi:[1,0]
	s_nop 0
	v_cvt_pk_bf16_f32 v40, v2, v3
	v_pk_mul_f32 v[2:3], v[120:121], v[178:179] op_sel_hi:[1,0]
	s_nop 0
	v_cvt_pk_bf16_f32 v41, v2, v3
	v_pk_mul_f32 v[2:3], v[178:179], v[114:115] op_sel_hi:[0,1]
	v_cvt_pk_bf16_f32 v42, v2, v3
	v_pk_mul_f32 v[2:3], v[178:179], v[116:117] op_sel_hi:[0,1]
	v_cvt_pk_bf16_f32 v43, v2, v3
	v_or_b32_e32 v2, s27, v1
	v_ashrrev_i32_e32 v3, 31, v2
	v_mfma_f32_32x32x16_bf16 v[4:19], v[40:43], v[94:97], 0
	v_lshlrev_b64 v[2:3], 14, v[2:3]
	v_or_b32_e32 v2, s2, v2
	v_or_b32_e32 v2, v2, v122
	v_lshlrev_b64 v[38:39], 2, v[2:3]
	v_lshl_add_u64 v[36:37], s[40:41], 0, v[38:39]
	s_nop 6
	v_mov_b32_e32 v2, v4
	v_mfma_f32_32x32x16_bf16 v[20:35], v[40:43], v[90:93], 0
	s_nop 11
	v_mov_b32_e32 v3, v20
	v_pk_fma_f32 v[2:3], v[148:149], v[176:177], v[2:3]
	v_mov_b32_e32 v4, v21
	v_pk_fma_f32 v[2:3], v[158:159], v[176:177], v[2:3] op_sel:[0,0,1] op_sel_hi:[1,1,0]
	s_nop 0
	v_pk_fma_f32 v[4:5], v[148:149], v[2:3], v[4:5]
	v_pk_mov_b32 v[44:45], v[2:3], v[2:3] op_sel:[1,0]
	v_pk_fma_f32 v[2:3], v[160:161], v[2:3], v[4:5] op_sel:[0,0,1] op_sel_hi:[1,1,0]
	v_mov_b32_e32 v4, v6
	v_mov_b32_e32 v5, v22
	v_pk_fma_f32 v[4:5], v[148:149], v[2:3], v[4:5]
	v_cvt_pk_bf16_f32 v44, v44, v45
	v_cvt_pk_bf16_f32 v45, v2, v3
	v_pk_fma_f32 v[2:3], v[160:161], v[2:3], v[4:5] op_sel:[0,1,0] op_sel_hi:[1,0,1]
	v_mov_b32_e32 v22, v7
	v_pk_fma_f32 v[4:5], v[148:149], v[2:3], v[22:23]
	v_cvt_pk_bf16_f32 v46, v2, v3
	v_pk_fma_f32 v[2:3], v[160:161], v[2:3], v[4:5] op_sel:[0,1,0] op_sel_hi:[1,0,1]
	v_mov_b32_e32 v4, v8
	v_mov_b32_e32 v5, v24
	v_pk_fma_f32 v[4:5], v[148:149], v[2:3], v[4:5]
	v_cvt_pk_bf16_f32 v47, v2, v3
	v_pk_fma_f32 v[2:3], v[160:161], v[2:3], v[4:5] op_sel:[0,1,0] op_sel_hi:[1,0,1]
	v_mov_b32_e32 v24, v9
	v_pk_fma_f32 v[4:5], v[148:149], v[2:3], v[24:25]
	v_cvt_pk_bf16_f32 v48, v2, v3
	v_pk_fma_f32 v[2:3], v[160:161], v[2:3], v[4:5] op_sel:[0,1,0] op_sel_hi:[1,0,1]
	v_mov_b32_e32 v4, v10
	v_mov_b32_e32 v5, v26
	v_pk_fma_f32 v[4:5], v[148:149], v[2:3], v[4:5]
	v_cvt_pk_bf16_f32 v49, v2, v3
	v_pk_fma_f32 v[2:3], v[160:161], v[2:3], v[4:5] op_sel:[0,1,0] op_sel_hi:[1,0,1]
	v_mov_b32_e32 v26, v11
	v_pk_fma_f32 v[4:5], v[148:149], v[2:3], v[26:27]
	v_cvt_pk_bf16_f32 v50, v2, v3
	v_pk_fma_f32 v[2:3], v[160:161], v[2:3], v[4:5] op_sel:[0,1,0] op_sel_hi:[1,0,1]
	v_mov_b32_e32 v4, v12
	v_mov_b32_e32 v5, v28
	v_pk_fma_f32 v[4:5], v[148:149], v[2:3], v[4:5]
	v_cvt_pk_bf16_f32 v51, v2, v3
	v_pk_fma_f32 v[2:3], v[160:161], v[2:3], v[4:5] op_sel:[0,1,0] op_sel_hi:[1,0,1]
	v_mov_b32_e32 v28, v13
	v_pk_fma_f32 v[4:5], v[148:149], v[2:3], v[28:29]
	v_cvt_pk_bf16_f32 v52, v2, v3
	v_pk_fma_f32 v[2:3], v[160:161], v[2:3], v[4:5] op_sel:[0,1,0] op_sel_hi:[1,0,1]
	v_mov_b32_e32 v4, v14
	v_mov_b32_e32 v5, v30
	v_pk_fma_f32 v[4:5], v[148:149], v[2:3], v[4:5]
	v_cvt_pk_bf16_f32 v53, v2, v3
	v_pk_fma_f32 v[2:3], v[160:161], v[2:3], v[4:5] op_sel:[0,1,0] op_sel_hi:[1,0,1]
	v_mov_b32_e32 v30, v15
	v_pk_fma_f32 v[4:5], v[148:149], v[2:3], v[30:31]
	v_cvt_pk_bf16_f32 v54, v2, v3
	v_pk_fma_f32 v[2:3], v[160:161], v[2:3], v[4:5] op_sel:[0,1,0] op_sel_hi:[1,0,1]
	v_mov_b32_e32 v4, v16
	v_mov_b32_e32 v5, v32
	v_pk_fma_f32 v[4:5], v[148:149], v[2:3], v[4:5]
	v_cvt_pk_bf16_f32 v55, v2, v3
	v_pk_fma_f32 v[2:3], v[160:161], v[2:3], v[4:5] op_sel:[0,1,0] op_sel_hi:[1,0,1]
	v_mov_b32_e32 v32, v17
	v_pk_fma_f32 v[4:5], v[148:149], v[2:3], v[32:33]
	v_mov_b32_e32 v22, v18
	v_pk_fma_f32 v[20:21], v[160:161], v[2:3], v[4:5] op_sel:[0,1,0] op_sel_hi:[1,0,1]
	v_mov_b32_e32 v23, v34
	v_pk_fma_f32 v[22:23], v[148:149], v[20:21], v[22:23]
	v_cvt_pk_bf16_f32 v57, v20, v21
	v_pk_fma_f32 v[20:21], v[160:161], v[20:21], v[22:23] op_sel:[0,1,0] op_sel_hi:[1,0,1]
	v_mov_b32_e32 v34, v19
	v_pk_fma_f32 v[18:19], v[148:149], v[20:21], v[34:35]
	v_cvt_pk_bf16_f32 v56, v2, v3
	v_mfma_f32_32x32x16_bf16 v[2:17], v[40:43], v[86:89], 0
	v_cvt_pk_bf16_f32 v58, v20, v21
	v_fma_f32 v34, v160, v21, v18
	v_fma_f32 v35, v161, v20, v19
	v_cvt_pk_bf16_f32 v59, v34, v35
	v_mfma_f32_32x32x16_bf16 v[18:33], v[40:43], v[82:85], 0
	s_nop 6
	v_mov_b32_e32 v40, v2
	s_nop 3
	v_mov_b32_e32 v41, v18
	v_pk_fma_f32 v[40:41], v[142:143], v[164:165], v[40:41]
	s_nop 0
	v_pk_fma_f32 v[40:41], v[146:147], v[164:165], v[40:41] op_sel:[0,0,1] op_sel_hi:[1,1,0]
	s_nop 0
	v_pk_mov_b32 v[42:43], v[40:41], v[40:41] op_sel:[1,0]
	s_nop 0
	v_cvt_pk_bf16_f32 v2, v42, v43
	ds_write2_b32 v191, v44, v2 offset1:32
	v_mov_b32_e32 v2, v19
	v_pk_fma_f32 v[2:3], v[142:143], v[40:41], v[2:3]
	v_mov_b32_e32 v19, v20
	v_pk_fma_f32 v[2:3], v[152:153], v[40:41], v[2:3] op_sel:[0,0,1] op_sel_hi:[1,1,0]
	v_mov_b32_e32 v20, v5
	v_cvt_pk_bf16_f32 v18, v2, v3
	ds_write2_b32 v191, v45, v18 offset0:68 offset1:100
	v_mov_b32_e32 v18, v4
	v_pk_fma_f32 v[18:19], v[142:143], v[2:3], v[18:19]
	s_nop 0
	v_pk_fma_f32 v[2:3], v[152:153], v[2:3], v[18:19] op_sel:[0,1,0] op_sel_hi:[1,0,1]
	s_nop 0
	v_cvt_pk_bf16_f32 v4, v2, v3
	ds_write2_b32 v191, v46, v4 offset0:136 offset1:168
	v_pk_fma_f32 v[4:5], v[142:143], v[2:3], v[20:21]
	s_nop 0
	v_pk_fma_f32 v[2:3], v[152:153], v[2:3], v[4:5] op_sel:[0,1,0] op_sel_hi:[1,0,1]
	v_mov_b32_e32 v5, v22
	v_cvt_pk_bf16_f32 v4, v2, v3
	ds_write2_b32 v191, v47, v4 offset0:204 offset1:236
	v_mov_b32_e32 v4, v6
	v_pk_fma_f32 v[4:5], v[142:143], v[2:3], v[4:5]
	v_mov_b32_e32 v22, v7
	v_pk_fma_f32 v[2:3], v[152:153], v[2:3], v[4:5] op_sel:[0,1,0] op_sel_hi:[1,0,1]
	s_nop 0
	v_cvt_pk_bf16_f32 v4, v2, v3
	ds_write2_b32 v197, v48, v4 offset0:32 offset1:64
	v_pk_fma_f32 v[4:5], v[142:143], v[2:3], v[22:23]
	s_nop 0
	v_pk_fma_f32 v[2:3], v[152:153], v[2:3], v[4:5] op_sel:[0,1,0] op_sel_hi:[1,0,1]
	v_mov_b32_e32 v5, v24
	v_cvt_pk_bf16_f32 v4, v2, v3
	ds_write2_b32 v197, v49, v4 offset0:100 offset1:132
	v_mov_b32_e32 v4, v8
	v_pk_fma_f32 v[4:5], v[142:143], v[2:3], v[4:5]
	v_mov_b32_e32 v24, v9
	v_pk_fma_f32 v[2:3], v[152:153], v[2:3], v[4:5] op_sel:[0,1,0] op_sel_hi:[1,0,1]
	s_nop 0
	v_cvt_pk_bf16_f32 v4, v2, v3
	ds_write2_b32 v197, v50, v4 offset0:168 offset1:200
	v_pk_fma_f32 v[4:5], v[142:143], v[2:3], v[24:25]
	s_nop 0
	v_pk_fma_f32 v[2:3], v[152:153], v[2:3], v[4:5] op_sel:[0,1,0] op_sel_hi:[1,0,1]
	v_mov_b32_e32 v5, v26
	v_cvt_pk_bf16_f32 v4, v2, v3
	ds_write2_b32 v196, v51, v4 offset0:108 offset1:140
	v_mov_b32_e32 v4, v10
	v_pk_fma_f32 v[4:5], v[142:143], v[2:3], v[4:5]
	v_mov_b32_e32 v26, v11
	v_pk_fma_f32 v[2:3], v[152:153], v[2:3], v[4:5] op_sel:[0,1,0] op_sel_hi:[1,0,1]
	s_nop 0
	v_cvt_pk_bf16_f32 v4, v2, v3
	ds_write2_b32 v195, v52, v4 offset0:64 offset1:96
	v_pk_fma_f32 v[4:5], v[142:143], v[2:3], v[26:27]
	s_nop 0
	v_pk_fma_f32 v[2:3], v[152:153], v[2:3], v[4:5] op_sel:[0,1,0] op_sel_hi:[1,0,1]
	v_mov_b32_e32 v5, v28
	v_cvt_pk_bf16_f32 v4, v2, v3
	ds_write2_b32 v195, v53, v4 offset0:132 offset1:164
	v_mov_b32_e32 v4, v12
	v_pk_fma_f32 v[4:5], v[142:143], v[2:3], v[4:5]
	v_mov_b32_e32 v28, v13
	v_pk_fma_f32 v[2:3], v[152:153], v[2:3], v[4:5] op_sel:[0,1,0] op_sel_hi:[1,0,1]
	s_nop 0
	v_cvt_pk_bf16_f32 v4, v2, v3
	ds_write2_b32 v195, v54, v4 offset0:200 offset1:232
	v_pk_fma_f32 v[4:5], v[142:143], v[2:3], v[28:29]
	s_nop 0
	v_pk_fma_f32 v[2:3], v[152:153], v[2:3], v[4:5] op_sel:[0,1,0] op_sel_hi:[1,0,1]
	v_mov_b32_e32 v5, v30
	v_cvt_pk_bf16_f32 v4, v2, v3
	ds_write2_b32 v194, v55, v4 offset0:12 offset1:44
	v_mov_b32_e32 v4, v14
	v_pk_fma_f32 v[4:5], v[142:143], v[2:3], v[4:5]
	v_mov_b32_e32 v30, v15
	v_pk_fma_f32 v[2:3], v[152:153], v[2:3], v[4:5] op_sel:[0,1,0] op_sel_hi:[1,0,1]
	s_nop 0
	v_cvt_pk_bf16_f32 v4, v2, v3
	ds_write2_b32 v163, v56, v4 offset0:96 offset1:128
	v_pk_fma_f32 v[4:5], v[142:143], v[2:3], v[30:31]
	s_nop 0
	v_pk_fma_f32 v[2:3], v[152:153], v[2:3], v[4:5] op_sel:[0,1,0] op_sel_hi:[1,0,1]
	v_mov_b32_e32 v5, v32
	v_cvt_pk_bf16_f32 v4, v2, v3
	ds_write2_b32 v163, v57, v4 offset0:164 offset1:196
	v_mov_b32_e32 v4, v16
	v_pk_fma_f32 v[4:5], v[142:143], v[2:3], v[4:5]
	v_mov_b32_e32 v32, v17
	v_pk_fma_f32 v[2:3], v[152:153], v[2:3], v[4:5] op_sel:[0,1,0] op_sel_hi:[1,0,1]
	s_nop 0
	v_cvt_pk_bf16_f32 v4, v2, v3
	ds_write2_b32 v193, v58, v4 offset0:104 offset1:136
	v_pk_fma_f32 v[4:5], v[142:143], v[2:3], v[32:33]
	s_nop 0
	v_pk_fma_f32 v[18:19], v[152:153], v[2:3], v[4:5] op_sel:[0,1,0] op_sel_hi:[1,0,1]
	s_nop 0
	v_cvt_pk_bf16_f32 v2, v18, v19
	ds_write2_b32 v137, v59, v2 offset0:44 offset1:76
	s_waitcnt lgkmcnt(0)
	ds_read_b128 v[2:5], v192
	ds_read_b128 v[6:9], v192 offset:64
	s_waitcnt lgkmcnt(1)
	v_mfma_f32_16x16x32_bf16 v[2:5], v[74:77], v[2:5], 0
	s_waitcnt lgkmcnt(0)
	v_mfma_f32_16x16x32_bf16 v[2:5], v[78:81], v[6:9], v[2:5]
	ds_read_b128 v[6:9], v192 offset:128
	ds_read_b128 v[10:13], v192 offset:192
	s_waitcnt lgkmcnt(1)
	v_mfma_f32_16x16x32_bf16 v[2:5], v[70:73], v[6:9], v[2:5]
	s_waitcnt lgkmcnt(0)
	v_mfma_f32_16x16x32_bf16 v[2:5], v[66:69], v[10:13], v[2:5]
	ds_read_b128 v[6:9], v192 offset:4352
	ds_read_b128 v[10:13], v192 offset:4416
	s_waitcnt lgkmcnt(1)
	v_mfma_f32_16x16x32_bf16 v[6:9], v[74:77], v[6:9], 0
	s_waitcnt lgkmcnt(0)
	v_mfma_f32_16x16x32_bf16 v[6:9], v[78:81], v[10:13], v[6:9]
	ds_read_b128 v[10:13], v192 offset:4480
	ds_read_b128 v[14:17], v192 offset:4544
	s_waitcnt lgkmcnt(0)
	s_waitcnt lgkmcnt(1)
	v_mfma_f32_16x16x32_bf16 v[6:9], v[70:73], v[10:13], v[6:9]
	s_waitcnt lgkmcnt(0)
	v_mfma_f32_16x16x32_bf16 v[6:9], v[66:69], v[14:17], v[6:9]
	s_waitcnt vmcnt(3)
	v_pk_mul_f32 v[10:11], v[156:157], v[102:103] op_sel_hi:[0,1]
	v_pk_mul_f32 v[12:13], v[156:157], v[104:105] op_sel_hi:[0,1]
	v_pk_fma_f32 v[2:3], v[144:145], v[10:11], v[2:3]
	v_pk_fma_f32 v[4:5], v[140:141], v[12:13], v[4:5]
	v_mul_f32_e32 v10, 0x3d372713, v2
	v_mul_f32_e32 v11, 0x3d372713, v3
	v_mul_f32_e32 v12, 0x3d372713, v4
	v_mul_f32_e32 v13, 0x3d372713, v5
	v_mul_f32_e32 v10, v2, v10
	v_mul_f32_e32 v11, v3, v11
	v_mul_f32_e32 v12, v4, v12
	v_mul_f32_e32 v13, v5, v13
	v_fma_f32 v10, v2, v10, v2
	v_fma_f32 v11, v3, v11, v3
	v_fma_f32 v12, v4, v12, v4
	v_fma_f32 v13, v5, v13, v5
	v_mul_f32_e32 v10, 0x3f4c422a, v10
	v_mul_f32_e32 v11, 0x3f4c422a, v11
	v_mul_f32_e32 v12, 0x3f4c422a, v12
	v_mul_f32_e32 v13, 0x3f4c422a, v13
	v_mul_f32_e32 v10, -2.0, v10
	v_mul_f32_e32 v11, -2.0, v11
	v_mul_f32_e32 v12, -2.0, v12
	v_mul_f32_e32 v13, -2.0, v13
	v_mul_f32_e32 v10, 0x3fb8aa3b, v10
	v_mul_f32_e32 v11, 0x3fb8aa3b, v11
	v_mul_f32_e32 v12, 0x3fb8aa3b, v12
	v_mul_f32_e32 v13, 0x3fb8aa3b, v13
	v_exp_f32_e32 v10, v10
	v_exp_f32_e32 v11, v11
	v_exp_f32_e32 v12, v12
	v_exp_f32_e32 v13, v13
	v_add_f32_e32 v10, 1.0, v10
	v_add_f32_e32 v11, 1.0, v11
	v_add_f32_e32 v12, 1.0, v12
	v_add_f32_e32 v13, 1.0, v13
	v_rcp_f32_e32 v10, v10
	v_rcp_f32_e32 v11, v11
	v_rcp_f32_e32 v12, v12
	v_rcp_f32_e32 v13, v13
	s_add_i32 s24, s25, s24
	v_pk_mul_f32 v[2:3], v[2:3], v[10:11]
	v_or_b32_e32 v10, 0x7f0, v136
	v_pk_mul_f32 v[4:5], v[4:5], v[12:13]
	v_cvt_pk_bf16_f32 v2, v2, v3
	v_cvt_pk_bf16_f32 v3, v4, v5
	s_waitcnt vmcnt(2)
	v_pk_mul_f32 v[4:5], v[150:151], v[98:99] op_sel_hi:[0,1]
	v_pk_fma_f32 v[4:5], v[144:145], v[4:5], v[6:7]
	v_ashrrev_i32_e32 v11, 31, v10
	v_mul_f32_e32 v6, 0x3d372713, v4
	v_mul_f32_e32 v6, v4, v6
	v_fma_f32 v6, v4, v6, v4
	v_mul_f32_e32 v6, 0x3f4c422a, v6
	v_mul_f32_e32 v6, -2.0, v6
	v_mul_f32_e32 v6, 0x3fb8aa3b, v6
	v_exp_f32_e32 v12, v6
	v_mul_f32_e32 v6, 0x3d372713, v5
	v_mul_f32_e32 v6, v5, v6
	v_fma_f32 v6, v5, v6, v5
	v_mul_f32_e32 v6, 0x3f4c422a, v6
	v_mul_f32_e32 v6, -2.0, v6
	v_mul_f32_e32 v6, 0x3fb8aa3b, v6
	v_exp_f32_e32 v13, v6
	v_lshlrev_b64 v[6:7], 13, v[10:11]
	v_add_f32_e32 v10, 1.0, v12
	v_rcp_f32_e32 v10, v10
	v_add_f32_e32 v11, 1.0, v13
	v_pk_mul_f32 v[12:13], v[150:151], v[100:101] op_sel_hi:[0,1]
	v_pk_fma_f32 v[8:9], v[140:141], v[12:13], v[8:9]
	v_rcp_f32_e32 v11, v11
	v_mul_f32_e32 v12, 0x3d372713, v8
	v_mul_f32_e32 v13, 0x3d372713, v9
	v_mul_f32_e32 v12, v8, v12
	v_mul_f32_e32 v13, v9, v13
	v_fma_f32 v12, v8, v12, v8
	v_fma_f32 v13, v9, v13, v9
	v_mul_f32_e32 v12, 0x3f4c422a, v12
	v_mul_f32_e32 v13, 0x3f4c422a, v13
	v_mul_f32_e32 v12, -2.0, v12
	v_mul_f32_e32 v13, -2.0, v13
	v_mul_f32_e32 v12, 0x3fb8aa3b, v12
	v_mul_f32_e32 v13, 0x3fb8aa3b, v13
	v_exp_f32_e32 v12, v12
	v_exp_f32_e32 v13, v13
	v_lshl_add_u64 v[6:7], v[138:139], 0, v[6:7]
	global_store_dwordx2 v[6:7], v[2:3], off
	v_add_f32_e32 v12, 1.0, v12
	v_add_f32_e32 v13, 1.0, v13
	v_rcp_f32_e32 v12, v12
	v_rcp_f32_e32 v13, v13
	v_or_b32_e32 v6, 0x7f8, v136
	v_pk_mul_f32 v[2:3], v[4:5], v[10:11]
	v_ashrrev_i32_e32 v7, 31, v6
	v_pk_mul_f32 v[4:5], v[8:9], v[12:13]
	v_cvt_pk_bf16_f32 v2, v2, v3
	v_cvt_pk_bf16_f32 v3, v4, v5
	v_lshlrev_b64 v[4:5], 13, v[6:7]
	v_lshl_add_u64 v[4:5], v[138:139], 0, v[4:5]
	global_store_dwordx2 v[4:5], v[2:3], off
	v_lshl_add_u64 v[2:3], s[42:43], 0, v[38:39]
	s_cmpk_gt_i32 s24, 0x1ff
	global_store_dword v[36:37], v34, off
	global_store_dword v[2:3], v35, off
	global_store_dword v[36:37], v18, off offset:128
	global_store_dword v[2:3], v19, off offset:128
	s_cbranch_scc0 .LBB0_86

.LBB0_227:
	v_lshl_add_u32 v140, s80, 8, v146
	s_movk_i32 s2, 0x1fff
	v_cmp_lt_i32_e32 vcc, s2, v140
	s_and_saveexec_b64 s[2:3], vcc
	s_xor_b64 s[2:3], exec, s[2:3]
	v_add_u32_e32 v134, 0xffffe000, v140
	v_lshlrev_b64 v[142:143], 14, v[134:135]
	v_mov_b32_e32 v141, v135
	v_lshl_add_u64 v[142:143], s[10:11], 0, v[142:143]
	v_mov_b64_e32 v[144:145], v[140:141]
	s_or_saveexec_b64 s[2:3], s[2:3]
	v_ashrrev_i32_e32 v141, 31, v140
	s_xor_b64 exec, exec, s[2:3]
	v_lshlrev_b64 v[142:143], 14, v[140:141]
	v_lshl_add_u64 v[142:143], s[8:9], 0, v[142:143]
	v_mov_b64_e32 v[144:145], v[140:141]
	s_or_b64 exec, exec, s[2:3]
	v_lshl_or_b32 v160, s78, 7, v148
	v_ashrrev_i32_e32 v161, 31, v160
	v_lshlrev_b64 v[162:163], 2, v[160:161]
	v_lshl_add_u64 v[142:143], v[142:143], 0, v[162:163]
	global_load_dwordx4 v[170:173], v[142:143], off
	global_load_dwordx4 v[174:177], v[142:143], off offset:64
	v_lshl_add_u64 v[234:235], v[142:143], 0, s[38:39]
	global_load_dwordx4 v[178:181], v[234:235], off
	global_load_dwordx4 v[182:185], v[234:235], off offset:64
	v_lshl_add_u64 v[234:235], v[142:143], 0, s[40:41]
	global_load_dwordx4 v[186:189], v[234:235], off
	global_load_dwordx4 v[190:193], v[234:235], off offset:64
	v_lshl_add_u64 v[234:235], v[142:143], 0, s[42:43]
	global_load_dwordx4 v[194:197], v[234:235], off
	global_load_dwordx4 v[198:201], v[234:235], off offset:64
	v_lshl_add_u64 v[234:235], v[142:143], 0, s[44:45]
	global_load_dwordx4 v[202:205], v[234:235], off
	global_load_dwordx4 v[206:209], v[234:235], off offset:64
	v_lshl_add_u64 v[234:235], v[142:143], 0, s[46:47]
	global_load_dwordx4 v[210:213], v[234:235], off
	global_load_dwordx4 v[214:217], v[234:235], off offset:64
	v_lshl_add_u64 v[234:235], v[142:143], 0, s[48:49]
	global_load_dwordx4 v[218:221], v[234:235], off
	global_load_dwordx4 v[222:225], v[234:235], off offset:64
	v_lshl_add_u64 v[234:235], v[142:143], 0, s[66:67]
	global_load_dwordx4 v[226:229], v[234:235], off
	global_load_dwordx4 v[230:233], v[234:235], off offset:64
	v_lshlrev_b64 v[164:165], 14, v[144:145]
	v_mul_f32_e32 v134, 0xbfb8aa3b, v126
	v_mul_f32_e32 v153, 0xbfb8aa3b, v127
	v_mul_f32_e32 v155, 0xbfb8aa3b, v128
	v_mul_f32_e32 v168, 0xbfb8aa3b, v129
	v_lshl_add_u64 v[128:129], s[12:13], 0, v[164:165]
	v_exp_f32_e32 v134, v134
	v_exp_f32_e32 v153, v153
	v_exp_f32_e32 v155, v155
	v_exp_f32_e32 v164, v168
	v_lshlrev_b64 v[166:167], 13, v[144:145]
	v_lshl_add_u64 v[126:127], s[14:15], 0, v[166:167]
	v_add_f32_e32 v134, 1.0, v134
	v_add_f32_e32 v153, 1.0, v153
	v_add_f32_e32 v155, 1.0, v155
	v_add_f32_e32 v167, 1.0, v164
	v_rcp_f32_e32 v164, v134
	v_rcp_f32_e32 v165, v153
	v_rcp_f32_e32 v166, v155
	v_rcp_f32_e32 v167, v167
	v_lshl_add_u64 v[126:127], v[160:161], 1, v[126:127]
	v_lshl_add_u64 v[128:129], v[128:129], 0, v[162:163]
	v_mul_f32_e32 v118, 0xbfb8aa3b, v118
	v_mul_f32_e32 v119, 0xbfb8aa3b, v119
	v_mul_f32_e32 v120, 0xbfb8aa3b, v120
	v_mul_f32_e32 v121, 0xbfb8aa3b, v121
	v_exp_f32_e32 v155, v118
	v_exp_f32_e32 v119, v119
	v_and_b32_e32 v153, 64, v152
	v_exp_f32_e32 v120, v120
	v_exp_f32_e32 v121, v121
	v_xor_b32_e32 v134, 16, v152
	v_add_u32_e32 v153, 64, v153
	v_cmp_lt_i32_e32 vcc, v134, v153
	v_add_f32_e32 v119, 1.0, v119
	v_add_f32_e32 v161, 1.0, v121
	v_cndmask_b32_e32 v118, v152, v134, vcc
	v_add_f32_e32 v134, 1.0, v155
	v_add_f32_e32 v155, 1.0, v120
	v_rcp_f32_e32 v120, v134
	v_rcp_f32_e32 v121, v119
	v_rcp_f32_e32 v160, v155
	v_rcp_f32_e32 v161, v161
	v_lshlrev_b32_e32 v118, 2, v118
	s_waitcnt vmcnt(15)
	v_mov_b64_e32 v[156:157], v[170:171]
	v_mov_b64_e32 v[158:159], v[172:173]
	v_pk_fma_f32 v[122:123], v[122:123], v[164:165], v[156:157]
	v_pk_fma_f32 v[124:125], v[124:125], v[166:167], v[158:159]
	global_store_dwordx4 v[128:129], v[122:125], off
	v_cvt_pk_bf16_f32 v156, v122, v123
	v_cvt_pk_bf16_f32 v157, v124, v125
	global_store_dwordx2 v[126:127], v[156:157], off
	s_nop 0
	v_fma_f32 v119, v122, v122, 0
	v_fmac_f32_e32 v119, v123, v123
	v_fmac_f32_e32 v119, v124, v124
	v_fmac_f32_e32 v119, v125, v125
	s_waitcnt vmcnt(14)
	v_mov_b64_e32 v[156:157], v[174:175]
	v_mov_b64_e32 v[158:159], v[176:177]
	v_pk_fma_f32 v[120:121], v[114:115], v[120:121], v[156:157]
	s_nop 0
	v_fmac_f32_e32 v119, v120, v120
	v_pk_fma_f32 v[122:123], v[116:117], v[160:161], v[158:159]
	v_fmac_f32_e32 v119, v121, v121
	v_fmac_f32_e32 v119, v122, v122
	v_fmac_f32_e32 v119, v123, v123
	ds_bpermute_b32 v114, v118, v119
	v_xor_b32_e32 v115, 32, v152
	v_cmp_lt_i32_e32 vcc, v115, v153
	global_store_dwordx4 v[128:129], v[120:123], off offset:64
	s_nop 0
	v_cndmask_b32_e32 v116, v152, v115, vcc
	s_waitcnt lgkmcnt(0)
	v_add_f32_e32 v115, v119, v114
	v_lshlrev_b32_e32 v114, 2, v116
	ds_bpermute_b32 v116, v114, v115
	v_cvt_pk_bf16_f32 v120, v120, v121
	v_cvt_pk_bf16_f32 v121, v122, v123
	global_store_dwordx2 v[126:127], v[120:121], off offset:32
	s_and_saveexec_b64 s[2:3], s[0:1]
	s_mov_b32 s87, s93
	s_cbranch_execz .LBB0_233
	v_lshl_add_u64 v[120:121], v[144:145], 2, s[4:5]
	s_waitcnt lgkmcnt(0)
	v_add_f32_e32 v115, v115, v116
	global_atomic_add_f32 v[120:121], v115, off
.LBB0_233:
	s_or_b64 exec, exec, s[2:3]
	s_waitcnt lgkmcnt(0)
	v_add_co_u32_e32 v116, vcc, 0x40000, v142
	v_mul_f32_e32 v115, 0xbfb8aa3b, v110
	s_nop 0
	v_addc_co_u32_e32 v117, vcc, 0, v143, vcc
	s_nop 0
	v_mul_f32_e32 v119, 0xbfb8aa3b, v111
	v_mul_f32_e32 v112, 0xbfb8aa3b, v112
	v_mul_f32_e32 v113, 0xbfb8aa3b, v113
	v_exp_f32_e32 v115, v115
	v_exp_f32_e32 v119, v119
	v_exp_f32_e32 v112, v112
	v_exp_f32_e32 v113, v113
	v_add_f32_e32 v115, 1.0, v115
	v_add_f32_e32 v119, 1.0, v119
	v_add_f32_e32 v124, 1.0, v112
	v_add_f32_e32 v125, 1.0, v113
	v_rcp_f32_e32 v112, v115
	v_rcp_f32_e32 v113, v119
	v_rcp_f32_e32 v124, v124
	v_rcp_f32_e32 v125, v125
	v_add_co_u32_e32 v110, vcc, s79, v128
	s_mov_b32 s2, 0x20000
	s_nop 0
	v_addc_co_u32_e32 v111, vcc, 0, v129, vcc
	v_add_co_u32_e32 v144, vcc, s2, v126
	v_lshl_add_u64 v[116:117], v[142:143], 0, s[38:39]
	s_nop 0
	v_addc_co_u32_e32 v145, vcc, 0, v127, vcc
	v_mul_f32_e32 v98, 0xbfb8aa3b, v98
	v_mul_f32_e32 v99, 0xbfb8aa3b, v99
	v_exp_f32_e32 v98, v98
	v_exp_f32_e32 v99, v99
	v_mul_f32_e32 v100, 0xbfb8aa3b, v100
	v_mul_f32_e32 v101, 0xbfb8aa3b, v101
	v_exp_f32_e32 v100, v100
	v_exp_f32_e32 v101, v101
	v_add_f32_e32 v98, 1.0, v98
	v_add_f32_e32 v99, 1.0, v99
	v_rcp_f32_e32 v98, v98
	v_rcp_f32_e32 v99, v99
	v_add_f32_e32 v100, 1.0, v100
	v_add_f32_e32 v101, 1.0, v101
	s_mov_b64 s[2:3], 0x20000
	s_waitcnt vmcnt(13)
	v_mov_b64_e32 v[120:121], v[178:179]
	v_mov_b64_e32 v[122:123], v[180:181]
	v_pk_fma_f32 v[106:107], v[106:107], v[112:113], v[120:121]
	v_pk_fma_f32 v[108:109], v[108:109], v[124:125], v[122:123]
	global_store_dwordx4 v[110:111], v[106:109], off
	v_cvt_pk_bf16_f32 v110, v106, v107
	v_cvt_pk_bf16_f32 v111, v108, v109
	global_store_dwordx2 v[144:145], v[110:111], off
	s_nop 0
	v_fma_f32 v115, v106, v106, 0
	v_rcp_f32_e32 v116, v100
	v_rcp_f32_e32 v117, v101
	v_fmac_f32_e32 v115, v107, v107
	v_fmac_f32_e32 v115, v108, v108
	v_fmac_f32_e32 v115, v109, v109
	v_lshl_add_u64 v[106:107], v[126:127], 0, s[2:3]
	s_waitcnt vmcnt(12)
	v_mov_b64_e32 v[110:111], v[182:183]
	v_mov_b64_e32 v[112:113], v[184:185]
	v_pk_fma_f32 v[100:101], v[102:103], v[98:99], v[110:111]
	s_nop 0
	v_fmac_f32_e32 v115, v100, v100
	v_fmac_f32_e32 v115, v101, v101
	v_pk_fma_f32 v[102:103], v[104:105], v[116:117], v[112:113]
	v_lshl_add_u64 v[104:105], v[128:129], 0, s[38:39]
	v_fmac_f32_e32 v115, v102, v102
	v_fmac_f32_e32 v115, v103, v103
	ds_bpermute_b32 v98, v118, v115
	global_store_dwordx4 v[104:105], v[100:103], off offset:64
	s_waitcnt lgkmcnt(0)
	v_add_f32_e32 v98, v115, v98
	ds_bpermute_b32 v99, v114, v98
	v_cvt_pk_bf16_f32 v100, v100, v101
	v_cvt_pk_bf16_f32 v101, v102, v103
	global_store_dwordx2 v[106:107], v[100:101], off offset:32
	s_and_saveexec_b64 s[2:3], s[0:1]
	s_cbranch_execz .LBB0_235
	v_lshl_add_u64 v[100:101], v[140:141], 2, s[4:5]
	s_waitcnt lgkmcnt(0)
	v_add_f32_e32 v98, v98, v99
	global_atomic_add_f32 v[100:101], v98, off offset:64
.LBB0_235:
	s_or_b64 exec, exec, s[2:3]
	v_add_co_u32_e32 v98, vcc, 0x80000, v142
	v_mul_f32_e32 v104, 0xbfb8aa3b, v94
	s_waitcnt lgkmcnt(0)
	v_addc_co_u32_e32 v99, vcc, 0, v143, vcc
	s_nop 0
	v_mul_f32_e32 v105, 0xbfb8aa3b, v95
	v_mul_f32_e32 v96, 0xbfb8aa3b, v96
	v_mul_f32_e32 v97, 0xbfb8aa3b, v97
	v_exp_f32_e32 v104, v104
	v_exp_f32_e32 v105, v105
	v_exp_f32_e32 v96, v96
	v_exp_f32_e32 v97, v97
	v_add_f32_e32 v104, 1.0, v104
	v_add_f32_e32 v105, 1.0, v105
	v_add_f32_e32 v106, 1.0, v96
	v_add_f32_e32 v107, 1.0, v97
	s_mov_b32 s2, 0x80000
	v_rcp_f32_e32 v96, v104
	v_rcp_f32_e32 v97, v105
	v_rcp_f32_e32 v104, v106
	v_rcp_f32_e32 v105, v107
	v_add_co_u32_e32 v94, vcc, s2, v128
	v_lshl_add_u64 v[102:103], v[142:143], 0, s[40:41]
	s_nop 0
	v_addc_co_u32_e32 v95, vcc, 0, v129, vcc
	v_add_co_u32_e32 v106, vcc, s79, v126
	v_mul_f32_e32 v82, 0xbfb8aa3b, v82
	s_nop 0
	v_addc_co_u32_e32 v107, vcc, 0, v127, vcc
	v_mul_f32_e32 v83, 0xbfb8aa3b, v83
	v_exp_f32_e32 v82, v82
	v_exp_f32_e32 v83, v83
	v_mul_f32_e32 v84, 0xbfb8aa3b, v84
	v_mul_f32_e32 v85, 0xbfb8aa3b, v85
	v_exp_f32_e32 v84, v84
	v_exp_f32_e32 v85, v85
	v_add_f32_e32 v82, 1.0, v82
	v_add_f32_e32 v83, 1.0, v83
	v_rcp_f32_e32 v82, v82
	v_rcp_f32_e32 v83, v83
	v_add_f32_e32 v84, 1.0, v84
	v_add_f32_e32 v85, 1.0, v85
	s_waitcnt vmcnt(11)
	v_mov_b64_e32 v[98:99], v[186:187]
	v_mov_b64_e32 v[100:101], v[188:189]
	v_pk_fma_f32 v[90:91], v[90:91], v[96:97], v[98:99]
	v_pk_fma_f32 v[92:93], v[92:93], v[104:105], v[100:101]
	global_store_dwordx4 v[94:95], v[90:93], off
	v_cvt_pk_bf16_f32 v94, v90, v91
	v_cvt_pk_bf16_f32 v95, v92, v93
	global_store_dwordx2 v[106:107], v[94:95], off
	s_nop 0
	v_fma_f32 v100, v90, v90, 0
	v_rcp_f32_e32 v98, v84
	v_rcp_f32_e32 v99, v85
	v_fmac_f32_e32 v100, v91, v91
	v_fmac_f32_e32 v100, v92, v92
	v_fmac_f32_e32 v100, v93, v93
	v_lshl_add_u64 v[90:91], v[126:127], 0, s[38:39]
	s_waitcnt vmcnt(10)
	v_mov_b64_e32 v[94:95], v[190:191]
	v_mov_b64_e32 v[96:97], v[192:193]
	v_pk_fma_f32 v[84:85], v[86:87], v[82:83], v[94:95]
	s_nop 0
	v_fmac_f32_e32 v100, v84, v84
	v_fmac_f32_e32 v100, v85, v85
	v_pk_fma_f32 v[86:87], v[88:89], v[98:99], v[96:97]
	v_lshl_add_u64 v[88:89], v[128:129], 0, s[40:41]
	v_fmac_f32_e32 v100, v86, v86
	v_fmac_f32_e32 v100, v87, v87
	ds_bpermute_b32 v82, v118, v100
	global_store_dwordx4 v[88:89], v[84:87], off offset:64
	s_waitcnt lgkmcnt(0)
	v_add_f32_e32 v82, v100, v82
	ds_bpermute_b32 v83, v114, v82
	v_cvt_pk_bf16_f32 v84, v84, v85
	v_cvt_pk_bf16_f32 v85, v86, v87
	global_store_dwordx2 v[90:91], v[84:85], off offset:32
	s_and_saveexec_b64 s[2:3], s[0:1]
	s_cbranch_execz .LBB0_237
	v_lshl_add_u64 v[84:85], v[140:141], 2, s[4:5]
	s_waitcnt lgkmcnt(0)
	v_add_f32_e32 v82, v82, v83
	global_atomic_add_f32 v[84:85], v82, off offset:128
.LBB0_237:
	s_or_b64 exec, exec, s[2:3]
	v_add_co_u32_e32 v82, vcc, 0xc0000, v142
	v_mul_f32_e32 v88, 0xbfb8aa3b, v78
	s_waitcnt lgkmcnt(0)
	v_addc_co_u32_e32 v83, vcc, 0, v143, vcc
	s_nop 0
	v_mul_f32_e32 v89, 0xbfb8aa3b, v79
	v_mul_f32_e32 v80, 0xbfb8aa3b, v80
	v_mul_f32_e32 v81, 0xbfb8aa3b, v81
	v_exp_f32_e32 v88, v88
	v_exp_f32_e32 v89, v89
	v_exp_f32_e32 v80, v80
	v_exp_f32_e32 v81, v81
	v_add_f32_e32 v88, 1.0, v88
	v_add_f32_e32 v89, 1.0, v89
	v_add_f32_e32 v90, 1.0, v80
	v_add_f32_e32 v91, 1.0, v81
	s_mov_b32 s2, 0xc0000
	v_rcp_f32_e32 v80, v88
	v_rcp_f32_e32 v81, v89
	v_rcp_f32_e32 v88, v90
	v_rcp_f32_e32 v89, v91
	v_add_co_u32_e32 v78, vcc, s2, v128
	s_mov_b32 s2, 0x60000
	s_nop 0
	v_addc_co_u32_e32 v79, vcc, 0, v129, vcc
	v_add_co_u32_e32 v90, vcc, s2, v126
	v_lshl_add_u64 v[86:87], v[142:143], 0, s[42:43]
	s_nop 0
	v_addc_co_u32_e32 v91, vcc, 0, v127, vcc
	v_mul_f32_e32 v66, 0xbfb8aa3b, v66
	v_mul_f32_e32 v67, 0xbfb8aa3b, v67
	v_exp_f32_e32 v66, v66
	v_exp_f32_e32 v67, v67
	v_mul_f32_e32 v68, 0xbfb8aa3b, v68
	v_mul_f32_e32 v69, 0xbfb8aa3b, v69
	v_exp_f32_e32 v68, v68
	v_exp_f32_e32 v69, v69
	v_add_f32_e32 v66, 1.0, v66
	v_add_f32_e32 v67, 1.0, v67
	v_rcp_f32_e32 v66, v66
	v_rcp_f32_e32 v67, v67
	v_add_f32_e32 v68, 1.0, v68
	v_add_f32_e32 v69, 1.0, v69
	s_mov_b64 s[2:3], 0x60000
	s_waitcnt vmcnt(9)
	v_mov_b64_e32 v[82:83], v[194:195]
	v_mov_b64_e32 v[84:85], v[196:197]
	v_pk_fma_f32 v[74:75], v[74:75], v[80:81], v[82:83]
	v_pk_fma_f32 v[76:77], v[76:77], v[88:89], v[84:85]
	global_store_dwordx4 v[78:79], v[74:77], off
	v_cvt_pk_bf16_f32 v78, v74, v75
	v_cvt_pk_bf16_f32 v79, v76, v77
	global_store_dwordx2 v[90:91], v[78:79], off
	s_nop 0
	v_fma_f32 v84, v74, v74, 0
	v_rcp_f32_e32 v82, v68
	v_rcp_f32_e32 v83, v69
	v_fmac_f32_e32 v84, v75, v75
	v_fmac_f32_e32 v84, v76, v76
	v_fmac_f32_e32 v84, v77, v77
	v_lshl_add_u64 v[74:75], v[126:127], 0, s[2:3]
	s_waitcnt vmcnt(8)
	v_mov_b64_e32 v[78:79], v[198:199]
	v_mov_b64_e32 v[80:81], v[200:201]
	v_pk_fma_f32 v[68:69], v[70:71], v[66:67], v[78:79]
	s_nop 0
	v_fmac_f32_e32 v84, v68, v68
	v_fmac_f32_e32 v84, v69, v69
	v_pk_fma_f32 v[70:71], v[72:73], v[82:83], v[80:81]
	v_lshl_add_u64 v[72:73], v[128:129], 0, s[42:43]
	v_fmac_f32_e32 v84, v70, v70
	v_fmac_f32_e32 v84, v71, v71
	ds_bpermute_b32 v66, v118, v84
	global_store_dwordx4 v[72:73], v[68:71], off offset:64
	s_waitcnt lgkmcnt(0)
	v_add_f32_e32 v66, v84, v66
	ds_bpermute_b32 v67, v114, v66
	v_cvt_pk_bf16_f32 v68, v68, v69
	v_cvt_pk_bf16_f32 v69, v70, v71
	global_store_dwordx2 v[74:75], v[68:69], off offset:32
	s_and_saveexec_b64 s[2:3], s[0:1]
	s_cbranch_execz .LBB0_239
	v_lshl_add_u64 v[68:69], v[140:141], 2, s[4:5]
	s_waitcnt lgkmcnt(0)
	v_add_f32_e32 v66, v66, v67
	global_atomic_add_f32 v[68:69], v66, off offset:192
.LBB0_239:
	s_or_b64 exec, exec, s[2:3]
	v_add_co_u32_e32 v66, vcc, 0x200000, v142
	v_mul_f32_e32 v72, 0xbfb8aa3b, v62
	s_waitcnt lgkmcnt(0)
	v_addc_co_u32_e32 v67, vcc, 0, v143, vcc
	s_nop 0
	v_mul_f32_e32 v73, 0xbfb8aa3b, v63
	v_mul_f32_e32 v64, 0xbfb8aa3b, v64
	v_mul_f32_e32 v65, 0xbfb8aa3b, v65
	v_exp_f32_e32 v72, v72
	v_exp_f32_e32 v73, v73
	v_exp_f32_e32 v64, v64
	v_exp_f32_e32 v65, v65
	v_add_f32_e32 v72, 1.0, v72
	v_add_f32_e32 v73, 1.0, v73
	v_add_f32_e32 v74, 1.0, v64
	v_add_f32_e32 v75, 1.0, v65
	s_mov_b32 s2, 0x200000
	v_rcp_f32_e32 v64, v72
	v_rcp_f32_e32 v65, v73
	v_rcp_f32_e32 v72, v74
	v_rcp_f32_e32 v73, v75
	v_add_co_u32_e32 v62, vcc, s2, v128
	s_mov_b32 s2, 0x100000
	s_nop 0
	v_addc_co_u32_e32 v63, vcc, 0, v129, vcc
	v_add_co_u32_e32 v74, vcc, s2, v126
	v_lshl_add_u64 v[70:71], v[142:143], 0, s[44:45]
	s_nop 0
	v_addc_co_u32_e32 v75, vcc, 0, v127, vcc
	v_mul_f32_e32 v50, 0xbfb8aa3b, v50
	v_mul_f32_e32 v51, 0xbfb8aa3b, v51
	v_exp_f32_e32 v50, v50
	v_exp_f32_e32 v51, v51
	v_mul_f32_e32 v52, 0xbfb8aa3b, v52
	v_mul_f32_e32 v53, 0xbfb8aa3b, v53
	v_exp_f32_e32 v52, v52
	v_exp_f32_e32 v53, v53
	v_add_f32_e32 v50, 1.0, v50
	v_add_f32_e32 v51, 1.0, v51
	v_rcp_f32_e32 v50, v50
	v_rcp_f32_e32 v51, v51
	v_add_f32_e32 v52, 1.0, v52
	v_add_f32_e32 v53, 1.0, v53
	s_mov_b64 s[2:3], 0x100000
	s_waitcnt vmcnt(7)
	v_mov_b64_e32 v[66:67], v[202:203]
	v_mov_b64_e32 v[68:69], v[204:205]
	v_pk_fma_f32 v[58:59], v[58:59], v[64:65], v[66:67]
	v_pk_fma_f32 v[60:61], v[60:61], v[72:73], v[68:69]
	global_store_dwordx4 v[62:63], v[58:61], off
	v_cvt_pk_bf16_f32 v62, v58, v59
	v_cvt_pk_bf16_f32 v63, v60, v61
	global_store_dwordx2 v[74:75], v[62:63], off
	s_nop 0
	v_fma_f32 v68, v58, v58, 0
	v_rcp_f32_e32 v66, v52
	v_rcp_f32_e32 v67, v53
	v_fmac_f32_e32 v68, v59, v59
	v_fmac_f32_e32 v68, v60, v60
	v_fmac_f32_e32 v68, v61, v61
	v_lshl_add_u64 v[58:59], v[126:127], 0, s[2:3]
	s_waitcnt vmcnt(6)
	v_mov_b64_e32 v[62:63], v[206:207]
	v_mov_b64_e32 v[64:65], v[208:209]
	v_pk_fma_f32 v[52:53], v[54:55], v[50:51], v[62:63]
	s_nop 0
	v_fmac_f32_e32 v68, v52, v52
	v_fmac_f32_e32 v68, v53, v53
	v_pk_fma_f32 v[54:55], v[56:57], v[66:67], v[64:65]
	v_lshl_add_u64 v[56:57], v[128:129], 0, s[44:45]
	v_fmac_f32_e32 v68, v54, v54
	v_fmac_f32_e32 v68, v55, v55
	ds_bpermute_b32 v50, v118, v68
	global_store_dwordx4 v[56:57], v[52:55], off offset:64
	s_waitcnt lgkmcnt(0)
	v_add_f32_e32 v50, v68, v50
	ds_bpermute_b32 v51, v114, v50
	v_cvt_pk_bf16_f32 v52, v52, v53
	v_cvt_pk_bf16_f32 v53, v54, v55
	global_store_dwordx2 v[58:59], v[52:53], off offset:32
	s_and_saveexec_b64 s[2:3], s[0:1]
	s_cbranch_execz .LBB0_241
	v_lshl_add_u64 v[52:53], v[140:141], 2, s[4:5]
	s_waitcnt lgkmcnt(0)
	v_add_f32_e32 v50, v50, v51
	global_atomic_add_f32 v[52:53], v50, off offset:512
.LBB0_241:
	s_or_b64 exec, exec, s[2:3]
	v_add_co_u32_e32 v50, vcc, 0x240000, v142
	v_mul_f32_e32 v56, 0xbfb8aa3b, v46
	s_waitcnt lgkmcnt(0)
	v_addc_co_u32_e32 v51, vcc, 0, v143, vcc
	s_nop 0
	v_mul_f32_e32 v57, 0xbfb8aa3b, v47
	v_mul_f32_e32 v48, 0xbfb8aa3b, v48
	v_mul_f32_e32 v49, 0xbfb8aa3b, v49
	v_exp_f32_e32 v56, v56
	v_exp_f32_e32 v57, v57
	v_exp_f32_e32 v48, v48
	v_exp_f32_e32 v49, v49
	v_add_f32_e32 v56, 1.0, v56
	v_add_f32_e32 v57, 1.0, v57
	v_add_f32_e32 v58, 1.0, v48
	v_add_f32_e32 v59, 1.0, v49
	s_mov_b32 s2, 0x240000
	v_rcp_f32_e32 v48, v56
	v_rcp_f32_e32 v49, v57
	v_rcp_f32_e32 v56, v58
	v_rcp_f32_e32 v57, v59
	v_add_co_u32_e32 v46, vcc, s2, v128
	s_mov_b32 s2, 0x120000
	s_nop 0
	v_addc_co_u32_e32 v47, vcc, 0, v129, vcc
	v_add_co_u32_e32 v58, vcc, s2, v126
	v_lshl_add_u64 v[54:55], v[142:143], 0, s[46:47]
	s_nop 0
	v_addc_co_u32_e32 v59, vcc, 0, v127, vcc
	v_mul_f32_e32 v34, 0xbfb8aa3b, v34
	v_mul_f32_e32 v35, 0xbfb8aa3b, v35
	v_exp_f32_e32 v34, v34
	v_exp_f32_e32 v35, v35
	v_mul_f32_e32 v36, 0xbfb8aa3b, v36
	v_mul_f32_e32 v37, 0xbfb8aa3b, v37
	v_exp_f32_e32 v36, v36
	v_exp_f32_e32 v37, v37
	v_add_f32_e32 v34, 1.0, v34
	v_add_f32_e32 v35, 1.0, v35
	v_rcp_f32_e32 v34, v34
	v_rcp_f32_e32 v35, v35
	v_add_f32_e32 v36, 1.0, v36
	v_add_f32_e32 v37, 1.0, v37
	s_mov_b64 s[2:3], 0x120000
	s_waitcnt vmcnt(5)
	v_mov_b64_e32 v[50:51], v[210:211]
	v_mov_b64_e32 v[52:53], v[212:213]
	v_pk_fma_f32 v[42:43], v[42:43], v[48:49], v[50:51]
	v_pk_fma_f32 v[44:45], v[44:45], v[56:57], v[52:53]
	global_store_dwordx4 v[46:47], v[42:45], off
	v_cvt_pk_bf16_f32 v46, v42, v43
	v_cvt_pk_bf16_f32 v47, v44, v45
	global_store_dwordx2 v[58:59], v[46:47], off
	s_nop 0
	v_fma_f32 v52, v42, v42, 0
	v_rcp_f32_e32 v50, v36
	v_rcp_f32_e32 v51, v37
	v_fmac_f32_e32 v52, v43, v43
	v_fmac_f32_e32 v52, v44, v44
	v_fmac_f32_e32 v52, v45, v45
	v_lshl_add_u64 v[42:43], v[126:127], 0, s[2:3]
	s_waitcnt vmcnt(4)
	v_mov_b64_e32 v[46:47], v[214:215]
	v_mov_b64_e32 v[48:49], v[216:217]
	v_pk_fma_f32 v[36:37], v[38:39], v[34:35], v[46:47]
	s_nop 0
	v_fmac_f32_e32 v52, v36, v36
	v_fmac_f32_e32 v52, v37, v37
	v_pk_fma_f32 v[38:39], v[40:41], v[50:51], v[48:49]
	v_lshl_add_u64 v[40:41], v[128:129], 0, s[46:47]
	v_fmac_f32_e32 v52, v38, v38
	v_fmac_f32_e32 v52, v39, v39
	ds_bpermute_b32 v34, v118, v52
	global_store_dwordx4 v[40:41], v[36:39], off offset:64
	s_waitcnt lgkmcnt(0)
	v_add_f32_e32 v34, v52, v34
	ds_bpermute_b32 v35, v114, v34
	v_cvt_pk_bf16_f32 v36, v36, v37
	v_cvt_pk_bf16_f32 v37, v38, v39
	global_store_dwordx2 v[42:43], v[36:37], off offset:32
	s_and_saveexec_b64 s[2:3], s[0:1]
	s_cbranch_execz .LBB0_243
	v_lshl_add_u64 v[36:37], v[140:141], 2, s[4:5]
	s_waitcnt lgkmcnt(0)
	v_add_f32_e32 v34, v34, v35
	global_atomic_add_f32 v[36:37], v34, off offset:576
.LBB0_243:
	s_or_b64 exec, exec, s[2:3]
	v_add_co_u32_e32 v34, vcc, 0x280000, v142
	v_mul_f32_e32 v40, 0xbfb8aa3b, v30
	s_waitcnt lgkmcnt(0)
	v_addc_co_u32_e32 v35, vcc, 0, v143, vcc
	s_nop 0
	v_mul_f32_e32 v41, 0xbfb8aa3b, v31
	v_mul_f32_e32 v32, 0xbfb8aa3b, v32
	v_mul_f32_e32 v33, 0xbfb8aa3b, v33
	v_exp_f32_e32 v40, v40
	v_exp_f32_e32 v41, v41
	v_exp_f32_e32 v32, v32
	v_exp_f32_e32 v33, v33
	v_add_f32_e32 v40, 1.0, v40
	v_add_f32_e32 v41, 1.0, v41
	v_add_f32_e32 v42, 1.0, v32
	v_add_f32_e32 v43, 1.0, v33
	s_mov_b32 s2, 0x280000
	v_rcp_f32_e32 v32, v40
	v_rcp_f32_e32 v33, v41
	v_rcp_f32_e32 v40, v42
	v_rcp_f32_e32 v41, v43
	v_add_co_u32_e32 v30, vcc, s2, v128
	s_mov_b32 s2, 0x140000
	s_nop 0
	v_addc_co_u32_e32 v31, vcc, 0, v129, vcc
	v_add_co_u32_e32 v42, vcc, s2, v126
	v_lshl_add_u64 v[38:39], v[142:143], 0, s[48:49]
	s_nop 0
	v_addc_co_u32_e32 v43, vcc, 0, v127, vcc
	v_mul_f32_e32 v18, 0xbfb8aa3b, v18
	v_mul_f32_e32 v19, 0xbfb8aa3b, v19
	v_exp_f32_e32 v18, v18
	v_exp_f32_e32 v19, v19
	v_mul_f32_e32 v20, 0xbfb8aa3b, v20
	v_mul_f32_e32 v21, 0xbfb8aa3b, v21
	v_exp_f32_e32 v20, v20
	v_exp_f32_e32 v21, v21
	v_add_f32_e32 v18, 1.0, v18
	v_add_f32_e32 v19, 1.0, v19
	v_rcp_f32_e32 v18, v18
	v_rcp_f32_e32 v19, v19
	v_add_f32_e32 v20, 1.0, v20
	v_add_f32_e32 v21, 1.0, v21
	s_mov_b64 s[2:3], 0x140000
	s_waitcnt vmcnt(3)
	v_mov_b64_e32 v[34:35], v[218:219]
	v_mov_b64_e32 v[36:37], v[220:221]
	v_pk_fma_f32 v[26:27], v[26:27], v[32:33], v[34:35]
	v_pk_fma_f32 v[28:29], v[28:29], v[40:41], v[36:37]
	global_store_dwordx4 v[30:31], v[26:29], off
	v_cvt_pk_bf16_f32 v30, v26, v27
	v_cvt_pk_bf16_f32 v31, v28, v29
	global_store_dwordx2 v[42:43], v[30:31], off
	s_nop 0
	v_fma_f32 v36, v26, v26, 0
	v_rcp_f32_e32 v34, v20
	v_rcp_f32_e32 v35, v21
	v_fmac_f32_e32 v36, v27, v27
	v_fmac_f32_e32 v36, v28, v28
	v_fmac_f32_e32 v36, v29, v29
	v_lshl_add_u64 v[26:27], v[126:127], 0, s[2:3]
	s_waitcnt vmcnt(2)
	v_mov_b64_e32 v[30:31], v[222:223]
	v_mov_b64_e32 v[32:33], v[224:225]
	v_pk_fma_f32 v[20:21], v[22:23], v[18:19], v[30:31]
	s_nop 0
	v_fmac_f32_e32 v36, v20, v20
	v_fmac_f32_e32 v36, v21, v21
	v_pk_fma_f32 v[22:23], v[24:25], v[34:35], v[32:33]
	v_lshl_add_u64 v[24:25], v[128:129], 0, s[48:49]
	v_fmac_f32_e32 v36, v22, v22
	v_fmac_f32_e32 v36, v23, v23
	ds_bpermute_b32 v18, v118, v36
	global_store_dwordx4 v[24:25], v[20:23], off offset:64
	s_waitcnt lgkmcnt(0)
	v_add_f32_e32 v18, v36, v18
	ds_bpermute_b32 v19, v114, v18
	v_cvt_pk_bf16_f32 v20, v20, v21
	v_cvt_pk_bf16_f32 v21, v22, v23
	global_store_dwordx2 v[26:27], v[20:21], off offset:32
	s_and_saveexec_b64 s[2:3], s[0:1]
	s_cbranch_execz .LBB0_245
	v_lshl_add_u64 v[20:21], v[140:141], 2, s[4:5]
	s_waitcnt lgkmcnt(0)
	v_add_f32_e32 v18, v18, v19
	global_atomic_add_f32 v[20:21], v18, off offset:640
.LBB0_245:
	s_or_b64 exec, exec, s[2:3]
	v_add_co_u32_e32 v18, vcc, 0x2c0000, v142
	v_mul_f32_e32 v24, 0xbfb8aa3b, v14
	s_waitcnt lgkmcnt(0)
	v_addc_co_u32_e32 v19, vcc, 0, v143, vcc
	s_nop 0
	v_mul_f32_e32 v25, 0xbfb8aa3b, v15
	v_mul_f32_e32 v16, 0xbfb8aa3b, v16
	v_mul_f32_e32 v17, 0xbfb8aa3b, v17
	v_exp_f32_e32 v24, v24
	v_exp_f32_e32 v25, v25
	v_exp_f32_e32 v16, v16
	v_exp_f32_e32 v17, v17
	v_add_f32_e32 v24, 1.0, v24
	v_add_f32_e32 v25, 1.0, v25
	v_add_f32_e32 v26, 1.0, v16
	v_add_f32_e32 v27, 1.0, v17
	s_mov_b32 s2, 0x2c0000
	v_rcp_f32_e32 v16, v24
	v_rcp_f32_e32 v17, v25
	v_rcp_f32_e32 v24, v26
	v_rcp_f32_e32 v25, v27
	v_add_co_u32_e32 v14, vcc, s2, v128
	s_mov_b32 s2, 0x160000
	s_nop 0
	v_addc_co_u32_e32 v15, vcc, 0, v129, vcc
	v_add_co_u32_e32 v26, vcc, s2, v126
	v_lshl_add_u64 v[22:23], v[142:143], 0, s[66:67]
	s_nop 0
	v_addc_co_u32_e32 v27, vcc, 0, v127, vcc
	v_mul_f32_e32 v2, 0xbfb8aa3b, v2
	v_mul_f32_e32 v3, 0xbfb8aa3b, v3
	v_exp_f32_e32 v2, v2
	v_exp_f32_e32 v3, v3
	v_mul_f32_e32 v4, 0xbfb8aa3b, v4
	v_mul_f32_e32 v5, 0xbfb8aa3b, v5
	v_exp_f32_e32 v4, v4
	v_exp_f32_e32 v5, v5
	v_add_f32_e32 v2, 1.0, v2
	v_add_f32_e32 v3, 1.0, v3
	v_rcp_f32_e32 v2, v2
	v_rcp_f32_e32 v3, v3
	v_add_f32_e32 v4, 1.0, v4
	v_add_f32_e32 v5, 1.0, v5
	s_mov_b64 s[2:3], 0x160000
	s_waitcnt vmcnt(1)
	v_mov_b64_e32 v[18:19], v[226:227]
	v_mov_b64_e32 v[20:21], v[228:229]
	v_pk_fma_f32 v[10:11], v[10:11], v[16:17], v[18:19]
	v_pk_fma_f32 v[12:13], v[12:13], v[24:25], v[20:21]
	global_store_dwordx4 v[14:15], v[10:13], off
	v_cvt_pk_bf16_f32 v14, v10, v11
	v_cvt_pk_bf16_f32 v15, v12, v13
	global_store_dwordx2 v[26:27], v[14:15], off
	s_nop 0
	v_fma_f32 v20, v10, v10, 0
	v_rcp_f32_e32 v18, v4
	v_rcp_f32_e32 v19, v5
	v_fmac_f32_e32 v20, v11, v11
	v_fmac_f32_e32 v20, v12, v12
	v_fmac_f32_e32 v20, v13, v13
	v_lshl_add_u64 v[10:11], v[126:127], 0, s[2:3]
	s_waitcnt vmcnt(0)
	v_mov_b64_e32 v[14:15], v[230:231]
	v_mov_b64_e32 v[16:17], v[232:233]
	v_pk_fma_f32 v[4:5], v[6:7], v[2:3], v[14:15]
	s_nop 0
	v_fmac_f32_e32 v20, v4, v4
	v_fmac_f32_e32 v20, v5, v5
	v_pk_fma_f32 v[6:7], v[8:9], v[18:19], v[16:17]
	v_lshl_add_u64 v[8:9], v[128:129], 0, s[66:67]
	v_fmac_f32_e32 v20, v6, v6
	v_fmac_f32_e32 v20, v7, v7
	ds_bpermute_b32 v2, v118, v20
	global_store_dwordx4 v[8:9], v[4:7], off offset:64
	s_waitcnt lgkmcnt(0)
	v_add_f32_e32 v2, v20, v2
	ds_bpermute_b32 v3, v114, v2
	v_cvt_pk_bf16_f32 v4, v4, v5
	v_cvt_pk_bf16_f32 v5, v6, v7
	global_store_dwordx2 v[10:11], v[4:5], off offset:32
	s_and_saveexec_b64 s[2:3], s[0:1]
	s_cbranch_execz .LBB0_247
	v_lshl_add_u64 v[4:5], v[140:141], 2, s[4:5]
	s_waitcnt lgkmcnt(0)
	v_add_f32_e32 v2, v2, v3
	global_atomic_add_f32 v[4:5], v2, off offset:704

.LBB0_479:
	v_lshl_add_u32 v142, s36, 8, v148
	v_ashrrev_i32_e32 v143, 31, v142
	v_lshl_add_u64 v[146:147], v[142:143], 2, s[4:5]
	global_load_dword v241, v[146:147], off
	global_load_dword v242, v[146:147], off offset:64
	global_load_dword v243, v[146:147], off offset:128
	global_load_dword v244, v[146:147], off offset:192
	global_load_dword v245, v[146:147], off offset:512
	global_load_dword v246, v[146:147], off offset:576
	global_load_dword v247, v[146:147], off offset:640
	global_load_dword v248, v[146:147], off offset:704
	v_mov_b32_e32 v168, v125
	v_mov_b32_e32 v160, v127
	v_mov_b32_e32 v158, v118
	v_mov_b32_e32 v162, v129
	v_lshl_or_b32 v156, s22, 7, v150
	v_mov_b64_e32 v[144:145], s[6:7]
	v_ashrrev_i32_e32 v157, 31, v156
	v_or_b32_e32 v172, 16, v142
	v_mov_b32_e32 v164, v122
	v_mov_b32_e32 v166, v123
	v_mad_i64_i32 v[170:171], s[2:3], v142, s60, v[144:145]
	v_lshlrev_b64 v[122:123], 1, v[156:157]
	v_ashrrev_i32_e32 v173, 31, v172
	v_lshl_add_u64 v[156:157], v[170:171], 0, v[122:123]
	v_lshl_add_u64 v[170:171], v[172:173], 2, s[4:5]
	s_andn2_b64 vcc, exec, s[38:39]
	s_waitcnt vmcnt(7)
	v_mov_b32_e32 v143, v241
	v_fmamk_f32 v125, v143, 0x39800000, v155
	v_rsq_f32_e32 v125, v125
	s_nop 0
	v_mul_f32_e32 v127, 0xbfb8aa3b, v125
	v_mul_f32_e32 v118, v118, v127
	v_mul_f32_e32 v159, v125, v125
	v_mul_f32_e32 v125, v119, v127
	v_mul_f32_e32 v129, v120, v127
	v_mul_f32_e32 v143, v121, v127
	v_mul_f32_e32 v161, v114, v127
	v_mul_f32_e32 v163, v115, v127
	v_mul_f32_e32 v165, v116, v127
	v_mul_f32_e32 v127, v117, v127
	v_exp_f32_e32 v118, v118
	v_exp_f32_e32 v125, v125
	v_exp_f32_e32 v127, v127
	v_exp_f32_e32 v129, v129
	v_exp_f32_e32 v161, v161
	v_exp_f32_e32 v143, v143
	v_exp_f32_e32 v163, v163
	v_add_f32_e32 v118, 1.0, v118
	v_exp_f32_e32 v165, v165
	v_add_f32_e32 v125, 1.0, v125
	v_add_f32_e32 v174, 1.0, v127
	v_rcp_f32_e32 v127, v118
	v_add_f32_e32 v129, 1.0, v129
	v_add_f32_e32 v167, 1.0, v161
	v_rcp_f32_e32 v161, v125
	v_add_f32_e32 v143, 1.0, v143
	v_rcp_f32_e32 v129, v129
	v_add_f32_e32 v169, 1.0, v163
	v_rcp_f32_e32 v163, v143
	v_add_f32_e32 v173, 1.0, v165
	v_rcp_f32_e32 v165, v167
	v_pk_mul_f32 v[126:127], v[158:159], v[126:127]
	v_mov_b32_e32 v158, v119
	v_rcp_f32_e32 v167, v169
	v_pk_mul_f32 v[118:119], v[158:159], v[160:161]
	v_mov_b32_e32 v158, v120
	v_rcp_f32_e32 v125, v173
	v_mul_f32_e32 v120, v118, v119
	v_pk_mul_f32 v[118:119], v[158:159], v[128:129]
	v_mov_b32_e32 v158, v121
	v_rcp_f32_e32 v169, v174
	v_mul_f32_e32 v121, v118, v119
	v_pk_mul_f32 v[118:119], v[158:159], v[162:163]
	v_mov_b32_e32 v158, v114
	v_mul_f32_e32 v126, v126, v127
	v_cvt_pk_bf16_f32 v114, v126, v120
	v_mul_f32_e32 v120, v118, v119
	v_pk_mul_f32 v[118:119], v[158:159], v[164:165]
	v_mov_b32_e32 v158, v115
	v_mul_f32_e32 v126, v118, v119
	v_pk_mul_f32 v[118:119], v[158:159], v[166:167]
	v_mov_b32_e32 v158, v116
	v_mul_f32_e32 v116, v118, v119
	v_pk_mul_f32 v[118:119], v[158:159], v[124:125]
	v_mov_b32_e32 v158, v117
	v_mul_f32_e32 v117, v118, v119
	v_pk_mul_f32 v[118:119], v[158:159], v[168:169]
	v_cvt_pk_bf16_f32 v115, v121, v120
	v_cvt_pk_bf16_f32 v116, v126, v116
	v_mov_b32_e32 v120, v107
	v_mul_f32_e32 v118, v118, v119
	v_cvt_pk_bf16_f32 v117, v117, v118
	global_store_dwordx4 v[156:157], v[114:117], off
	s_nop 0
	v_mov_b32_e32 v124, v109
	v_mov_b32_e32 v114, v102
	v_mov_b32_e32 v116, v111
	v_mov_b32_e32 v118, v113
	v_or_b32_e32 v126, 32, v142
	v_ashrrev_i32_e32 v127, 31, v126
	v_lshl_add_u64 v[156:157], v[126:127], 2, s[4:5]
	v_mad_i64_i32 v[128:129], s[2:3], v172, s60, v[144:145]
	v_lshl_add_u64 v[128:129], v[128:129], 0, v[122:123]
	s_waitcnt vmcnt(6)
	v_mov_b32_e32 v115, v242
	v_fmamk_f32 v107, v115, 0x39800000, v155
	v_rsq_f32_e32 v107, v107
	s_nop 0
	v_mul_f32_e32 v109, 0xbfb8aa3b, v107
	v_mul_f32_e32 v102, v102, v109
	v_mul_f32_e32 v115, v107, v107
	v_mul_f32_e32 v107, v103, v109
	v_mul_f32_e32 v111, v104, v109
	v_exp_f32_e32 v102, v102
	v_mul_f32_e32 v117, v98, v109
	v_exp_f32_e32 v107, v107
	v_exp_f32_e32 v111, v111
	v_mul_f32_e32 v113, v105, v109
	v_exp_f32_e32 v117, v117
	v_mul_f32_e32 v119, v99, v109
	v_exp_f32_e32 v113, v113
	v_exp_f32_e32 v119, v119
	v_add_f32_e32 v102, 1.0, v102
	v_mul_f32_e32 v121, v100, v109
	v_add_f32_e32 v107, 1.0, v107
	v_add_f32_e32 v125, 1.0, v111
	v_rcp_f32_e32 v111, v102
	v_mul_f32_e32 v109, v101, v109
	v_exp_f32_e32 v121, v121
	v_add_f32_e32 v143, 1.0, v117
	v_rcp_f32_e32 v117, v107
	v_exp_f32_e32 v109, v109
	v_add_f32_e32 v127, 1.0, v113
	v_rcp_f32_e32 v113, v125
	v_add_f32_e32 v158, 1.0, v119
	v_rcp_f32_e32 v119, v127
	v_rcp_f32_e32 v107, v143
	v_pk_mul_f32 v[110:111], v[114:115], v[110:111]
	v_mov_b32_e32 v114, v103
	v_add_f32_e32 v159, 1.0, v121
	v_rcp_f32_e32 v121, v158
	v_pk_mul_f32 v[102:103], v[114:115], v[116:117]
	v_mov_b32_e32 v114, v104
	v_add_f32_e32 v160, 1.0, v109
	v_rcp_f32_e32 v109, v159
	v_mul_f32_e32 v104, v102, v103
	v_pk_mul_f32 v[102:103], v[114:115], v[112:113]
	v_mov_b32_e32 v114, v105
	v_rcp_f32_e32 v125, v160
	v_mul_f32_e32 v105, v102, v103
	v_pk_mul_f32 v[102:103], v[114:115], v[118:119]
	v_mov_b32_e32 v114, v98
	v_mul_f32_e32 v110, v110, v111
	v_cvt_pk_bf16_f32 v98, v110, v104
	v_mul_f32_e32 v104, v102, v103
	v_pk_mul_f32 v[102:103], v[114:115], v[106:107]
	v_mov_b32_e32 v114, v99
	v_mul_f32_e32 v106, v102, v103
	v_pk_mul_f32 v[102:103], v[114:115], v[120:121]
	v_mov_b32_e32 v114, v100
	v_mul_f32_e32 v100, v102, v103
	v_pk_mul_f32 v[102:103], v[114:115], v[108:109]
	v_mov_b32_e32 v114, v101
	v_mul_f32_e32 v101, v102, v103
	v_pk_mul_f32 v[102:103], v[114:115], v[124:125]
	v_cvt_pk_bf16_f32 v99, v105, v104
	v_cvt_pk_bf16_f32 v100, v106, v100
	v_mov_b32_e32 v104, v91
	v_mul_f32_e32 v102, v102, v103
	v_cvt_pk_bf16_f32 v101, v101, v102
	global_store_dwordx4 v[128:129], v[98:101], off
	s_nop 0
	v_mov_b32_e32 v106, v93
	v_mov_b32_e32 v98, v86
	v_mov_b32_e32 v100, v95
	v_mov_b32_e32 v102, v97
	v_or_b32_e32 v108, 48, v142
	v_ashrrev_i32_e32 v109, 31, v108
	v_lshl_add_u64 v[112:113], v[108:109], 2, s[4:5]
	v_mad_i64_i32 v[110:111], s[2:3], v126, s60, v[144:145]
	v_lshl_add_u64 v[110:111], v[110:111], 0, v[122:123]
	s_waitcnt vmcnt(5)
	v_mov_b32_e32 v99, v243
	v_fmamk_f32 v91, v99, 0x39800000, v155
	v_rsq_f32_e32 v91, v91
	s_nop 0
	v_mul_f32_e32 v93, 0xbfb8aa3b, v91
	v_mul_f32_e32 v86, v86, v93
	v_mul_f32_e32 v99, v91, v91
	v_mul_f32_e32 v91, v87, v93
	v_mul_f32_e32 v95, v88, v93
	v_exp_f32_e32 v86, v86
	v_mul_f32_e32 v101, v82, v93
	v_exp_f32_e32 v91, v91
	v_exp_f32_e32 v95, v95
	v_mul_f32_e32 v97, v89, v93
	v_exp_f32_e32 v101, v101
	v_mul_f32_e32 v103, v83, v93
	v_exp_f32_e32 v97, v97
	v_exp_f32_e32 v103, v103
	v_add_f32_e32 v86, 1.0, v86
	v_mul_f32_e32 v105, v84, v93
	v_add_f32_e32 v91, 1.0, v91
	v_add_f32_e32 v107, 1.0, v95
	v_rcp_f32_e32 v95, v86
	v_mul_f32_e32 v93, v85, v93
	v_exp_f32_e32 v105, v105
	v_add_f32_e32 v114, 1.0, v101
	v_rcp_f32_e32 v101, v91
	v_exp_f32_e32 v93, v93
	v_add_f32_e32 v109, 1.0, v97
	v_rcp_f32_e32 v97, v107
	v_add_f32_e32 v115, 1.0, v103
	v_rcp_f32_e32 v103, v109
	v_rcp_f32_e32 v91, v114
	v_pk_mul_f32 v[94:95], v[98:99], v[94:95]
	v_mov_b32_e32 v98, v87
	v_add_f32_e32 v116, 1.0, v105
	v_rcp_f32_e32 v105, v115
	v_pk_mul_f32 v[86:87], v[98:99], v[100:101]
	v_mov_b32_e32 v98, v88
	v_add_f32_e32 v117, 1.0, v93
	v_rcp_f32_e32 v93, v116
	v_mul_f32_e32 v88, v86, v87
	v_pk_mul_f32 v[86:87], v[98:99], v[96:97]
	v_mov_b32_e32 v98, v89
	v_rcp_f32_e32 v107, v117
	v_mul_f32_e32 v89, v86, v87
	v_pk_mul_f32 v[86:87], v[98:99], v[102:103]
	v_mov_b32_e32 v98, v82
	v_mul_f32_e32 v94, v94, v95
	v_cvt_pk_bf16_f32 v82, v94, v88
	v_mul_f32_e32 v88, v86, v87
	v_pk_mul_f32 v[86:87], v[98:99], v[90:91]
	v_mov_b32_e32 v98, v83
	v_mul_f32_e32 v90, v86, v87
	v_pk_mul_f32 v[86:87], v[98:99], v[104:105]
	v_mov_b32_e32 v98, v84
	v_mul_f32_e32 v84, v86, v87
	v_pk_mul_f32 v[86:87], v[98:99], v[92:93]
	v_mov_b32_e32 v98, v85
	v_mul_f32_e32 v85, v86, v87
	v_pk_mul_f32 v[86:87], v[98:99], v[106:107]
	v_cvt_pk_bf16_f32 v83, v89, v88
	v_cvt_pk_bf16_f32 v84, v90, v84
	v_mov_b32_e32 v88, v75
	v_mul_f32_e32 v86, v86, v87
	v_cvt_pk_bf16_f32 v85, v85, v86
	global_store_dwordx4 v[110:111], v[82:85], off
	s_nop 0
	v_mov_b32_e32 v90, v77
	v_mov_b32_e32 v82, v70
	v_mov_b32_e32 v84, v79
	v_mov_b32_e32 v86, v81
	v_mad_i64_i32 v[92:93], s[2:3], v108, s60, v[144:145]
	v_lshl_add_u64 v[92:93], v[92:93], 0, v[122:123]
	s_waitcnt vmcnt(4)
	v_mov_b32_e32 v83, v244
	v_fmamk_f32 v75, v83, 0x39800000, v155
	v_rsq_f32_e32 v75, v75
	s_nop 0
	v_mul_f32_e32 v77, 0xbfb8aa3b, v75
	v_mul_f32_e32 v70, v70, v77
	v_mul_f32_e32 v83, v75, v75
	v_mul_f32_e32 v75, v71, v77
	v_mul_f32_e32 v79, v72, v77
	v_exp_f32_e32 v70, v70
	v_mul_f32_e32 v85, v66, v77
	v_exp_f32_e32 v75, v75
	v_exp_f32_e32 v79, v79
	v_mul_f32_e32 v81, v73, v77
	v_exp_f32_e32 v85, v85
	v_mul_f32_e32 v87, v67, v77
	v_exp_f32_e32 v81, v81
	v_exp_f32_e32 v87, v87
	v_add_f32_e32 v70, 1.0, v70
	v_mul_f32_e32 v89, v68, v77
	v_add_f32_e32 v75, 1.0, v75
	v_add_f32_e32 v91, 1.0, v79
	v_rcp_f32_e32 v79, v70
	v_mul_f32_e32 v77, v69, v77
	v_exp_f32_e32 v89, v89
	v_add_f32_e32 v95, 1.0, v85
	v_rcp_f32_e32 v85, v75
	v_exp_f32_e32 v77, v77
	v_add_f32_e32 v94, 1.0, v81
	v_rcp_f32_e32 v81, v91
	v_add_f32_e32 v96, 1.0, v87
	v_rcp_f32_e32 v87, v94
	v_rcp_f32_e32 v75, v95
	v_pk_mul_f32 v[78:79], v[82:83], v[78:79]
	v_mov_b32_e32 v82, v71
	v_add_f32_e32 v97, 1.0, v89
	v_rcp_f32_e32 v89, v96
	v_pk_mul_f32 v[70:71], v[82:83], v[84:85]
	v_mov_b32_e32 v82, v72
	v_add_f32_e32 v98, 1.0, v77
	v_rcp_f32_e32 v77, v97
	v_mul_f32_e32 v72, v70, v71
	v_pk_mul_f32 v[70:71], v[82:83], v[80:81]
	v_mov_b32_e32 v82, v73
	v_rcp_f32_e32 v91, v98
	v_mul_f32_e32 v73, v70, v71
	v_pk_mul_f32 v[70:71], v[82:83], v[86:87]
	v_mov_b32_e32 v82, v66
	v_mul_f32_e32 v78, v78, v79
	v_cvt_pk_bf16_f32 v66, v78, v72
	v_mul_f32_e32 v72, v70, v71
	v_pk_mul_f32 v[70:71], v[82:83], v[74:75]
	v_mov_b32_e32 v82, v67
	v_mul_f32_e32 v74, v70, v71
	v_pk_mul_f32 v[70:71], v[82:83], v[88:89]
	v_mov_b32_e32 v82, v68
	v_mul_f32_e32 v68, v70, v71
	v_pk_mul_f32 v[70:71], v[82:83], v[76:77]
	v_mov_b32_e32 v82, v69
	v_mul_f32_e32 v69, v70, v71
	v_pk_mul_f32 v[70:71], v[82:83], v[90:91]
	v_cvt_pk_bf16_f32 v67, v73, v72
	v_cvt_pk_bf16_f32 v68, v74, v68
	v_mov_b32_e32 v74, v61
	v_mul_f32_e32 v70, v70, v71
	v_cvt_pk_bf16_f32 v69, v69, v70
	global_store_dwordx4 v[92:93], v[66:69], off
	s_nop 0
	v_mov_b32_e32 v72, v59
	v_add_u32_e32 v59, 0x80, v142
	v_mad_i64_i32 v[76:77], s[2:3], v59, s60, v[144:145]
	v_mov_b32_e32 v66, v54
	v_mov_b32_e32 v68, v63
	v_mov_b32_e32 v70, v65
	v_lshl_add_u64 v[76:77], v[76:77], 0, v[122:123]
	s_waitcnt vmcnt(3)
	v_mov_b32_e32 v67, v245
	v_fmamk_f32 v61, v67, 0x39800000, v155
	v_rsq_f32_e32 v61, v61
	s_nop 0
	v_mul_f32_e32 v59, 0xbfb8aa3b, v61
	v_mul_f32_e32 v54, v54, v59
	v_mul_f32_e32 v67, v61, v61
	v_mul_f32_e32 v61, v55, v59
	v_mul_f32_e32 v63, v56, v59
	v_exp_f32_e32 v54, v54
	v_mul_f32_e32 v69, v50, v59
	v_exp_f32_e32 v61, v61
	v_exp_f32_e32 v63, v63
	v_mul_f32_e32 v65, v57, v59
	v_exp_f32_e32 v69, v69
	v_mul_f32_e32 v71, v51, v59
	v_exp_f32_e32 v65, v65
	v_mul_f32_e32 v73, v52, v59
	v_mul_f32_e32 v59, v53, v59
	v_exp_f32_e32 v71, v71
	v_add_f32_e32 v54, 1.0, v54
	v_exp_f32_e32 v59, v59
	v_add_f32_e32 v61, 1.0, v61
	v_add_f32_e32 v75, 1.0, v63
	v_rcp_f32_e32 v63, v54
	v_exp_f32_e32 v73, v73
	v_add_f32_e32 v79, 1.0, v69
	v_rcp_f32_e32 v69, v61
	v_add_f32_e32 v78, 1.0, v65
	v_rcp_f32_e32 v65, v75
	v_add_f32_e32 v80, 1.0, v71
	v_rcp_f32_e32 v71, v78
	v_add_f32_e32 v82, 1.0, v59
	v_rcp_f32_e32 v59, v79
	v_pk_mul_f32 v[62:63], v[66:67], v[62:63]
	v_mov_b32_e32 v66, v55
	v_add_f32_e32 v81, 1.0, v73
	v_rcp_f32_e32 v73, v80
	v_pk_mul_f32 v[54:55], v[66:67], v[68:69]
	v_mov_b32_e32 v66, v56
	v_rcp_f32_e32 v61, v81
	v_mul_f32_e32 v56, v54, v55
	v_pk_mul_f32 v[54:55], v[66:67], v[64:65]
	v_mov_b32_e32 v66, v57
	v_rcp_f32_e32 v75, v82
	v_mul_f32_e32 v57, v54, v55
	v_pk_mul_f32 v[54:55], v[66:67], v[70:71]
	v_mov_b32_e32 v66, v50
	v_mul_f32_e32 v62, v62, v63
	v_cvt_pk_bf16_f32 v50, v62, v56
	v_mul_f32_e32 v56, v54, v55
	v_pk_mul_f32 v[54:55], v[66:67], v[58:59]
	v_mov_b32_e32 v66, v51
	v_mul_f32_e32 v58, v54, v55
	v_pk_mul_f32 v[54:55], v[66:67], v[72:73]
	v_mov_b32_e32 v66, v52
	v_mul_f32_e32 v52, v54, v55
	v_pk_mul_f32 v[54:55], v[66:67], v[60:61]
	v_mov_b32_e32 v66, v53
	v_mul_f32_e32 v53, v54, v55
	v_pk_mul_f32 v[54:55], v[66:67], v[74:75]
	v_cvt_pk_bf16_f32 v51, v57, v56
	v_cvt_pk_bf16_f32 v52, v58, v52
	v_mov_b32_e32 v58, v45
	v_mul_f32_e32 v54, v54, v55
	v_cvt_pk_bf16_f32 v53, v53, v54
	global_store_dwordx4 v[76:77], v[50:53], off
	s_nop 0
	v_mov_b32_e32 v56, v43
	v_add_u32_e32 v43, 0x90, v142
	v_mad_i64_i32 v[60:61], s[2:3], v43, s60, v[144:145]
	v_mov_b32_e32 v50, v38
	v_mov_b32_e32 v52, v47
	v_mov_b32_e32 v54, v49
	v_lshl_add_u64 v[60:61], v[60:61], 0, v[122:123]
	s_waitcnt vmcnt(2)
	v_mov_b32_e32 v51, v246
	v_fmamk_f32 v45, v51, 0x39800000, v155
	v_rsq_f32_e32 v45, v45
	s_nop 0
	v_mul_f32_e32 v43, 0xbfb8aa3b, v45
	v_mul_f32_e32 v38, v38, v43
	v_mul_f32_e32 v51, v45, v45
	v_mul_f32_e32 v45, v39, v43
	v_mul_f32_e32 v47, v40, v43
	v_exp_f32_e32 v38, v38
	v_mul_f32_e32 v53, v34, v43
	v_exp_f32_e32 v45, v45
	v_exp_f32_e32 v47, v47
	v_mul_f32_e32 v49, v41, v43
	v_exp_f32_e32 v53, v53
	v_mul_f32_e32 v55, v35, v43
	v_exp_f32_e32 v49, v49
	v_mul_f32_e32 v57, v36, v43
	v_mul_f32_e32 v43, v37, v43
	v_exp_f32_e32 v55, v55
	v_add_f32_e32 v38, 1.0, v38
	v_exp_f32_e32 v43, v43
	v_add_f32_e32 v45, 1.0, v45
	v_add_f32_e32 v59, 1.0, v47
	v_rcp_f32_e32 v47, v38
	v_exp_f32_e32 v57, v57
	v_add_f32_e32 v63, 1.0, v53
	v_rcp_f32_e32 v53, v45
	v_add_f32_e32 v62, 1.0, v49
	v_rcp_f32_e32 v49, v59
	v_add_f32_e32 v64, 1.0, v55
	v_rcp_f32_e32 v55, v62
	v_add_f32_e32 v66, 1.0, v43
	v_rcp_f32_e32 v43, v63
	v_pk_mul_f32 v[46:47], v[50:51], v[46:47]
	v_mov_b32_e32 v50, v39
	v_add_f32_e32 v65, 1.0, v57
	v_rcp_f32_e32 v57, v64
	v_pk_mul_f32 v[38:39], v[50:51], v[52:53]
	v_mov_b32_e32 v50, v40
	v_rcp_f32_e32 v45, v65
	v_mul_f32_e32 v40, v38, v39
	v_pk_mul_f32 v[38:39], v[50:51], v[48:49]
	v_mov_b32_e32 v50, v41
	v_rcp_f32_e32 v59, v66
	v_mul_f32_e32 v41, v38, v39
	v_pk_mul_f32 v[38:39], v[50:51], v[54:55]
	v_mov_b32_e32 v50, v34
	v_mul_f32_e32 v46, v46, v47
	v_cvt_pk_bf16_f32 v34, v46, v40
	v_mul_f32_e32 v40, v38, v39
	v_pk_mul_f32 v[38:39], v[50:51], v[42:43]
	v_mov_b32_e32 v50, v35
	v_mul_f32_e32 v42, v38, v39
	v_pk_mul_f32 v[38:39], v[50:51], v[56:57]
	v_mov_b32_e32 v50, v36
	v_mul_f32_e32 v36, v38, v39
	v_pk_mul_f32 v[38:39], v[50:51], v[44:45]
	v_mov_b32_e32 v50, v37
	v_mul_f32_e32 v37, v38, v39
	v_pk_mul_f32 v[38:39], v[50:51], v[58:59]
	v_cvt_pk_bf16_f32 v35, v41, v40
	v_cvt_pk_bf16_f32 v36, v42, v36
	v_mov_b32_e32 v42, v29
	v_mul_f32_e32 v38, v38, v39
	v_cvt_pk_bf16_f32 v37, v37, v38
	global_store_dwordx4 v[60:61], v[34:37], off
	s_nop 0
	v_mov_b32_e32 v40, v27
	v_add_u32_e32 v27, 0xa0, v142
	v_mad_i64_i32 v[44:45], s[2:3], v27, s60, v[144:145]
	v_mov_b32_e32 v34, v22
	v_mov_b32_e32 v36, v31
	v_mov_b32_e32 v38, v33
	v_lshl_add_u64 v[44:45], v[44:45], 0, v[122:123]
	s_waitcnt vmcnt(1)
	v_mov_b32_e32 v35, v247
	v_fmamk_f32 v29, v35, 0x39800000, v155
	v_rsq_f32_e32 v29, v29
	s_nop 0
	v_mul_f32_e32 v27, 0xbfb8aa3b, v29
	v_mul_f32_e32 v22, v22, v27
	v_mul_f32_e32 v35, v29, v29
	v_mul_f32_e32 v29, v23, v27
	v_mul_f32_e32 v31, v24, v27
	v_exp_f32_e32 v22, v22
	v_mul_f32_e32 v37, v18, v27
	v_exp_f32_e32 v29, v29
	v_exp_f32_e32 v31, v31
	v_mul_f32_e32 v33, v25, v27
	v_exp_f32_e32 v37, v37
	v_mul_f32_e32 v39, v19, v27
	v_exp_f32_e32 v33, v33
	v_mul_f32_e32 v41, v20, v27
	v_mul_f32_e32 v27, v21, v27
	v_exp_f32_e32 v39, v39
	v_add_f32_e32 v22, 1.0, v22
	v_exp_f32_e32 v27, v27
	v_add_f32_e32 v29, 1.0, v29
	v_add_f32_e32 v43, 1.0, v31
	v_rcp_f32_e32 v31, v22
	v_exp_f32_e32 v41, v41
	v_add_f32_e32 v47, 1.0, v37
	v_rcp_f32_e32 v37, v29
	v_add_f32_e32 v46, 1.0, v33
	v_rcp_f32_e32 v33, v43
	v_add_f32_e32 v48, 1.0, v39
	v_rcp_f32_e32 v39, v46
	v_add_f32_e32 v50, 1.0, v27
	v_rcp_f32_e32 v27, v47
	v_pk_mul_f32 v[30:31], v[34:35], v[30:31]
	v_mov_b32_e32 v34, v23
	v_add_f32_e32 v49, 1.0, v41
	v_rcp_f32_e32 v41, v48
	v_pk_mul_f32 v[22:23], v[34:35], v[36:37]
	v_mov_b32_e32 v34, v24
	v_rcp_f32_e32 v29, v49
	v_mul_f32_e32 v24, v22, v23
	v_pk_mul_f32 v[22:23], v[34:35], v[32:33]
	v_mov_b32_e32 v34, v25
	v_rcp_f32_e32 v43, v50
	v_mul_f32_e32 v25, v22, v23
	v_pk_mul_f32 v[22:23], v[34:35], v[38:39]
	v_mov_b32_e32 v34, v18
	v_mul_f32_e32 v30, v30, v31
	v_cvt_pk_bf16_f32 v18, v30, v24
	v_mul_f32_e32 v24, v22, v23
	v_pk_mul_f32 v[22:23], v[34:35], v[26:27]
	v_mov_b32_e32 v34, v19
	v_mul_f32_e32 v26, v22, v23
	v_pk_mul_f32 v[22:23], v[34:35], v[40:41]
	v_mov_b32_e32 v34, v20
	v_mul_f32_e32 v20, v22, v23
	v_pk_mul_f32 v[22:23], v[34:35], v[28:29]
	v_mov_b32_e32 v34, v21
	v_mul_f32_e32 v21, v22, v23
	v_pk_mul_f32 v[22:23], v[34:35], v[42:43]
	v_cvt_pk_bf16_f32 v19, v25, v24
	v_cvt_pk_bf16_f32 v20, v26, v20
	v_mov_b32_e32 v26, v13
	v_mul_f32_e32 v22, v22, v23
	v_cvt_pk_bf16_f32 v21, v21, v22
	global_store_dwordx4 v[44:45], v[18:21], off
	s_nop 0
	v_mov_b32_e32 v24, v11
	v_add_u32_e32 v11, 0xb0, v142
	v_mad_i64_i32 v[28:29], s[2:3], v11, s60, v[144:145]
	v_mov_b32_e32 v18, v6
	v_mov_b32_e32 v20, v15
	v_mov_b32_e32 v22, v17
	v_lshl_add_u64 v[28:29], v[28:29], 0, v[122:123]
	s_mov_b64 s[2:3], -1
	s_waitcnt vmcnt(0)
	v_mov_b32_e32 v19, v248
	v_fmamk_f32 v13, v19, 0x39800000, v155
	v_rsq_f32_e32 v13, v13
	s_nop 0
	v_mul_f32_e32 v11, 0xbfb8aa3b, v13
	v_mul_f32_e32 v6, v6, v11
	v_mul_f32_e32 v19, v13, v13
	v_mul_f32_e32 v13, v7, v11
	v_mul_f32_e32 v15, v8, v11
	v_exp_f32_e32 v6, v6
	v_mul_f32_e32 v21, v2, v11
	v_exp_f32_e32 v13, v13
	v_exp_f32_e32 v15, v15
	v_mul_f32_e32 v17, v9, v11
	v_exp_f32_e32 v21, v21
	v_mul_f32_e32 v23, v3, v11
	v_exp_f32_e32 v17, v17
	v_mul_f32_e32 v25, v4, v11
	v_mul_f32_e32 v11, v5, v11
	v_exp_f32_e32 v23, v23
	v_add_f32_e32 v6, 1.0, v6
	v_exp_f32_e32 v11, v11
	v_add_f32_e32 v13, 1.0, v13
	v_add_f32_e32 v27, 1.0, v15
	v_rcp_f32_e32 v15, v6
	v_exp_f32_e32 v25, v25
	v_add_f32_e32 v31, 1.0, v21
	v_rcp_f32_e32 v21, v13
	v_add_f32_e32 v30, 1.0, v17
	v_rcp_f32_e32 v17, v27
	v_add_f32_e32 v32, 1.0, v23
	v_rcp_f32_e32 v23, v30
	v_add_f32_e32 v34, 1.0, v11
	v_rcp_f32_e32 v11, v31
	v_pk_mul_f32 v[14:15], v[18:19], v[14:15]
	v_mov_b32_e32 v18, v7
	v_add_f32_e32 v33, 1.0, v25
	v_rcp_f32_e32 v25, v32
	v_pk_mul_f32 v[6:7], v[18:19], v[20:21]
	v_mov_b32_e32 v18, v8
	v_rcp_f32_e32 v13, v33
	v_mul_f32_e32 v8, v6, v7
	v_pk_mul_f32 v[6:7], v[18:19], v[16:17]
	v_mov_b32_e32 v18, v9
	v_rcp_f32_e32 v27, v34
	v_mul_f32_e32 v9, v6, v7
	v_pk_mul_f32 v[6:7], v[18:19], v[22:23]
	v_mov_b32_e32 v18, v2
	v_mul_f32_e32 v14, v14, v15
	v_cvt_pk_bf16_f32 v2, v14, v8
	v_mul_f32_e32 v8, v6, v7
	v_pk_mul_f32 v[6:7], v[18:19], v[10:11]
	v_mov_b32_e32 v18, v3
	v_mul_f32_e32 v10, v6, v7
	v_pk_mul_f32 v[6:7], v[18:19], v[24:25]
	v_mov_b32_e32 v18, v4
	v_mul_f32_e32 v4, v6, v7
	v_pk_mul_f32 v[6:7], v[18:19], v[12:13]
	v_mov_b32_e32 v18, v5
	v_mul_f32_e32 v5, v6, v7
	v_pk_mul_f32 v[6:7], v[18:19], v[26:27]
	v_cvt_pk_bf16_f32 v3, v9, v8
	v_cvt_pk_bf16_f32 v4, v10, v4
	s_nop 0
	v_mul_f32_e32 v6, v6, v7
	v_cvt_pk_bf16_f32 v5, v5, v6
	global_store_dwordx4 v[28:29], v[2:5], off
	s_cbranch_vccnz .LBB0_401
	s_andn2_b64 vcc, exec, s[0:1]
	s_cbranch_vccnz .LBB0_400
	s_barrier
	s_branch .LBB0_400

.LBB0_1336:
	v_lshl_add_u32 v142, s22, 8, v153
	v_ashrrev_i32_e32 v143, 31, v142
	v_lshl_add_u64 v[146:147], v[142:143], 2, s[4:5]
	global_load_dword v241, v[146:147], off
	global_load_dword v242, v[146:147], off offset:64
	global_load_dword v243, v[146:147], off offset:128
	global_load_dword v244, v[146:147], off offset:192
	global_load_dword v245, v[146:147], off offset:512
	global_load_dword v246, v[146:147], off offset:576
	global_load_dword v247, v[146:147], off offset:640
	global_load_dword v248, v[146:147], off offset:704
	v_mov_b32_e32 v176, v125
	v_mov_b32_e32 v168, v127
	v_mov_b32_e32 v166, v118
	v_mov_b32_e32 v170, v129
	v_lshl_or_b32 v164, s18, 7, v158
	v_mov_b64_e32 v[144:145], s[6:7]
	v_ashrrev_i32_e32 v165, 31, v164
	v_or_b32_e32 v180, 16, v142
	v_mov_b32_e32 v172, v122
	v_mov_b32_e32 v174, v123
	v_mad_i64_i32 v[178:179], s[2:3], v142, s57, v[144:145]
	v_lshlrev_b64 v[122:123], 1, v[164:165]
	v_ashrrev_i32_e32 v181, 31, v180
	v_lshl_add_u64 v[164:165], v[178:179], 0, v[122:123]
	v_lshl_add_u64 v[178:179], v[180:181], 2, s[4:5]
	s_andn2_b64 vcc, exec, s[26:27]
	s_waitcnt vmcnt(7)
	v_mov_b32_e32 v143, v241
	v_fmamk_f32 v125, v143, 0x39800000, v162
	v_rsq_f32_e32 v125, v125
	s_nop 0
	v_mul_f32_e32 v127, 0xbfb8aa3b, v125
	v_mul_f32_e32 v118, v118, v127
	v_mul_f32_e32 v167, v125, v125
	v_mul_f32_e32 v125, v119, v127
	v_mul_f32_e32 v129, v120, v127
	v_mul_f32_e32 v143, v121, v127
	v_mul_f32_e32 v163, v114, v127
	v_mul_f32_e32 v169, v115, v127
	v_mul_f32_e32 v171, v116, v127
	v_mul_f32_e32 v127, v117, v127
	v_exp_f32_e32 v118, v118
	v_exp_f32_e32 v125, v125
	v_exp_f32_e32 v127, v127
	v_exp_f32_e32 v129, v129
	v_exp_f32_e32 v169, v169
	v_exp_f32_e32 v143, v143
	v_exp_f32_e32 v163, v163
	v_exp_f32_e32 v171, v171
	v_add_f32_e32 v118, 1.0, v118
	v_add_f32_e32 v125, 1.0, v125
	v_add_f32_e32 v181, 1.0, v127
	v_rcp_f32_e32 v127, v118
	v_add_f32_e32 v129, 1.0, v129
	v_add_f32_e32 v175, 1.0, v169
	v_rcp_f32_e32 v169, v125
	v_add_f32_e32 v143, 1.0, v143
	v_rcp_f32_e32 v129, v129
	v_add_f32_e32 v163, 1.0, v163
	v_add_f32_e32 v177, 1.0, v171
	v_rcp_f32_e32 v171, v143
	v_rcp_f32_e32 v173, v163
	v_pk_mul_f32 v[126:127], v[166:167], v[126:127]
	v_mov_b32_e32 v166, v119
	v_rcp_f32_e32 v175, v175
	v_pk_mul_f32 v[118:119], v[166:167], v[168:169]
	v_mov_b32_e32 v166, v120
	v_rcp_f32_e32 v125, v177
	v_mul_f32_e32 v120, v118, v119
	v_pk_mul_f32 v[118:119], v[166:167], v[128:129]
	v_mov_b32_e32 v166, v121
	v_rcp_f32_e32 v177, v181
	v_mul_f32_e32 v121, v118, v119
	v_pk_mul_f32 v[118:119], v[166:167], v[170:171]
	v_mov_b32_e32 v166, v114
	v_mul_f32_e32 v126, v126, v127
	v_cvt_pk_bf16_f32 v114, v126, v120
	v_mul_f32_e32 v120, v118, v119
	v_pk_mul_f32 v[118:119], v[166:167], v[172:173]
	v_mov_b32_e32 v166, v115
	v_mul_f32_e32 v126, v118, v119
	v_pk_mul_f32 v[118:119], v[166:167], v[174:175]
	v_mov_b32_e32 v166, v116
	v_mul_f32_e32 v116, v118, v119
	v_pk_mul_f32 v[118:119], v[166:167], v[124:125]
	v_mov_b32_e32 v166, v117
	v_mul_f32_e32 v117, v118, v119
	v_pk_mul_f32 v[118:119], v[166:167], v[176:177]
	v_cvt_pk_bf16_f32 v115, v121, v120
	v_cvt_pk_bf16_f32 v116, v126, v116
	v_mov_b32_e32 v120, v107
	v_mul_f32_e32 v118, v118, v119
	v_cvt_pk_bf16_f32 v117, v117, v118
	global_store_dwordx4 v[164:165], v[114:117], off
	s_nop 0
	v_mov_b32_e32 v124, v109
	v_mov_b32_e32 v114, v102
	v_mov_b32_e32 v116, v111
	v_mov_b32_e32 v118, v113
	v_or_b32_e32 v126, 32, v142
	v_ashrrev_i32_e32 v127, 31, v126
	v_lshl_add_u64 v[164:165], v[126:127], 2, s[4:5]
	v_mad_i64_i32 v[128:129], s[2:3], v180, s57, v[144:145]
	v_lshl_add_u64 v[128:129], v[128:129], 0, v[122:123]
	s_waitcnt vmcnt(6)
	v_mov_b32_e32 v115, v242
	v_fmamk_f32 v107, v115, 0x39800000, v162
	v_rsq_f32_e32 v107, v107
	s_nop 0
	v_mul_f32_e32 v109, 0xbfb8aa3b, v107
	v_mul_f32_e32 v102, v102, v109
	v_mul_f32_e32 v115, v107, v107
	v_mul_f32_e32 v107, v103, v109
	v_mul_f32_e32 v111, v104, v109
	v_exp_f32_e32 v102, v102
	v_mul_f32_e32 v117, v98, v109
	v_exp_f32_e32 v107, v107
	v_exp_f32_e32 v111, v111
	v_mul_f32_e32 v113, v105, v109
	v_exp_f32_e32 v117, v117
	v_mul_f32_e32 v119, v99, v109
	v_exp_f32_e32 v113, v113
	v_exp_f32_e32 v119, v119
	v_add_f32_e32 v102, 1.0, v102
	v_mul_f32_e32 v121, v100, v109
	v_add_f32_e32 v107, 1.0, v107
	v_add_f32_e32 v125, 1.0, v111
	v_rcp_f32_e32 v111, v102
	v_mul_f32_e32 v109, v101, v109
	v_exp_f32_e32 v121, v121
	v_add_f32_e32 v143, 1.0, v117
	v_rcp_f32_e32 v117, v107
	v_exp_f32_e32 v109, v109
	v_add_f32_e32 v127, 1.0, v113
	v_rcp_f32_e32 v113, v125
	v_add_f32_e32 v163, 1.0, v119
	v_rcp_f32_e32 v119, v127
	v_rcp_f32_e32 v107, v143
	v_pk_mul_f32 v[110:111], v[114:115], v[110:111]
	v_mov_b32_e32 v114, v103
	v_add_f32_e32 v166, 1.0, v121
	v_rcp_f32_e32 v121, v163
	v_pk_mul_f32 v[102:103], v[114:115], v[116:117]
	v_mov_b32_e32 v114, v104
	v_add_f32_e32 v167, 1.0, v109
	v_rcp_f32_e32 v109, v166
	v_mul_f32_e32 v104, v102, v103
	v_pk_mul_f32 v[102:103], v[114:115], v[112:113]
	v_mov_b32_e32 v114, v105
	v_rcp_f32_e32 v125, v167
	v_mul_f32_e32 v105, v102, v103
	v_pk_mul_f32 v[102:103], v[114:115], v[118:119]
	v_mov_b32_e32 v114, v98
	v_mul_f32_e32 v110, v110, v111
	v_cvt_pk_bf16_f32 v98, v110, v104
	v_mul_f32_e32 v104, v102, v103
	v_pk_mul_f32 v[102:103], v[114:115], v[106:107]
	v_mov_b32_e32 v114, v99
	v_mul_f32_e32 v106, v102, v103
	v_pk_mul_f32 v[102:103], v[114:115], v[120:121]
	v_mov_b32_e32 v114, v100
	v_mul_f32_e32 v100, v102, v103
	v_pk_mul_f32 v[102:103], v[114:115], v[108:109]
	v_mov_b32_e32 v114, v101
	v_mul_f32_e32 v101, v102, v103
	v_pk_mul_f32 v[102:103], v[114:115], v[124:125]
	v_cvt_pk_bf16_f32 v99, v105, v104
	v_cvt_pk_bf16_f32 v100, v106, v100
	v_mov_b32_e32 v104, v91
	v_mul_f32_e32 v102, v102, v103
	v_cvt_pk_bf16_f32 v101, v101, v102
	global_store_dwordx4 v[128:129], v[98:101], off
	s_nop 0
	v_mov_b32_e32 v106, v93
	v_mov_b32_e32 v98, v86
	v_mov_b32_e32 v100, v95
	v_mov_b32_e32 v102, v97
	v_or_b32_e32 v108, 48, v142
	v_ashrrev_i32_e32 v109, 31, v108
	v_lshl_add_u64 v[112:113], v[108:109], 2, s[4:5]
	v_mad_i64_i32 v[110:111], s[2:3], v126, s57, v[144:145]
	v_lshl_add_u64 v[110:111], v[110:111], 0, v[122:123]
	s_waitcnt vmcnt(5)
	v_mov_b32_e32 v99, v243
	v_fmamk_f32 v91, v99, 0x39800000, v162
	v_rsq_f32_e32 v91, v91
	s_nop 0
	v_mul_f32_e32 v93, 0xbfb8aa3b, v91
	v_mul_f32_e32 v86, v86, v93
	v_mul_f32_e32 v99, v91, v91
	v_mul_f32_e32 v91, v87, v93
	v_mul_f32_e32 v95, v88, v93
	v_exp_f32_e32 v86, v86
	v_mul_f32_e32 v101, v82, v93
	v_exp_f32_e32 v91, v91
	v_exp_f32_e32 v95, v95
	v_mul_f32_e32 v97, v89, v93
	v_exp_f32_e32 v101, v101
	v_mul_f32_e32 v103, v83, v93
	v_exp_f32_e32 v97, v97
	v_exp_f32_e32 v103, v103
	v_add_f32_e32 v86, 1.0, v86
	v_mul_f32_e32 v105, v84, v93
	v_add_f32_e32 v91, 1.0, v91
	v_add_f32_e32 v107, 1.0, v95
	v_rcp_f32_e32 v95, v86
	v_mul_f32_e32 v93, v85, v93
	v_exp_f32_e32 v105, v105
	v_add_f32_e32 v114, 1.0, v101
	v_rcp_f32_e32 v101, v91
	v_exp_f32_e32 v93, v93
	v_add_f32_e32 v109, 1.0, v97
	v_rcp_f32_e32 v97, v107
	v_add_f32_e32 v115, 1.0, v103
	v_rcp_f32_e32 v103, v109
	v_rcp_f32_e32 v91, v114
	v_pk_mul_f32 v[94:95], v[98:99], v[94:95]
	v_mov_b32_e32 v98, v87
	v_add_f32_e32 v116, 1.0, v105
	v_rcp_f32_e32 v105, v115
	v_pk_mul_f32 v[86:87], v[98:99], v[100:101]
	v_mov_b32_e32 v98, v88
	v_add_f32_e32 v117, 1.0, v93
	v_rcp_f32_e32 v93, v116
	v_mul_f32_e32 v88, v86, v87
	v_pk_mul_f32 v[86:87], v[98:99], v[96:97]
	v_mov_b32_e32 v98, v89
	v_rcp_f32_e32 v107, v117
	v_mul_f32_e32 v89, v86, v87
	v_pk_mul_f32 v[86:87], v[98:99], v[102:103]
	v_mov_b32_e32 v98, v82
	v_mul_f32_e32 v94, v94, v95
	v_cvt_pk_bf16_f32 v82, v94, v88
	v_mul_f32_e32 v88, v86, v87
	v_pk_mul_f32 v[86:87], v[98:99], v[90:91]
	v_mov_b32_e32 v98, v83
	v_mul_f32_e32 v90, v86, v87
	v_pk_mul_f32 v[86:87], v[98:99], v[104:105]
	v_mov_b32_e32 v98, v84
	v_mul_f32_e32 v84, v86, v87
	v_pk_mul_f32 v[86:87], v[98:99], v[92:93]
	v_mov_b32_e32 v98, v85
	v_mul_f32_e32 v85, v86, v87
	v_pk_mul_f32 v[86:87], v[98:99], v[106:107]
	v_cvt_pk_bf16_f32 v83, v89, v88
	v_cvt_pk_bf16_f32 v84, v90, v84
	v_mov_b32_e32 v88, v75
	v_mul_f32_e32 v86, v86, v87
	v_cvt_pk_bf16_f32 v85, v85, v86
	global_store_dwordx4 v[110:111], v[82:85], off
	s_nop 0
	v_mov_b32_e32 v90, v77
	v_mov_b32_e32 v82, v70
	v_mov_b32_e32 v84, v79
	v_mov_b32_e32 v86, v81
	v_mad_i64_i32 v[92:93], s[2:3], v108, s57, v[144:145]
	v_lshl_add_u64 v[92:93], v[92:93], 0, v[122:123]
	s_waitcnt vmcnt(4)
	v_mov_b32_e32 v83, v244
	v_fmamk_f32 v75, v83, 0x39800000, v162
	v_rsq_f32_e32 v75, v75
	s_nop 0
	v_mul_f32_e32 v77, 0xbfb8aa3b, v75
	v_mul_f32_e32 v70, v70, v77
	v_mul_f32_e32 v83, v75, v75
	v_mul_f32_e32 v75, v71, v77
	v_mul_f32_e32 v79, v72, v77
	v_exp_f32_e32 v70, v70
	v_mul_f32_e32 v85, v66, v77
	v_exp_f32_e32 v75, v75
	v_exp_f32_e32 v79, v79
	v_mul_f32_e32 v81, v73, v77
	v_exp_f32_e32 v85, v85
	v_mul_f32_e32 v87, v67, v77
	v_exp_f32_e32 v81, v81
	v_exp_f32_e32 v87, v87
	v_add_f32_e32 v70, 1.0, v70
	v_mul_f32_e32 v89, v68, v77
	v_add_f32_e32 v75, 1.0, v75
	v_add_f32_e32 v91, 1.0, v79
	v_rcp_f32_e32 v79, v70
	v_mul_f32_e32 v77, v69, v77
	v_exp_f32_e32 v89, v89
	v_add_f32_e32 v95, 1.0, v85
	v_rcp_f32_e32 v85, v75
	v_exp_f32_e32 v77, v77
	v_add_f32_e32 v94, 1.0, v81
	v_rcp_f32_e32 v81, v91
	v_add_f32_e32 v96, 1.0, v87
	v_rcp_f32_e32 v87, v94
	v_rcp_f32_e32 v75, v95
	v_pk_mul_f32 v[78:79], v[82:83], v[78:79]
	v_mov_b32_e32 v82, v71
	v_add_f32_e32 v97, 1.0, v89
	v_rcp_f32_e32 v89, v96
	v_pk_mul_f32 v[70:71], v[82:83], v[84:85]
	v_mov_b32_e32 v82, v72
	v_add_f32_e32 v98, 1.0, v77
	v_rcp_f32_e32 v77, v97
	v_mul_f32_e32 v72, v70, v71
	v_pk_mul_f32 v[70:71], v[82:83], v[80:81]
	v_mov_b32_e32 v82, v73
	v_rcp_f32_e32 v91, v98
	v_mul_f32_e32 v73, v70, v71
	v_pk_mul_f32 v[70:71], v[82:83], v[86:87]
	v_mov_b32_e32 v82, v66
	v_mul_f32_e32 v78, v78, v79
	v_cvt_pk_bf16_f32 v66, v78, v72
	v_mul_f32_e32 v72, v70, v71
	v_pk_mul_f32 v[70:71], v[82:83], v[74:75]
	v_mov_b32_e32 v82, v67
	v_mul_f32_e32 v74, v70, v71
	v_pk_mul_f32 v[70:71], v[82:83], v[88:89]
	v_mov_b32_e32 v82, v68
	v_mul_f32_e32 v68, v70, v71
	v_pk_mul_f32 v[70:71], v[82:83], v[76:77]
	v_mov_b32_e32 v82, v69
	v_mul_f32_e32 v69, v70, v71
	v_pk_mul_f32 v[70:71], v[82:83], v[90:91]
	v_cvt_pk_bf16_f32 v67, v73, v72
	v_cvt_pk_bf16_f32 v68, v74, v68
	v_mov_b32_e32 v74, v61
	v_mul_f32_e32 v70, v70, v71
	v_cvt_pk_bf16_f32 v69, v69, v70
	global_store_dwordx4 v[92:93], v[66:69], off
	s_nop 0
	v_mov_b32_e32 v72, v59
	v_add_u32_e32 v59, 0x80, v142
	v_mad_i64_i32 v[76:77], s[2:3], v59, s57, v[144:145]
	v_mov_b32_e32 v66, v54
	v_mov_b32_e32 v68, v63
	v_mov_b32_e32 v70, v65
	v_lshl_add_u64 v[76:77], v[76:77], 0, v[122:123]
	s_waitcnt vmcnt(3)
	v_mov_b32_e32 v67, v245
	v_fmamk_f32 v61, v67, 0x39800000, v162
	v_rsq_f32_e32 v61, v61
	s_nop 0
	v_mul_f32_e32 v59, 0xbfb8aa3b, v61
	v_mul_f32_e32 v54, v54, v59
	v_mul_f32_e32 v67, v61, v61
	v_mul_f32_e32 v61, v55, v59
	v_mul_f32_e32 v63, v56, v59
	v_exp_f32_e32 v54, v54
	v_mul_f32_e32 v69, v50, v59
	v_exp_f32_e32 v61, v61
	v_exp_f32_e32 v63, v63
	v_mul_f32_e32 v65, v57, v59
	v_exp_f32_e32 v69, v69
	v_mul_f32_e32 v71, v51, v59
	v_exp_f32_e32 v65, v65
	v_mul_f32_e32 v73, v52, v59
	v_mul_f32_e32 v59, v53, v59
	v_exp_f32_e32 v71, v71
	v_add_f32_e32 v54, 1.0, v54
	v_exp_f32_e32 v59, v59
	v_add_f32_e32 v61, 1.0, v61
	v_add_f32_e32 v75, 1.0, v63
	v_rcp_f32_e32 v63, v54
	v_exp_f32_e32 v73, v73
	v_add_f32_e32 v79, 1.0, v69
	v_rcp_f32_e32 v69, v61
	v_add_f32_e32 v78, 1.0, v65
	v_rcp_f32_e32 v65, v75
	v_add_f32_e32 v80, 1.0, v71
	v_rcp_f32_e32 v71, v78
	v_add_f32_e32 v82, 1.0, v59
	v_rcp_f32_e32 v59, v79
	v_pk_mul_f32 v[62:63], v[66:67], v[62:63]
	v_mov_b32_e32 v66, v55
	v_add_f32_e32 v81, 1.0, v73
	v_rcp_f32_e32 v73, v80
	v_pk_mul_f32 v[54:55], v[66:67], v[68:69]
	v_mov_b32_e32 v66, v56
	v_rcp_f32_e32 v61, v81
	v_mul_f32_e32 v56, v54, v55
	v_pk_mul_f32 v[54:55], v[66:67], v[64:65]
	v_mov_b32_e32 v66, v57
	v_rcp_f32_e32 v75, v82
	v_mul_f32_e32 v57, v54, v55
	v_pk_mul_f32 v[54:55], v[66:67], v[70:71]
	v_mov_b32_e32 v66, v50
	v_mul_f32_e32 v62, v62, v63
	v_cvt_pk_bf16_f32 v50, v62, v56
	v_mul_f32_e32 v56, v54, v55
	v_pk_mul_f32 v[54:55], v[66:67], v[58:59]
	v_mov_b32_e32 v66, v51
	v_mul_f32_e32 v58, v54, v55
	v_pk_mul_f32 v[54:55], v[66:67], v[72:73]
	v_mov_b32_e32 v66, v52
	v_mul_f32_e32 v52, v54, v55
	v_pk_mul_f32 v[54:55], v[66:67], v[60:61]
	v_mov_b32_e32 v66, v53
	v_mul_f32_e32 v53, v54, v55
	v_pk_mul_f32 v[54:55], v[66:67], v[74:75]
	v_cvt_pk_bf16_f32 v51, v57, v56
	v_cvt_pk_bf16_f32 v52, v58, v52
	v_mov_b32_e32 v58, v45
	v_mul_f32_e32 v54, v54, v55
	v_cvt_pk_bf16_f32 v53, v53, v54
	global_store_dwordx4 v[76:77], v[50:53], off
	s_nop 0
	v_mov_b32_e32 v56, v43
	v_add_u32_e32 v43, 0x90, v142
	v_mad_i64_i32 v[60:61], s[2:3], v43, s57, v[144:145]
	v_mov_b32_e32 v50, v38
	v_mov_b32_e32 v52, v47
	v_mov_b32_e32 v54, v49
	v_lshl_add_u64 v[60:61], v[60:61], 0, v[122:123]
	s_waitcnt vmcnt(2)
	v_mov_b32_e32 v51, v246
	v_fmamk_f32 v45, v51, 0x39800000, v162
	v_rsq_f32_e32 v45, v45
	s_nop 0
	v_mul_f32_e32 v43, 0xbfb8aa3b, v45
	v_mul_f32_e32 v38, v38, v43
	v_mul_f32_e32 v51, v45, v45
	v_mul_f32_e32 v45, v39, v43
	v_mul_f32_e32 v47, v40, v43
	v_exp_f32_e32 v38, v38
	v_mul_f32_e32 v53, v34, v43
	v_exp_f32_e32 v45, v45
	v_exp_f32_e32 v47, v47
	v_mul_f32_e32 v49, v41, v43
	v_exp_f32_e32 v53, v53
	v_mul_f32_e32 v55, v35, v43
	v_exp_f32_e32 v49, v49
	v_mul_f32_e32 v57, v36, v43
	v_mul_f32_e32 v43, v37, v43
	v_exp_f32_e32 v55, v55
	v_add_f32_e32 v38, 1.0, v38
	v_exp_f32_e32 v43, v43
	v_add_f32_e32 v45, 1.0, v45
	v_add_f32_e32 v59, 1.0, v47
	v_rcp_f32_e32 v47, v38
	v_exp_f32_e32 v57, v57
	v_add_f32_e32 v63, 1.0, v53
	v_rcp_f32_e32 v53, v45
	v_add_f32_e32 v62, 1.0, v49
	v_rcp_f32_e32 v49, v59
	v_add_f32_e32 v64, 1.0, v55
	v_rcp_f32_e32 v55, v62
	v_add_f32_e32 v66, 1.0, v43
	v_rcp_f32_e32 v43, v63
	v_pk_mul_f32 v[46:47], v[50:51], v[46:47]
	v_mov_b32_e32 v50, v39
	v_add_f32_e32 v65, 1.0, v57
	v_rcp_f32_e32 v57, v64
	v_pk_mul_f32 v[38:39], v[50:51], v[52:53]
	v_mov_b32_e32 v50, v40
	v_rcp_f32_e32 v45, v65
	v_mul_f32_e32 v40, v38, v39
	v_pk_mul_f32 v[38:39], v[50:51], v[48:49]
	v_mov_b32_e32 v50, v41
	v_rcp_f32_e32 v59, v66
	v_mul_f32_e32 v41, v38, v39
	v_pk_mul_f32 v[38:39], v[50:51], v[54:55]
	v_mov_b32_e32 v50, v34
	v_mul_f32_e32 v46, v46, v47
	v_cvt_pk_bf16_f32 v34, v46, v40
	v_mul_f32_e32 v40, v38, v39
	v_pk_mul_f32 v[38:39], v[50:51], v[42:43]
	v_mov_b32_e32 v50, v35
	v_mul_f32_e32 v42, v38, v39
	v_pk_mul_f32 v[38:39], v[50:51], v[56:57]
	v_mov_b32_e32 v50, v36
	v_mul_f32_e32 v36, v38, v39
	v_pk_mul_f32 v[38:39], v[50:51], v[44:45]
	v_mov_b32_e32 v50, v37
	v_mul_f32_e32 v37, v38, v39
	v_pk_mul_f32 v[38:39], v[50:51], v[58:59]
	v_cvt_pk_bf16_f32 v35, v41, v40
	v_cvt_pk_bf16_f32 v36, v42, v36
	v_mov_b32_e32 v42, v29
	v_mul_f32_e32 v38, v38, v39
	v_cvt_pk_bf16_f32 v37, v37, v38
	global_store_dwordx4 v[60:61], v[34:37], off
	s_nop 0
	v_mov_b32_e32 v40, v27
	v_add_u32_e32 v27, 0xa0, v142
	v_mad_i64_i32 v[44:45], s[2:3], v27, s57, v[144:145]
	v_mov_b32_e32 v34, v22
	v_mov_b32_e32 v36, v31
	v_mov_b32_e32 v38, v33
	v_lshl_add_u64 v[44:45], v[44:45], 0, v[122:123]
	s_waitcnt vmcnt(1)
	v_mov_b32_e32 v35, v247
	v_fmamk_f32 v29, v35, 0x39800000, v162
	v_rsq_f32_e32 v29, v29
	s_nop 0
	v_mul_f32_e32 v27, 0xbfb8aa3b, v29
	v_mul_f32_e32 v22, v22, v27
	v_mul_f32_e32 v35, v29, v29
	v_mul_f32_e32 v29, v23, v27
	v_mul_f32_e32 v31, v24, v27
	v_exp_f32_e32 v22, v22
	v_mul_f32_e32 v37, v18, v27
	v_exp_f32_e32 v29, v29
	v_exp_f32_e32 v31, v31
	v_mul_f32_e32 v33, v25, v27
	v_exp_f32_e32 v37, v37
	v_mul_f32_e32 v39, v19, v27
	v_exp_f32_e32 v33, v33
	v_mul_f32_e32 v41, v20, v27
	v_mul_f32_e32 v27, v21, v27
	v_exp_f32_e32 v39, v39
	v_add_f32_e32 v22, 1.0, v22
	v_exp_f32_e32 v27, v27
	v_add_f32_e32 v29, 1.0, v29
	v_add_f32_e32 v43, 1.0, v31
	v_rcp_f32_e32 v31, v22
	v_exp_f32_e32 v41, v41
	v_add_f32_e32 v47, 1.0, v37
	v_rcp_f32_e32 v37, v29
	v_add_f32_e32 v46, 1.0, v33
	v_rcp_f32_e32 v33, v43
	v_add_f32_e32 v48, 1.0, v39
	v_rcp_f32_e32 v39, v46
	v_add_f32_e32 v50, 1.0, v27
	v_rcp_f32_e32 v27, v47
	v_pk_mul_f32 v[30:31], v[34:35], v[30:31]
	v_mov_b32_e32 v34, v23
	v_add_f32_e32 v49, 1.0, v41
	v_rcp_f32_e32 v41, v48
	v_pk_mul_f32 v[22:23], v[34:35], v[36:37]
	v_mov_b32_e32 v34, v24
	v_rcp_f32_e32 v29, v49
	v_mul_f32_e32 v24, v22, v23
	v_pk_mul_f32 v[22:23], v[34:35], v[32:33]
	v_mov_b32_e32 v34, v25
	v_rcp_f32_e32 v43, v50
	v_mul_f32_e32 v25, v22, v23
	v_pk_mul_f32 v[22:23], v[34:35], v[38:39]
	v_mov_b32_e32 v34, v18
	v_mul_f32_e32 v30, v30, v31
	v_cvt_pk_bf16_f32 v18, v30, v24
	v_mul_f32_e32 v24, v22, v23
	v_pk_mul_f32 v[22:23], v[34:35], v[26:27]
	v_mov_b32_e32 v34, v19
	v_mul_f32_e32 v26, v22, v23
	v_pk_mul_f32 v[22:23], v[34:35], v[40:41]
	v_mov_b32_e32 v34, v20
	v_mul_f32_e32 v20, v22, v23
	v_pk_mul_f32 v[22:23], v[34:35], v[28:29]
	v_mov_b32_e32 v34, v21
	v_mul_f32_e32 v21, v22, v23
	v_pk_mul_f32 v[22:23], v[34:35], v[42:43]
	v_cvt_pk_bf16_f32 v19, v25, v24
	v_cvt_pk_bf16_f32 v20, v26, v20
	v_mov_b32_e32 v26, v13
	v_mul_f32_e32 v22, v22, v23
	v_cvt_pk_bf16_f32 v21, v21, v22
	global_store_dwordx4 v[44:45], v[18:21], off
	s_nop 0
	v_mov_b32_e32 v24, v11
	v_add_u32_e32 v11, 0xb0, v142
	v_mad_i64_i32 v[28:29], s[2:3], v11, s57, v[144:145]
	v_mov_b32_e32 v18, v6
	v_mov_b32_e32 v20, v15
	v_mov_b32_e32 v22, v17
	v_lshl_add_u64 v[28:29], v[28:29], 0, v[122:123]
	s_mov_b64 s[2:3], -1
	s_waitcnt vmcnt(0)
	v_mov_b32_e32 v19, v248
	v_fmamk_f32 v13, v19, 0x39800000, v162
	v_rsq_f32_e32 v13, v13
	s_nop 0
	v_mul_f32_e32 v11, 0xbfb8aa3b, v13
	v_mul_f32_e32 v6, v6, v11
	v_mul_f32_e32 v19, v13, v13
	v_mul_f32_e32 v13, v7, v11
	v_mul_f32_e32 v15, v8, v11
	v_exp_f32_e32 v6, v6
	v_mul_f32_e32 v21, v2, v11
	v_exp_f32_e32 v13, v13
	v_exp_f32_e32 v15, v15
	v_mul_f32_e32 v17, v9, v11
	v_exp_f32_e32 v21, v21
	v_mul_f32_e32 v23, v3, v11
	v_exp_f32_e32 v17, v17
	v_mul_f32_e32 v25, v4, v11
	v_mul_f32_e32 v11, v5, v11
	v_exp_f32_e32 v23, v23
	v_add_f32_e32 v6, 1.0, v6
	v_exp_f32_e32 v11, v11
	v_add_f32_e32 v13, 1.0, v13
	v_add_f32_e32 v27, 1.0, v15
	v_rcp_f32_e32 v15, v6
	v_exp_f32_e32 v25, v25
	v_add_f32_e32 v31, 1.0, v21
	v_rcp_f32_e32 v21, v13
	v_add_f32_e32 v30, 1.0, v17
	v_rcp_f32_e32 v17, v27
	v_add_f32_e32 v32, 1.0, v23
	v_rcp_f32_e32 v23, v30
	v_add_f32_e32 v34, 1.0, v11
	v_rcp_f32_e32 v11, v31
	v_pk_mul_f32 v[14:15], v[18:19], v[14:15]
	v_mov_b32_e32 v18, v7
	v_add_f32_e32 v33, 1.0, v25
	v_rcp_f32_e32 v25, v32
	v_pk_mul_f32 v[6:7], v[18:19], v[20:21]
	v_mov_b32_e32 v18, v8
	v_rcp_f32_e32 v13, v33
	v_mul_f32_e32 v8, v6, v7
	v_pk_mul_f32 v[6:7], v[18:19], v[16:17]
	v_mov_b32_e32 v18, v9
	v_rcp_f32_e32 v27, v34
	v_mul_f32_e32 v9, v6, v7
	v_pk_mul_f32 v[6:7], v[18:19], v[22:23]
	v_mov_b32_e32 v18, v2
	v_mul_f32_e32 v14, v14, v15
	v_cvt_pk_bf16_f32 v2, v14, v8
	v_mul_f32_e32 v8, v6, v7
	v_pk_mul_f32 v[6:7], v[18:19], v[10:11]
	v_mov_b32_e32 v18, v3
	v_mul_f32_e32 v10, v6, v7
	v_pk_mul_f32 v[6:7], v[18:19], v[24:25]
	v_mov_b32_e32 v18, v4
	v_mul_f32_e32 v4, v6, v7
	v_pk_mul_f32 v[6:7], v[18:19], v[12:13]
	v_mov_b32_e32 v18, v5
	v_mul_f32_e32 v5, v6, v7
	v_pk_mul_f32 v[6:7], v[18:19], v[26:27]
	v_cvt_pk_bf16_f32 v3, v9, v8
	v_cvt_pk_bf16_f32 v4, v10, v4
	s_nop 0
	v_mul_f32_e32 v6, v6, v7
	v_cvt_pk_bf16_f32 v5, v5, v6
	global_store_dwordx4 v[28:29], v[2:5], off
	s_cbranch_vccnz .LBB0_1258
	s_andn2_b64 vcc, exec, s[0:1]
	s_cbranch_vccnz .LBB0_1257
	s_barrier
	s_branch .LBB0_1257

.LBB0_1542:
	v_lshl_add_u32 v142, s18, 8, v153
	v_ashrrev_i32_e32 v143, 31, v142
	v_lshl_add_u64 v[146:147], v[142:143], 2, s[4:5]
	global_load_dword v241, v[146:147], off
	global_load_dword v242, v[146:147], off offset:64
	global_load_dword v243, v[146:147], off offset:128
	global_load_dword v244, v[146:147], off offset:192
	global_load_dword v245, v[146:147], off offset:512
	global_load_dword v246, v[146:147], off offset:576
	global_load_dword v247, v[146:147], off offset:640
	global_load_dword v248, v[146:147], off offset:704
	v_mov_b32_e32 v174, v125
	v_mov_b32_e32 v166, v127
	v_mov_b32_e32 v164, v118
	v_mov_b32_e32 v168, v129
	v_lshl_or_b32 v162, s16, 7, v158
	v_mov_b64_e32 v[144:145], s[6:7]
	v_ashrrev_i32_e32 v163, 31, v162
	v_or_b32_e32 v178, 16, v142
	v_mov_b32_e32 v170, v122
	v_mov_b32_e32 v172, v123
	v_mad_i64_i32 v[176:177], s[2:3], v142, s50, v[144:145]
	v_lshlrev_b64 v[122:123], 1, v[162:163]
	v_ashrrev_i32_e32 v179, 31, v178
	v_lshl_add_u64 v[162:163], v[176:177], 0, v[122:123]
	v_lshl_add_u64 v[176:177], v[178:179], 2, s[4:5]
	s_andn2_b64 vcc, exec, s[20:21]
	s_waitcnt vmcnt(7)
	v_mov_b32_e32 v143, v241
	v_fmamk_f32 v125, v143, 0x39800000, v161
	v_rsq_f32_e32 v125, v125
	s_nop 0
	v_mul_f32_e32 v127, 0xbfb8aa3b, v125
	v_mul_f32_e32 v118, v118, v127
	v_mul_f32_e32 v165, v125, v125
	v_mul_f32_e32 v125, v119, v127
	v_mul_f32_e32 v129, v120, v127
	v_mul_f32_e32 v143, v121, v127
	v_mul_f32_e32 v167, v114, v127
	v_mul_f32_e32 v169, v115, v127
	v_mul_f32_e32 v171, v116, v127
	v_mul_f32_e32 v127, v117, v127
	v_exp_f32_e32 v118, v118
	v_exp_f32_e32 v125, v125
	v_exp_f32_e32 v127, v127
	v_exp_f32_e32 v129, v129
	v_exp_f32_e32 v167, v167
	v_exp_f32_e32 v143, v143
	v_exp_f32_e32 v169, v169
	v_add_f32_e32 v118, 1.0, v118
	v_exp_f32_e32 v171, v171
	v_add_f32_e32 v125, 1.0, v125
	v_add_f32_e32 v180, 1.0, v127
	v_rcp_f32_e32 v127, v118
	v_add_f32_e32 v129, 1.0, v129
	v_add_f32_e32 v173, 1.0, v167
	v_rcp_f32_e32 v167, v125
	v_add_f32_e32 v143, 1.0, v143
	v_rcp_f32_e32 v129, v129
	v_add_f32_e32 v175, 1.0, v169
	v_rcp_f32_e32 v169, v143
	v_add_f32_e32 v179, 1.0, v171
	v_rcp_f32_e32 v171, v173
	v_pk_mul_f32 v[126:127], v[164:165], v[126:127]
	v_mov_b32_e32 v164, v119
	v_rcp_f32_e32 v173, v175
	v_pk_mul_f32 v[118:119], v[164:165], v[166:167]
	v_mov_b32_e32 v164, v120
	v_rcp_f32_e32 v125, v179
	v_mul_f32_e32 v120, v118, v119
	v_pk_mul_f32 v[118:119], v[164:165], v[128:129]
	v_mov_b32_e32 v164, v121
	v_rcp_f32_e32 v175, v180
	v_mul_f32_e32 v121, v118, v119
	v_pk_mul_f32 v[118:119], v[164:165], v[168:169]
	v_mov_b32_e32 v164, v114
	v_mul_f32_e32 v126, v126, v127
	v_cvt_pk_bf16_f32 v114, v126, v120
	v_mul_f32_e32 v120, v118, v119
	v_pk_mul_f32 v[118:119], v[164:165], v[170:171]
	v_mov_b32_e32 v164, v115
	v_mul_f32_e32 v126, v118, v119
	v_pk_mul_f32 v[118:119], v[164:165], v[172:173]
	v_mov_b32_e32 v164, v116
	v_mul_f32_e32 v116, v118, v119
	v_pk_mul_f32 v[118:119], v[164:165], v[124:125]
	v_mov_b32_e32 v164, v117
	v_mul_f32_e32 v117, v118, v119
	v_pk_mul_f32 v[118:119], v[164:165], v[174:175]
	v_cvt_pk_bf16_f32 v115, v121, v120
	v_cvt_pk_bf16_f32 v116, v126, v116
	v_mov_b32_e32 v120, v107
	v_mul_f32_e32 v118, v118, v119
	v_cvt_pk_bf16_f32 v117, v117, v118
	global_store_dwordx4 v[162:163], v[114:117], off
	s_nop 0
	v_mov_b32_e32 v124, v109
	v_mov_b32_e32 v114, v102
	v_mov_b32_e32 v116, v111
	v_mov_b32_e32 v118, v113
	v_or_b32_e32 v126, 32, v142
	v_ashrrev_i32_e32 v127, 31, v126
	v_lshl_add_u64 v[162:163], v[126:127], 2, s[4:5]
	v_mad_i64_i32 v[128:129], s[2:3], v178, s50, v[144:145]
	v_lshl_add_u64 v[128:129], v[128:129], 0, v[122:123]
	s_waitcnt vmcnt(6)
	v_mov_b32_e32 v115, v242
	v_fmamk_f32 v107, v115, 0x39800000, v161
	v_rsq_f32_e32 v107, v107
	s_nop 0
	v_mul_f32_e32 v109, 0xbfb8aa3b, v107
	v_mul_f32_e32 v102, v102, v109
	v_mul_f32_e32 v115, v107, v107
	v_mul_f32_e32 v107, v103, v109
	v_mul_f32_e32 v111, v104, v109
	v_exp_f32_e32 v102, v102
	v_mul_f32_e32 v117, v98, v109
	v_exp_f32_e32 v107, v107
	v_exp_f32_e32 v111, v111
	v_mul_f32_e32 v113, v105, v109
	v_exp_f32_e32 v117, v117
	v_mul_f32_e32 v119, v99, v109
	v_exp_f32_e32 v113, v113
	v_exp_f32_e32 v119, v119
	v_add_f32_e32 v102, 1.0, v102
	v_mul_f32_e32 v121, v100, v109
	v_add_f32_e32 v107, 1.0, v107
	v_add_f32_e32 v125, 1.0, v111
	v_rcp_f32_e32 v111, v102
	v_mul_f32_e32 v109, v101, v109
	v_exp_f32_e32 v121, v121
	v_add_f32_e32 v143, 1.0, v117
	v_rcp_f32_e32 v117, v107
	v_exp_f32_e32 v109, v109
	v_add_f32_e32 v127, 1.0, v113
	v_rcp_f32_e32 v113, v125
	v_add_f32_e32 v164, 1.0, v119
	v_rcp_f32_e32 v119, v127
	v_rcp_f32_e32 v107, v143
	v_pk_mul_f32 v[110:111], v[114:115], v[110:111]
	v_mov_b32_e32 v114, v103
	v_add_f32_e32 v165, 1.0, v121
	v_rcp_f32_e32 v121, v164
	v_pk_mul_f32 v[102:103], v[114:115], v[116:117]
	v_mov_b32_e32 v114, v104
	v_add_f32_e32 v166, 1.0, v109
	v_rcp_f32_e32 v109, v165
	v_mul_f32_e32 v104, v102, v103
	v_pk_mul_f32 v[102:103], v[114:115], v[112:113]
	v_mov_b32_e32 v114, v105
	v_rcp_f32_e32 v125, v166
	v_mul_f32_e32 v105, v102, v103
	v_pk_mul_f32 v[102:103], v[114:115], v[118:119]
	v_mov_b32_e32 v114, v98
	v_mul_f32_e32 v110, v110, v111
	v_cvt_pk_bf16_f32 v98, v110, v104
	v_mul_f32_e32 v104, v102, v103
	v_pk_mul_f32 v[102:103], v[114:115], v[106:107]
	v_mov_b32_e32 v114, v99
	v_mul_f32_e32 v106, v102, v103
	v_pk_mul_f32 v[102:103], v[114:115], v[120:121]
	v_mov_b32_e32 v114, v100
	v_mul_f32_e32 v100, v102, v103
	v_pk_mul_f32 v[102:103], v[114:115], v[108:109]
	v_mov_b32_e32 v114, v101
	v_mul_f32_e32 v101, v102, v103
	v_pk_mul_f32 v[102:103], v[114:115], v[124:125]
	v_cvt_pk_bf16_f32 v99, v105, v104
	v_cvt_pk_bf16_f32 v100, v106, v100
	v_mov_b32_e32 v104, v91
	v_mul_f32_e32 v102, v102, v103
	v_cvt_pk_bf16_f32 v101, v101, v102
	global_store_dwordx4 v[128:129], v[98:101], off
	s_nop 0
	v_mov_b32_e32 v106, v93
	v_mov_b32_e32 v98, v86
	v_mov_b32_e32 v100, v95
	v_mov_b32_e32 v102, v97
	v_or_b32_e32 v108, 48, v142
	v_ashrrev_i32_e32 v109, 31, v108
	v_lshl_add_u64 v[112:113], v[108:109], 2, s[4:5]
	v_mad_i64_i32 v[110:111], s[2:3], v126, s50, v[144:145]
	v_lshl_add_u64 v[110:111], v[110:111], 0, v[122:123]
	s_waitcnt vmcnt(5)
	v_mov_b32_e32 v99, v243
	v_fmamk_f32 v91, v99, 0x39800000, v161
	v_rsq_f32_e32 v91, v91
	s_nop 0
	v_mul_f32_e32 v93, 0xbfb8aa3b, v91
	v_mul_f32_e32 v86, v86, v93
	v_mul_f32_e32 v99, v91, v91
	v_mul_f32_e32 v91, v87, v93
	v_mul_f32_e32 v95, v88, v93
	v_exp_f32_e32 v86, v86
	v_mul_f32_e32 v101, v82, v93
	v_exp_f32_e32 v91, v91
	v_exp_f32_e32 v95, v95
	v_mul_f32_e32 v97, v89, v93
	v_exp_f32_e32 v101, v101
	v_mul_f32_e32 v103, v83, v93
	v_exp_f32_e32 v97, v97
	v_exp_f32_e32 v103, v103
	v_add_f32_e32 v86, 1.0, v86
	v_mul_f32_e32 v105, v84, v93
	v_add_f32_e32 v91, 1.0, v91
	v_add_f32_e32 v107, 1.0, v95
	v_rcp_f32_e32 v95, v86
	v_mul_f32_e32 v93, v85, v93
	v_exp_f32_e32 v105, v105
	v_add_f32_e32 v114, 1.0, v101
	v_rcp_f32_e32 v101, v91
	v_exp_f32_e32 v93, v93
	v_add_f32_e32 v109, 1.0, v97
	v_rcp_f32_e32 v97, v107
	v_add_f32_e32 v115, 1.0, v103
	v_rcp_f32_e32 v103, v109
	v_rcp_f32_e32 v91, v114
	v_pk_mul_f32 v[94:95], v[98:99], v[94:95]
	v_mov_b32_e32 v98, v87
	v_add_f32_e32 v116, 1.0, v105
	v_rcp_f32_e32 v105, v115
	v_pk_mul_f32 v[86:87], v[98:99], v[100:101]
	v_mov_b32_e32 v98, v88
	v_add_f32_e32 v117, 1.0, v93
	v_rcp_f32_e32 v93, v116
	v_mul_f32_e32 v88, v86, v87
	v_pk_mul_f32 v[86:87], v[98:99], v[96:97]
	v_mov_b32_e32 v98, v89
	v_rcp_f32_e32 v107, v117
	v_mul_f32_e32 v89, v86, v87
	v_pk_mul_f32 v[86:87], v[98:99], v[102:103]
	v_mov_b32_e32 v98, v82
	v_mul_f32_e32 v94, v94, v95
	v_cvt_pk_bf16_f32 v82, v94, v88
	v_mul_f32_e32 v88, v86, v87
	v_pk_mul_f32 v[86:87], v[98:99], v[90:91]
	v_mov_b32_e32 v98, v83
	v_mul_f32_e32 v90, v86, v87
	v_pk_mul_f32 v[86:87], v[98:99], v[104:105]
	v_mov_b32_e32 v98, v84
	v_mul_f32_e32 v84, v86, v87
	v_pk_mul_f32 v[86:87], v[98:99], v[92:93]
	v_mov_b32_e32 v98, v85
	v_mul_f32_e32 v85, v86, v87
	v_pk_mul_f32 v[86:87], v[98:99], v[106:107]
	v_cvt_pk_bf16_f32 v83, v89, v88
	v_cvt_pk_bf16_f32 v84, v90, v84
	v_mov_b32_e32 v88, v75
	v_mul_f32_e32 v86, v86, v87
	v_cvt_pk_bf16_f32 v85, v85, v86
	global_store_dwordx4 v[110:111], v[82:85], off
	s_nop 0
	v_mov_b32_e32 v90, v77
	v_mov_b32_e32 v82, v70
	v_mov_b32_e32 v84, v79
	v_mov_b32_e32 v86, v81
	v_mad_i64_i32 v[92:93], s[2:3], v108, s50, v[144:145]
	v_lshl_add_u64 v[92:93], v[92:93], 0, v[122:123]
	s_waitcnt vmcnt(4)
	v_mov_b32_e32 v83, v244
	v_fmamk_f32 v75, v83, 0x39800000, v161
	v_rsq_f32_e32 v75, v75
	s_nop 0
	v_mul_f32_e32 v77, 0xbfb8aa3b, v75
	v_mul_f32_e32 v70, v70, v77
	v_mul_f32_e32 v83, v75, v75
	v_mul_f32_e32 v75, v71, v77
	v_mul_f32_e32 v79, v72, v77
	v_exp_f32_e32 v70, v70
	v_mul_f32_e32 v85, v66, v77
	v_exp_f32_e32 v75, v75
	v_exp_f32_e32 v79, v79
	v_mul_f32_e32 v81, v73, v77
	v_exp_f32_e32 v85, v85
	v_mul_f32_e32 v87, v67, v77
	v_exp_f32_e32 v81, v81
	v_exp_f32_e32 v87, v87
	v_add_f32_e32 v70, 1.0, v70
	v_mul_f32_e32 v89, v68, v77
	v_add_f32_e32 v75, 1.0, v75
	v_add_f32_e32 v91, 1.0, v79
	v_rcp_f32_e32 v79, v70
	v_mul_f32_e32 v77, v69, v77
	v_exp_f32_e32 v89, v89
	v_add_f32_e32 v95, 1.0, v85
	v_rcp_f32_e32 v85, v75
	v_exp_f32_e32 v77, v77
	v_add_f32_e32 v94, 1.0, v81
	v_rcp_f32_e32 v81, v91
	v_add_f32_e32 v96, 1.0, v87
	v_rcp_f32_e32 v87, v94
	v_rcp_f32_e32 v75, v95
	v_pk_mul_f32 v[78:79], v[82:83], v[78:79]
	v_mov_b32_e32 v82, v71
	v_add_f32_e32 v97, 1.0, v89
	v_rcp_f32_e32 v89, v96
	v_pk_mul_f32 v[70:71], v[82:83], v[84:85]
	v_mov_b32_e32 v82, v72
	v_add_f32_e32 v98, 1.0, v77
	v_rcp_f32_e32 v77, v97
	v_mul_f32_e32 v72, v70, v71
	v_pk_mul_f32 v[70:71], v[82:83], v[80:81]
	v_mov_b32_e32 v82, v73
	v_rcp_f32_e32 v91, v98
	v_mul_f32_e32 v73, v70, v71
	v_pk_mul_f32 v[70:71], v[82:83], v[86:87]
	v_mov_b32_e32 v82, v66
	v_mul_f32_e32 v78, v78, v79
	v_cvt_pk_bf16_f32 v66, v78, v72
	v_mul_f32_e32 v72, v70, v71
	v_pk_mul_f32 v[70:71], v[82:83], v[74:75]
	v_mov_b32_e32 v82, v67
	v_mul_f32_e32 v74, v70, v71
	v_pk_mul_f32 v[70:71], v[82:83], v[88:89]
	v_mov_b32_e32 v82, v68
	v_mul_f32_e32 v68, v70, v71
	v_pk_mul_f32 v[70:71], v[82:83], v[76:77]
	v_mov_b32_e32 v82, v69
	v_mul_f32_e32 v69, v70, v71
	v_pk_mul_f32 v[70:71], v[82:83], v[90:91]
	v_cvt_pk_bf16_f32 v67, v73, v72
	v_cvt_pk_bf16_f32 v68, v74, v68
	v_mov_b32_e32 v74, v61
	v_mul_f32_e32 v70, v70, v71
	v_cvt_pk_bf16_f32 v69, v69, v70
	global_store_dwordx4 v[92:93], v[66:69], off
	s_nop 0
	v_mov_b32_e32 v72, v59
	v_add_u32_e32 v59, 0x80, v142
	v_mad_i64_i32 v[76:77], s[2:3], v59, s50, v[144:145]
	v_mov_b32_e32 v66, v54
	v_mov_b32_e32 v68, v63
	v_mov_b32_e32 v70, v65
	v_lshl_add_u64 v[76:77], v[76:77], 0, v[122:123]
	s_waitcnt vmcnt(3)
	v_mov_b32_e32 v67, v245
	v_fmamk_f32 v61, v67, 0x39800000, v161
	v_rsq_f32_e32 v61, v61
	s_nop 0
	v_mul_f32_e32 v59, 0xbfb8aa3b, v61
	v_mul_f32_e32 v54, v54, v59
	v_mul_f32_e32 v67, v61, v61
	v_mul_f32_e32 v61, v55, v59
	v_mul_f32_e32 v63, v56, v59
	v_exp_f32_e32 v54, v54
	v_mul_f32_e32 v69, v50, v59
	v_exp_f32_e32 v61, v61
	v_exp_f32_e32 v63, v63
	v_mul_f32_e32 v65, v57, v59
	v_exp_f32_e32 v69, v69
	v_mul_f32_e32 v71, v51, v59
	v_exp_f32_e32 v65, v65
	v_mul_f32_e32 v73, v52, v59
	v_mul_f32_e32 v59, v53, v59
	v_exp_f32_e32 v71, v71
	v_add_f32_e32 v54, 1.0, v54
	v_exp_f32_e32 v59, v59
	v_add_f32_e32 v61, 1.0, v61
	v_add_f32_e32 v75, 1.0, v63
	v_rcp_f32_e32 v63, v54
	v_exp_f32_e32 v73, v73
	v_add_f32_e32 v79, 1.0, v69
	v_rcp_f32_e32 v69, v61
	v_add_f32_e32 v78, 1.0, v65
	v_rcp_f32_e32 v65, v75
	v_add_f32_e32 v80, 1.0, v71
	v_rcp_f32_e32 v71, v78
	v_add_f32_e32 v82, 1.0, v59
	v_rcp_f32_e32 v59, v79
	v_pk_mul_f32 v[62:63], v[66:67], v[62:63]
	v_mov_b32_e32 v66, v55
	v_add_f32_e32 v81, 1.0, v73
	v_rcp_f32_e32 v73, v80
	v_pk_mul_f32 v[54:55], v[66:67], v[68:69]
	v_mov_b32_e32 v66, v56
	v_rcp_f32_e32 v61, v81
	v_mul_f32_e32 v56, v54, v55
	v_pk_mul_f32 v[54:55], v[66:67], v[64:65]
	v_mov_b32_e32 v66, v57
	v_rcp_f32_e32 v75, v82
	v_mul_f32_e32 v57, v54, v55
	v_pk_mul_f32 v[54:55], v[66:67], v[70:71]
	v_mov_b32_e32 v66, v50
	v_mul_f32_e32 v62, v62, v63
	v_cvt_pk_bf16_f32 v50, v62, v56
	v_mul_f32_e32 v56, v54, v55
	v_pk_mul_f32 v[54:55], v[66:67], v[58:59]
	v_mov_b32_e32 v66, v51
	v_mul_f32_e32 v58, v54, v55
	v_pk_mul_f32 v[54:55], v[66:67], v[72:73]
	v_mov_b32_e32 v66, v52
	v_mul_f32_e32 v52, v54, v55
	v_pk_mul_f32 v[54:55], v[66:67], v[60:61]
	v_mov_b32_e32 v66, v53
	v_mul_f32_e32 v53, v54, v55
	v_pk_mul_f32 v[54:55], v[66:67], v[74:75]
	v_cvt_pk_bf16_f32 v51, v57, v56
	v_cvt_pk_bf16_f32 v52, v58, v52
	v_mov_b32_e32 v58, v45
	v_mul_f32_e32 v54, v54, v55
	v_cvt_pk_bf16_f32 v53, v53, v54
	global_store_dwordx4 v[76:77], v[50:53], off
	s_nop 0
	v_mov_b32_e32 v56, v43
	v_add_u32_e32 v43, 0x90, v142
	v_mad_i64_i32 v[60:61], s[2:3], v43, s50, v[144:145]
	v_mov_b32_e32 v50, v38
	v_mov_b32_e32 v52, v47
	v_mov_b32_e32 v54, v49
	v_lshl_add_u64 v[60:61], v[60:61], 0, v[122:123]
	s_waitcnt vmcnt(2)
	v_mov_b32_e32 v51, v246
	v_fmamk_f32 v45, v51, 0x39800000, v161
	v_rsq_f32_e32 v45, v45
	s_nop 0
	v_mul_f32_e32 v43, 0xbfb8aa3b, v45
	v_mul_f32_e32 v38, v38, v43
	v_mul_f32_e32 v51, v45, v45
	v_mul_f32_e32 v45, v39, v43
	v_mul_f32_e32 v47, v40, v43
	v_exp_f32_e32 v38, v38
	v_mul_f32_e32 v53, v34, v43
	v_exp_f32_e32 v45, v45
	v_exp_f32_e32 v47, v47
	v_mul_f32_e32 v49, v41, v43
	v_exp_f32_e32 v53, v53
	v_mul_f32_e32 v55, v35, v43
	v_exp_f32_e32 v49, v49
	v_mul_f32_e32 v57, v36, v43
	v_mul_f32_e32 v43, v37, v43
	v_exp_f32_e32 v55, v55
	v_add_f32_e32 v38, 1.0, v38
	v_exp_f32_e32 v43, v43
	v_add_f32_e32 v45, 1.0, v45
	v_add_f32_e32 v59, 1.0, v47
	v_rcp_f32_e32 v47, v38
	v_exp_f32_e32 v57, v57
	v_add_f32_e32 v63, 1.0, v53
	v_rcp_f32_e32 v53, v45
	v_add_f32_e32 v62, 1.0, v49
	v_rcp_f32_e32 v49, v59
	v_add_f32_e32 v64, 1.0, v55
	v_rcp_f32_e32 v55, v62
	v_add_f32_e32 v66, 1.0, v43
	v_rcp_f32_e32 v43, v63
	v_pk_mul_f32 v[46:47], v[50:51], v[46:47]
	v_mov_b32_e32 v50, v39
	v_add_f32_e32 v65, 1.0, v57
	v_rcp_f32_e32 v57, v64
	v_pk_mul_f32 v[38:39], v[50:51], v[52:53]
	v_mov_b32_e32 v50, v40
	v_rcp_f32_e32 v45, v65
	v_mul_f32_e32 v40, v38, v39
	v_pk_mul_f32 v[38:39], v[50:51], v[48:49]
	v_mov_b32_e32 v50, v41
	v_rcp_f32_e32 v59, v66
	v_mul_f32_e32 v41, v38, v39
	v_pk_mul_f32 v[38:39], v[50:51], v[54:55]
	v_mov_b32_e32 v50, v34
	v_mul_f32_e32 v46, v46, v47
	v_cvt_pk_bf16_f32 v34, v46, v40
	v_mul_f32_e32 v40, v38, v39
	v_pk_mul_f32 v[38:39], v[50:51], v[42:43]
	v_mov_b32_e32 v50, v35
	v_mul_f32_e32 v42, v38, v39
	v_pk_mul_f32 v[38:39], v[50:51], v[56:57]
	v_mov_b32_e32 v50, v36
	v_mul_f32_e32 v36, v38, v39
	v_pk_mul_f32 v[38:39], v[50:51], v[44:45]
	v_mov_b32_e32 v50, v37
	v_mul_f32_e32 v37, v38, v39
	v_pk_mul_f32 v[38:39], v[50:51], v[58:59]
	v_cvt_pk_bf16_f32 v35, v41, v40
	v_cvt_pk_bf16_f32 v36, v42, v36
	v_mov_b32_e32 v42, v29
	v_mul_f32_e32 v38, v38, v39
	v_cvt_pk_bf16_f32 v37, v37, v38
	global_store_dwordx4 v[60:61], v[34:37], off
	s_nop 0
	v_mov_b32_e32 v40, v27
	v_add_u32_e32 v27, 0xa0, v142
	v_mad_i64_i32 v[44:45], s[2:3], v27, s50, v[144:145]
	v_mov_b32_e32 v34, v22
	v_mov_b32_e32 v36, v31
	v_mov_b32_e32 v38, v33
	v_lshl_add_u64 v[44:45], v[44:45], 0, v[122:123]
	s_waitcnt vmcnt(1)
	v_mov_b32_e32 v35, v247
	v_fmamk_f32 v29, v35, 0x39800000, v161
	v_rsq_f32_e32 v29, v29
	s_nop 0
	v_mul_f32_e32 v27, 0xbfb8aa3b, v29
	v_mul_f32_e32 v22, v22, v27
	v_mul_f32_e32 v35, v29, v29
	v_mul_f32_e32 v29, v23, v27
	v_mul_f32_e32 v31, v24, v27
	v_exp_f32_e32 v22, v22
	v_mul_f32_e32 v37, v18, v27
	v_exp_f32_e32 v29, v29
	v_exp_f32_e32 v31, v31
	v_mul_f32_e32 v33, v25, v27
	v_exp_f32_e32 v37, v37
	v_mul_f32_e32 v39, v19, v27
	v_exp_f32_e32 v33, v33
	v_mul_f32_e32 v41, v20, v27
	v_mul_f32_e32 v27, v21, v27
	v_exp_f32_e32 v39, v39
	v_add_f32_e32 v22, 1.0, v22
	v_exp_f32_e32 v27, v27
	v_add_f32_e32 v29, 1.0, v29
	v_add_f32_e32 v43, 1.0, v31
	v_rcp_f32_e32 v31, v22
	v_exp_f32_e32 v41, v41
	v_add_f32_e32 v47, 1.0, v37
	v_rcp_f32_e32 v37, v29
	v_add_f32_e32 v46, 1.0, v33
	v_rcp_f32_e32 v33, v43
	v_add_f32_e32 v48, 1.0, v39
	v_rcp_f32_e32 v39, v46
	v_add_f32_e32 v50, 1.0, v27
	v_rcp_f32_e32 v27, v47
	v_pk_mul_f32 v[30:31], v[34:35], v[30:31]
	v_mov_b32_e32 v34, v23
	v_add_f32_e32 v49, 1.0, v41
	v_rcp_f32_e32 v41, v48
	v_pk_mul_f32 v[22:23], v[34:35], v[36:37]
	v_mov_b32_e32 v34, v24
	v_rcp_f32_e32 v29, v49
	v_mul_f32_e32 v24, v22, v23
	v_pk_mul_f32 v[22:23], v[34:35], v[32:33]
	v_mov_b32_e32 v34, v25
	v_rcp_f32_e32 v43, v50
	v_mul_f32_e32 v25, v22, v23
	v_pk_mul_f32 v[22:23], v[34:35], v[38:39]
	v_mov_b32_e32 v34, v18
	v_mul_f32_e32 v30, v30, v31
	v_cvt_pk_bf16_f32 v18, v30, v24
	v_mul_f32_e32 v24, v22, v23
	v_pk_mul_f32 v[22:23], v[34:35], v[26:27]
	v_mov_b32_e32 v34, v19
	v_mul_f32_e32 v26, v22, v23
	v_pk_mul_f32 v[22:23], v[34:35], v[40:41]
	v_mov_b32_e32 v34, v20
	v_mul_f32_e32 v20, v22, v23
	v_pk_mul_f32 v[22:23], v[34:35], v[28:29]
	v_mov_b32_e32 v34, v21
	v_mul_f32_e32 v21, v22, v23
	v_pk_mul_f32 v[22:23], v[34:35], v[42:43]
	v_cvt_pk_bf16_f32 v19, v25, v24
	v_cvt_pk_bf16_f32 v20, v26, v20
	v_mov_b32_e32 v26, v13
	v_mul_f32_e32 v22, v22, v23
	v_cvt_pk_bf16_f32 v21, v21, v22
	global_store_dwordx4 v[44:45], v[18:21], off
	s_nop 0
	v_mov_b32_e32 v24, v11
	v_add_u32_e32 v11, 0xb0, v142
	v_mad_i64_i32 v[28:29], s[2:3], v11, s50, v[144:145]
	v_mov_b32_e32 v18, v6
	v_mov_b32_e32 v20, v15
	v_mov_b32_e32 v22, v17
	v_lshl_add_u64 v[28:29], v[28:29], 0, v[122:123]
	s_mov_b64 s[2:3], -1
	s_waitcnt vmcnt(0)
	v_mov_b32_e32 v19, v248
	v_fmamk_f32 v13, v19, 0x39800000, v161
	v_rsq_f32_e32 v13, v13
	s_nop 0
	v_mul_f32_e32 v11, 0xbfb8aa3b, v13
	v_mul_f32_e32 v6, v6, v11
	v_mul_f32_e32 v19, v13, v13
	v_mul_f32_e32 v13, v7, v11
	v_mul_f32_e32 v15, v8, v11
	v_exp_f32_e32 v6, v6
	v_mul_f32_e32 v21, v2, v11
	v_exp_f32_e32 v13, v13
	v_exp_f32_e32 v15, v15
	v_mul_f32_e32 v17, v9, v11
	v_exp_f32_e32 v21, v21
	v_mul_f32_e32 v23, v3, v11
	v_exp_f32_e32 v17, v17
	v_mul_f32_e32 v25, v4, v11
	v_mul_f32_e32 v11, v5, v11
	v_exp_f32_e32 v23, v23
	v_add_f32_e32 v6, 1.0, v6
	v_exp_f32_e32 v11, v11
	v_add_f32_e32 v13, 1.0, v13
	v_add_f32_e32 v27, 1.0, v15
	v_rcp_f32_e32 v15, v6
	v_exp_f32_e32 v25, v25
	v_add_f32_e32 v31, 1.0, v21
	v_rcp_f32_e32 v21, v13
	v_add_f32_e32 v30, 1.0, v17
	v_rcp_f32_e32 v17, v27
	v_add_f32_e32 v32, 1.0, v23
	v_rcp_f32_e32 v23, v30
	v_add_f32_e32 v34, 1.0, v11
	v_rcp_f32_e32 v11, v31
	v_pk_mul_f32 v[14:15], v[18:19], v[14:15]
	v_mov_b32_e32 v18, v7
	v_add_f32_e32 v33, 1.0, v25
	v_rcp_f32_e32 v25, v32
	v_pk_mul_f32 v[6:7], v[18:19], v[20:21]
	v_mov_b32_e32 v18, v8
	v_rcp_f32_e32 v13, v33
	v_mul_f32_e32 v8, v6, v7
	v_pk_mul_f32 v[6:7], v[18:19], v[16:17]
	v_mov_b32_e32 v18, v9
	v_rcp_f32_e32 v27, v34
	v_mul_f32_e32 v9, v6, v7
	v_pk_mul_f32 v[6:7], v[18:19], v[22:23]
	v_mov_b32_e32 v18, v2
	v_mul_f32_e32 v14, v14, v15
	v_cvt_pk_bf16_f32 v2, v14, v8
	v_mul_f32_e32 v8, v6, v7
	v_pk_mul_f32 v[6:7], v[18:19], v[10:11]
	v_mov_b32_e32 v18, v3
	v_mul_f32_e32 v10, v6, v7
	v_pk_mul_f32 v[6:7], v[18:19], v[24:25]
	v_mov_b32_e32 v18, v4
	v_mul_f32_e32 v4, v6, v7
	v_pk_mul_f32 v[6:7], v[18:19], v[12:13]
	v_mov_b32_e32 v18, v5
	v_mul_f32_e32 v5, v6, v7
	v_pk_mul_f32 v[6:7], v[18:19], v[26:27]
	v_cvt_pk_bf16_f32 v3, v9, v8
	v_cvt_pk_bf16_f32 v4, v10, v4
	s_nop 0
	v_mul_f32_e32 v6, v6, v7
	v_cvt_pk_bf16_f32 v5, v5, v6
	global_store_dwordx4 v[28:29], v[2:5], off
	s_cbranch_vccnz .LBB0_1464
	s_andn2_b64 vcc, exec, s[0:1]
	s_cbranch_vccnz .LBB0_1463
	s_barrier
	s_branch .LBB0_1463

.LBB0_1553:
	v_lshl_add_u32 v66, s2, 7, v68
	v_ashrrev_i32_e32 v67, 31, v66
	v_lshl_add_u64 v[70:71], v[66:67], 2, s[4:5]
	global_load_dword v241, v[70:71], off
	global_load_dword v242, v[70:71], off offset:64
	global_load_dword v243, v[70:71], off offset:256
	global_load_dword v244, v[70:71], off offset:320
	v_mov_b32_e32 v67, 0x358637bd
	v_mov_b32_e32 v82, v61
	v_mov_b32_e32 v74, v63
	v_lshl_or_b32 v75, s0, 7, v148
	v_mov_b32_e32 v72, v54
	v_mov_b32_e32 v76, v65
	v_mov_b32_e32 v78, v58
	v_or_b32_e32 v58, s1, v75
	v_or_b32_e32 v86, 16, v66
	v_ashrrev_i32_e32 v87, 31, v86
	v_lshl_add_u64 v[88:89], v[86:87], 2, s[4:5]
	v_mov_b32_e32 v80, v59
	s_movk_i32 s0, 0x5600
	v_mov_b64_e32 v[68:69], s[6:7]
	v_mov_b32_e32 v59, 0
	v_mad_i64_i32 v[84:85], s[2:3], v66, s0, v[68:69]
	v_lshlrev_b32_e32 v58, 1, v58
	v_lshl_add_u64 v[84:85], v[84:85], 0, v[58:59]
	s_waitcnt vmcnt(3)
	v_mov_b32_e32 v73, v241
	v_fmamk_f32 v61, v73, 0x39800000, v67
	v_rsq_f32_e32 v61, v61
	s_nop 0
	v_mul_f32_e32 v63, 0xbfb8aa3b, v61
	v_mul_f32_e32 v54, v54, v63
	v_mul_f32_e32 v73, v61, v61
	v_mul_f32_e32 v61, v55, v63
	v_mul_f32_e32 v65, v56, v63
	v_mul_f32_e32 v75, v57, v63
	v_mul_f32_e32 v77, v50, v63
	v_mul_f32_e32 v79, v51, v63
	v_mul_f32_e32 v81, v52, v63
	v_mul_f32_e32 v63, v53, v63
	v_exp_f32_e32 v54, v54
	v_exp_f32_e32 v61, v61
	v_exp_f32_e32 v63, v63
	v_exp_f32_e32 v65, v65
	v_exp_f32_e32 v75, v75
	v_exp_f32_e32 v77, v77
	v_add_f32_e32 v54, 1.0, v54
	v_exp_f32_e32 v79, v79
	v_add_f32_e32 v61, 1.0, v61
	v_add_f32_e32 v92, 1.0, v63
	v_rcp_f32_e32 v63, v54
	v_exp_f32_e32 v81, v81
	v_add_f32_e32 v65, 1.0, v65
	v_add_f32_e32 v83, 1.0, v75
	v_rcp_f32_e32 v75, v61
	v_rcp_f32_e32 v65, v65
	v_add_f32_e32 v87, 1.0, v77
	v_rcp_f32_e32 v77, v83
	v_add_f32_e32 v90, 1.0, v79
	v_rcp_f32_e32 v79, v87
	v_pk_mul_f32 v[62:63], v[72:73], v[62:63]
	v_mov_b32_e32 v72, v55
	v_add_f32_e32 v91, 1.0, v81
	v_rcp_f32_e32 v81, v90
	v_pk_mul_f32 v[54:55], v[72:73], v[74:75]
	v_mov_b32_e32 v72, v56
	v_rcp_f32_e32 v61, v91
	v_mul_f32_e32 v56, v54, v55
	v_pk_mul_f32 v[54:55], v[72:73], v[64:65]
	v_mov_b32_e32 v72, v57
	v_rcp_f32_e32 v83, v92
	v_mul_f32_e32 v57, v54, v55
	v_pk_mul_f32 v[54:55], v[72:73], v[76:77]
	v_mov_b32_e32 v72, v50
	v_mul_f32_e32 v62, v62, v63
	v_cvt_pk_bf16_f32 v50, v62, v56
	v_mul_f32_e32 v56, v54, v55
	v_pk_mul_f32 v[54:55], v[72:73], v[78:79]
	v_mov_b32_e32 v72, v51
	v_mul_f32_e32 v62, v54, v55
	v_pk_mul_f32 v[54:55], v[72:73], v[80:81]
	v_mov_b32_e32 v72, v52
	v_mul_f32_e32 v52, v54, v55
	v_pk_mul_f32 v[54:55], v[72:73], v[60:61]
	v_mov_b32_e32 v72, v53
	v_mul_f32_e32 v53, v54, v55
	v_pk_mul_f32 v[54:55], v[72:73], v[82:83]
	v_cvt_pk_bf16_f32 v51, v57, v56
	v_cvt_pk_bf16_f32 v52, v62, v52
	v_mov_b32_e32 v56, v43
	v_mul_f32_e32 v54, v54, v55
	v_cvt_pk_bf16_f32 v53, v53, v54
	global_store_dwordx4 v[84:85], v[50:53], off
	s_nop 0
	v_mov_b32_e32 v60, v45
	v_mov_b32_e32 v50, v38
	v_mov_b32_e32 v52, v47
	v_mov_b32_e32 v54, v49
	v_mad_i64_i32 v[62:63], s[2:3], v86, s0, v[68:69]
	v_lshl_add_u64 v[62:63], v[62:63], 0, v[58:59]
	s_waitcnt vmcnt(2)
	v_mov_b32_e32 v51, v242
	v_fmamk_f32 v43, v51, 0x39800000, v67
	v_rsq_f32_e32 v43, v43
	s_nop 0
	v_mul_f32_e32 v45, 0xbfb8aa3b, v43
	v_mul_f32_e32 v38, v38, v45
	v_mul_f32_e32 v51, v43, v43
	v_mul_f32_e32 v43, v39, v45
	v_mul_f32_e32 v47, v40, v45
	v_exp_f32_e32 v38, v38
	v_mul_f32_e32 v53, v34, v45
	v_exp_f32_e32 v43, v43
	v_exp_f32_e32 v47, v47
	v_mul_f32_e32 v49, v41, v45
	v_exp_f32_e32 v53, v53
	v_mul_f32_e32 v55, v35, v45
	v_exp_f32_e32 v49, v49
	v_exp_f32_e32 v55, v55
	v_add_f32_e32 v38, 1.0, v38
	v_mul_f32_e32 v57, v36, v45
	v_add_f32_e32 v43, 1.0, v43
	v_add_f32_e32 v61, 1.0, v47
	v_rcp_f32_e32 v47, v38
	v_mul_f32_e32 v45, v37, v45
	v_exp_f32_e32 v57, v57
	v_add_f32_e32 v65, 1.0, v53
	v_rcp_f32_e32 v53, v43
	v_exp_f32_e32 v45, v45
	v_add_f32_e32 v64, 1.0, v49
	v_rcp_f32_e32 v49, v61
	v_add_f32_e32 v72, 1.0, v55
	v_rcp_f32_e32 v55, v64
	v_rcp_f32_e32 v43, v65
	v_pk_mul_f32 v[46:47], v[50:51], v[46:47]
	v_mov_b32_e32 v50, v39
	v_add_f32_e32 v73, 1.0, v57
	v_rcp_f32_e32 v57, v72
	v_pk_mul_f32 v[38:39], v[50:51], v[52:53]
	v_mov_b32_e32 v50, v40
	v_add_f32_e32 v74, 1.0, v45
	v_rcp_f32_e32 v45, v73
	v_mul_f32_e32 v40, v38, v39
	v_pk_mul_f32 v[38:39], v[50:51], v[48:49]
	v_mov_b32_e32 v50, v41
	v_rcp_f32_e32 v61, v74
	v_mul_f32_e32 v41, v38, v39
	v_pk_mul_f32 v[38:39], v[50:51], v[54:55]
	v_mov_b32_e32 v50, v34
	v_mul_f32_e32 v46, v46, v47
	v_cvt_pk_bf16_f32 v34, v46, v40
	v_mul_f32_e32 v40, v38, v39
	v_pk_mul_f32 v[38:39], v[50:51], v[42:43]
	v_mov_b32_e32 v50, v35
	v_mul_f32_e32 v42, v38, v39
	v_pk_mul_f32 v[38:39], v[50:51], v[56:57]
	v_mov_b32_e32 v50, v36
	v_mul_f32_e32 v36, v38, v39
	v_pk_mul_f32 v[38:39], v[50:51], v[44:45]
	v_mov_b32_e32 v50, v37
	v_mul_f32_e32 v37, v38, v39
	v_pk_mul_f32 v[38:39], v[50:51], v[60:61]
	v_cvt_pk_bf16_f32 v35, v41, v40
	v_cvt_pk_bf16_f32 v36, v42, v36
	v_mov_b32_e32 v42, v29
	v_mul_f32_e32 v38, v38, v39
	v_cvt_pk_bf16_f32 v37, v37, v38
	global_store_dwordx4 v[62:63], v[34:37], off
	s_nop 0
	v_mov_b32_e32 v40, v27
	v_add_u32_e32 v27, 64, v66
	v_mad_i64_i32 v[44:45], s[2:3], v27, s0, v[68:69]
	v_mov_b32_e32 v34, v22
	v_mov_b32_e32 v36, v31
	v_mov_b32_e32 v38, v33
	v_lshl_add_u64 v[44:45], v[44:45], 0, v[58:59]
	s_waitcnt vmcnt(1)
	v_mov_b32_e32 v35, v243
	v_fmamk_f32 v29, v35, 0x39800000, v67
	v_rsq_f32_e32 v29, v29
	s_nop 0
	v_mul_f32_e32 v27, 0xbfb8aa3b, v29
	v_mul_f32_e32 v22, v22, v27
	v_mul_f32_e32 v35, v29, v29
	v_mul_f32_e32 v29, v23, v27
	v_mul_f32_e32 v31, v24, v27
	v_exp_f32_e32 v22, v22
	v_mul_f32_e32 v37, v18, v27
	v_exp_f32_e32 v29, v29
	v_exp_f32_e32 v31, v31
	v_mul_f32_e32 v33, v25, v27
	v_exp_f32_e32 v37, v37
	v_mul_f32_e32 v39, v19, v27
	v_exp_f32_e32 v33, v33
	v_mul_f32_e32 v41, v20, v27
	v_mul_f32_e32 v27, v21, v27
	v_exp_f32_e32 v39, v39
	v_add_f32_e32 v22, 1.0, v22
	v_exp_f32_e32 v27, v27
	v_add_f32_e32 v29, 1.0, v29
	v_add_f32_e32 v43, 1.0, v31
	v_rcp_f32_e32 v31, v22
	v_exp_f32_e32 v41, v41
	v_add_f32_e32 v47, 1.0, v37
	v_rcp_f32_e32 v37, v29
	v_add_f32_e32 v46, 1.0, v33
	v_rcp_f32_e32 v33, v43
	v_add_f32_e32 v48, 1.0, v39
	v_rcp_f32_e32 v39, v46
	v_add_f32_e32 v50, 1.0, v27
	v_rcp_f32_e32 v27, v47
	v_pk_mul_f32 v[30:31], v[34:35], v[30:31]
	v_mov_b32_e32 v34, v23
	v_add_f32_e32 v49, 1.0, v41
	v_rcp_f32_e32 v41, v48
	v_pk_mul_f32 v[22:23], v[34:35], v[36:37]
	v_mov_b32_e32 v34, v24
	v_rcp_f32_e32 v29, v49
	v_mul_f32_e32 v24, v22, v23
	v_pk_mul_f32 v[22:23], v[34:35], v[32:33]
	v_mov_b32_e32 v34, v25
	v_rcp_f32_e32 v43, v50
	v_mul_f32_e32 v25, v22, v23
	v_pk_mul_f32 v[22:23], v[34:35], v[38:39]
	v_mov_b32_e32 v34, v18
	v_mul_f32_e32 v30, v30, v31
	v_cvt_pk_bf16_f32 v18, v30, v24
	v_mul_f32_e32 v24, v22, v23
	v_pk_mul_f32 v[22:23], v[34:35], v[26:27]
	v_mov_b32_e32 v34, v19
	v_mul_f32_e32 v26, v22, v23
	v_pk_mul_f32 v[22:23], v[34:35], v[40:41]
	v_mov_b32_e32 v34, v20
	v_mul_f32_e32 v20, v22, v23
	v_pk_mul_f32 v[22:23], v[34:35], v[28:29]
	v_mov_b32_e32 v34, v21
	v_mul_f32_e32 v21, v22, v23
	v_pk_mul_f32 v[22:23], v[34:35], v[42:43]
	v_cvt_pk_bf16_f32 v19, v25, v24
	v_cvt_pk_bf16_f32 v20, v26, v20
	v_mov_b32_e32 v26, v13
	v_mul_f32_e32 v22, v22, v23
	v_cvt_pk_bf16_f32 v21, v21, v22
	global_store_dwordx4 v[44:45], v[18:21], off
	s_nop 0
	v_mov_b32_e32 v24, v11
	v_add_u32_e32 v11, 0x50, v66
	v_mad_i64_i32 v[28:29], s[0:1], v11, s0, v[68:69]
	v_mov_b32_e32 v18, v6
	v_mov_b32_e32 v20, v15
	v_mov_b32_e32 v22, v17
	v_lshl_add_u64 v[28:29], v[28:29], 0, v[58:59]
	s_waitcnt vmcnt(0)
	v_mov_b32_e32 v19, v244
	v_fmac_f32_e32 v67, 0x39800000, v19
	v_rsq_f32_e32 v13, v67
	s_nop 0
	v_mul_f32_e32 v11, 0xbfb8aa3b, v13
	v_mul_f32_e32 v6, v6, v11
	v_mul_f32_e32 v19, v13, v13
	v_mul_f32_e32 v13, v7, v11
	v_mul_f32_e32 v15, v8, v11
	v_exp_f32_e32 v6, v6
	v_mul_f32_e32 v21, v2, v11
	v_exp_f32_e32 v13, v13
	v_exp_f32_e32 v15, v15
	v_mul_f32_e32 v17, v9, v11
	v_exp_f32_e32 v21, v21
	v_mul_f32_e32 v23, v3, v11
	v_exp_f32_e32 v17, v17
	v_mul_f32_e32 v25, v4, v11
	v_mul_f32_e32 v11, v5, v11
	v_exp_f32_e32 v23, v23
	v_add_f32_e32 v6, 1.0, v6
	v_exp_f32_e32 v11, v11
	v_add_f32_e32 v13, 1.0, v13
	v_add_f32_e32 v27, 1.0, v15
	v_rcp_f32_e32 v15, v6
	v_exp_f32_e32 v25, v25
	v_add_f32_e32 v31, 1.0, v21
	v_rcp_f32_e32 v21, v13
	v_add_f32_e32 v30, 1.0, v17
	v_rcp_f32_e32 v17, v27
	v_add_f32_e32 v32, 1.0, v23
	v_rcp_f32_e32 v23, v30
	v_add_f32_e32 v34, 1.0, v11
	v_rcp_f32_e32 v11, v31
	v_pk_mul_f32 v[14:15], v[18:19], v[14:15]
	v_mov_b32_e32 v18, v7
	v_add_f32_e32 v33, 1.0, v25
	v_rcp_f32_e32 v25, v32
	v_pk_mul_f32 v[6:7], v[18:19], v[20:21]
	v_mov_b32_e32 v18, v8
	v_rcp_f32_e32 v13, v33
	v_mul_f32_e32 v8, v6, v7
	v_pk_mul_f32 v[6:7], v[18:19], v[16:17]
	v_mov_b32_e32 v18, v9
	v_rcp_f32_e32 v27, v34
	v_mul_f32_e32 v9, v6, v7
	v_pk_mul_f32 v[6:7], v[18:19], v[22:23]
	v_mov_b32_e32 v18, v2
	v_mul_f32_e32 v14, v14, v15
	v_cvt_pk_bf16_f32 v2, v14, v8
	v_mul_f32_e32 v8, v6, v7
	v_pk_mul_f32 v[6:7], v[18:19], v[10:11]
	v_mov_b32_e32 v18, v3
	v_mul_f32_e32 v10, v6, v7
	v_pk_mul_f32 v[6:7], v[18:19], v[24:25]
	v_mov_b32_e32 v18, v4
	v_cvt_pk_bf16_f32 v3, v9, v8
	v_mul_f32_e32 v8, v6, v7
	v_pk_mul_f32 v[6:7], v[18:19], v[12:13]
	v_mov_b32_e32 v18, v5
	v_pk_mul_f32 v[4:5], v[18:19], v[26:27]
	v_mul_f32_e32 v6, v6, v7
	v_mul_f32_e32 v5, v4, v5
	v_cvt_pk_bf16_f32 v4, v10, v8
	v_cvt_pk_bf16_f32 v5, v6, v5
	global_store_dwordx4 v[28:29], v[2:5], off
	s_waitcnt vmcnt(0)
	s_barrier

	.amdhsa_kernel _Z8skel_fwd4Args
		.amdhsa_group_segment_fixed_size 0
		.amdhsa_private_segment_fixed_size 0
		.amdhsa_kernarg_size 448
		.amdhsa_user_sgpr_count 2
		.amdhsa_user_sgpr_dispatch_ptr 0
		.amdhsa_user_sgpr_queue_ptr 0
		.amdhsa_user_sgpr_kernarg_segment_ptr 1
		.amdhsa_user_sgpr_dispatch_id 0
		.amdhsa_user_sgpr_kernarg_preload_length 0
		.amdhsa_user_sgpr_kernarg_preload_offset 0
		.amdhsa_user_sgpr_private_segment_size 0
		.amdhsa_uses_dynamic_stack 0
		.amdhsa_enable_private_segment 0
		.amdhsa_system_sgpr_workgroup_id_x 1
		.amdhsa_system_sgpr_workgroup_id_y 0
		.amdhsa_system_sgpr_workgroup_id_z 0
		.amdhsa_system_sgpr_workgroup_info 0
		.amdhsa_system_vgpr_workitem_id 0
		.amdhsa_next_free_vgpr 249
		.amdhsa_next_free_sgpr 102
		.amdhsa_accum_offset 252
		.amdhsa_reserve_vcc 1
		.amdhsa_float_round_mode_32 0
		.amdhsa_float_round_mode_16_64 0
		.amdhsa_float_denorm_mode_32 3
		.amdhsa_float_denorm_mode_16_64 3
		.amdhsa_dx10_clamp 1
		.amdhsa_ieee_mode 1
		.amdhsa_fp16_overflow 0
		.amdhsa_tg_split 0
		.amdhsa_exception_fp_ieee_invalid_op 0
		.amdhsa_exception_fp_denorm_src 0
		.amdhsa_exception_fp_ieee_div_zero 0
		.amdhsa_exception_fp_ieee_overflow 0
		.amdhsa_exception_fp_ieee_underflow 0
		.amdhsa_exception_fp_ieee_inexact 0
		.amdhsa_exception_int_div_zero 0
	.end_amdhsa_kernel

amdhsa.kernels:
  - .agpr_count:     0
    .args:
      - .offset:         0
        .size:           192
        .value_kind:     by_value
      - .offset:         192
        .size:           4
        .value_kind:     hidden_block_count_x
      - .offset:         196
        .size:           4
        .value_kind:     hidden_block_count_y
      - .offset:         200
        .size:           4
        .value_kind:     hidden_block_count_z
      - .offset:         204
        .size:           2
        .value_kind:     hidden_group_size_x
      - .offset:         206
        .size:           2
        .value_kind:     hidden_group_size_y
      - .offset:         208
        .size:           2
        .value_kind:     hidden_group_size_z
      - .offset:         210
        .size:           2
        .value_kind:     hidden_remainder_x
      - .offset:         212
        .size:           2
        .value_kind:     hidden_remainder_y
      - .offset:         214
        .size:           2
        .value_kind:     hidden_remainder_z
      - .offset:         232
        .size:           8
        .value_kind:     hidden_global_offset_x
      - .offset:         240
        .size:           8
        .value_kind:     hidden_global_offset_y
      - .offset:         248
        .size:           8
        .value_kind:     hidden_global_offset_z
      - .offset:         256
        .size:           2
        .value_kind:     hidden_grid_dims
      - .offset:         312
        .size:           4
        .value_kind:     hidden_dynamic_lds_size
    .group_segment_fixed_size: 0
    .kernarg_segment_align: 8
    .kernarg_segment_size: 448
    .language:       OpenCL C
    .language_version:
      - 2
      - 0
    .max_flat_workgroup_size: 512
    .name:           _Z8skel_fwd4Args
    .private_segment_fixed_size: 0
    .sgpr_count:     108
    .sgpr_spill_count: 29
    .symbol:         _Z8skel_fwd4Args.kd
    .uniform_work_group_size: 1
    .uses_dynamic_stack: false
    .vgpr_count:     249
    .vgpr_spill_count: 0
    .wavefront_size: 64
